# stack: fast seam + rstd LDS table + P3Y fin copy + gMLP Wm fragment pipelining + pooling z_c hoist + conv wait move
# speedup vs baseline: 1.0027x; 1.0027x over previous
.LBB0_391:
	s_add_u32 s0, s8, s16
	s_waitcnt lgkmcnt(0)
	s_addc_u32 s1, s11, 0
	v_lshl_add_u64 v[54:55], s[0:1], 0, v[100:101]
	s_waitcnt vmcnt(0)
	v_mov_b64_e32 v[32:33], v[192:193]
	v_mov_b64_e32 v[34:35], v[194:195]
	s_mov_b32 s0, 0xb000
	v_add_co_u32_e32 v52, vcc, s0, v54
	s_mov_b32 s0, 0x21000
	s_nop 0
	v_addc_co_u32_e32 v53, vcc, 0, v55, vcc
	v_mov_b64_e32 v[28:29], v[196:197]
	v_mov_b64_e32 v[30:31], v[198:199]
	v_add_co_u32_e32 v50, vcc, s81, v54
	s_waitcnt vmcnt(1)
	v_lshlrev_b32_e32 v60, 16, v32
	v_addc_co_u32_e32 v51, vcc, 0, v55, vcc
	v_add_co_u32_e32 v48, vcc, s0, v54
	s_mov_b32 s0, 0x2c000
	s_nop 0
	v_addc_co_u32_e32 v49, vcc, 0, v55, vcc
	v_add_co_u32_e32 v46, vcc, s0, v54
	v_and_b32_e32 v61, 0xffff0000, v32
	s_nop 0
	v_addc_co_u32_e32 v47, vcc, 0, v55, vcc
	s_mov_b32 s0, 0x37000
	v_pk_mul_f32 v[62:63], v[60:61], s[24:25] op_sel_hi:[1,0]
	v_add_co_u32_e32 v44, vcc, s0, v54
	v_exp_f32_e32 v62, v62
	v_exp_f32_e32 v63, v63
	v_addc_co_u32_e32 v45, vcc, 0, v55, vcc
	s_mov_b32 s0, 0x42000
	v_add_co_u32_e32 v42, vcc, s0, v54
	s_mov_b32 s0, 0x4d000
	s_nop 0
	v_addc_co_u32_e32 v43, vcc, 0, v55, vcc
	v_add_co_u32_e32 v40, vcc, s0, v54
	v_pk_add_f32 v[62:63], v[62:63], 1.0 op_sel_hi:[1,0]
	s_nop 0
	v_addc_co_u32_e32 v41, vcc, 0, v55, vcc
	v_rcp_f32_e32 v62, v62
	v_rcp_f32_e32 v63, v63
	v_mov_b64_e32 v[22:23], v[200:201]
	v_mov_b64_e32 v[24:25], v[202:203]
	v_mov_b64_e32 v[18:19], v[204:205]
	v_mov_b64_e32 v[20:21], v[206:207]
	v_mov_b64_e32 v[14:15], v[208:209]
	v_mov_b64_e32 v[16:17], v[210:211]
	v_mov_b64_e32 v[10:11], v[212:213]
	v_mov_b64_e32 v[12:13], v[214:215]
	v_mov_b64_e32 v[6:7], v[178:179]
	v_mov_b64_e32 v[8:9], v[180:181]
	v_mov_b64_e32 v[2:3], v[182:183]
	v_mov_b64_e32 v[4:5], v[184:185]
	ds_read_b128 v[56:59], v117
	ds_read_b128 v[36:39], v117 offset:16
	v_pk_mul_f32 v[60:61], v[62:63], v[60:61]
	s_add_i32 s0, s23, 0x80
	s_cmpk_gt_i32 s23, 0x27f
	s_waitcnt lgkmcnt(1)
	v_pk_mul_f32 v[56:57], v[56:57], v[60:61]
	s_mov_b32 s23, s0
	v_cvt_pk_bf16_f32 v32, v56, v57
	v_lshlrev_b32_e32 v56, 16, v33
	v_and_b32_e32 v57, 0xffff0000, v33
	v_pk_mul_f32 v[60:61], v[56:57], s[24:25] op_sel_hi:[1,0]
	s_nop 0
	v_exp_f32_e32 v60, v60
	v_exp_f32_e32 v61, v61
	s_nop 0
	v_pk_add_f32 v[60:61], v[60:61], 1.0 op_sel_hi:[1,0]
	s_nop 0
	v_rcp_f32_e32 v60, v60
	v_rcp_f32_e32 v61, v61
	s_nop 0
	v_pk_mul_f32 v[56:57], v[60:61], v[56:57]
	s_nop 0
	v_pk_mul_f32 v[56:57], v[58:59], v[56:57]
	s_nop 0
	v_cvt_pk_bf16_f32 v33, v56, v57
	v_lshlrev_b32_e32 v56, 16, v34
	v_and_b32_e32 v57, 0xffff0000, v34
	v_pk_mul_f32 v[58:59], v[56:57], s[24:25] op_sel_hi:[1,0]
	s_nop 0
	v_exp_f32_e32 v58, v58
	v_exp_f32_e32 v59, v59
	s_nop 0
	v_pk_add_f32 v[58:59], v[58:59], 1.0 op_sel_hi:[1,0]
	s_nop 0
	v_rcp_f32_e32 v58, v58
	v_rcp_f32_e32 v59, v59
	s_nop 0
	v_pk_mul_f32 v[56:57], v[58:59], v[56:57]
	s_waitcnt lgkmcnt(0)
	v_pk_mul_f32 v[36:37], v[36:37], v[56:57]
	s_nop 0
	v_cvt_pk_bf16_f32 v34, v36, v37
	v_lshlrev_b32_e32 v36, 16, v35
	v_and_b32_e32 v37, 0xffff0000, v35
	v_pk_mul_f32 v[56:57], v[36:37], s[24:25] op_sel_hi:[1,0]
	s_nop 0
	v_exp_f32_e32 v56, v56
	v_exp_f32_e32 v57, v57
	s_nop 0
	v_pk_add_f32 v[56:57], v[56:57], 1.0 op_sel_hi:[1,0]
	s_nop 0
	v_rcp_f32_e32 v56, v56
	v_rcp_f32_e32 v57, v57
	s_nop 0
	v_pk_mul_f32 v[36:37], v[56:57], v[36:37]
	s_nop 0
	v_pk_mul_f32 v[36:37], v[38:39], v[36:37]
	s_nop 0
	v_cvt_pk_bf16_f32 v35, v36, v37
	global_store_dwordx4 v[54:55], v[32:35], off offset:2048
	s_waitcnt vmcnt(7)
	v_lshlrev_b32_e32 v54, 16, v28
	v_and_b32_e32 v55, 0xffff0000, v28
	v_pk_mul_f32 v[56:57], v[54:55], s[24:25] op_sel_hi:[1,0]
	ds_read_b128 v[36:39], v117 offset:2112
	ds_read_b128 v[32:35], v117 offset:2128
	v_exp_f32_e32 v56, v56
	v_exp_f32_e32 v57, v57
	s_nop 0
	v_pk_add_f32 v[56:57], v[56:57], 1.0 op_sel_hi:[1,0]
	s_nop 0
	v_rcp_f32_e32 v56, v56
	v_rcp_f32_e32 v57, v57
	s_nop 0
	v_pk_mul_f32 v[54:55], v[56:57], v[54:55]
	s_waitcnt lgkmcnt(1)
	v_pk_mul_f32 v[36:37], v[36:37], v[54:55]
	s_nop 0
	v_cvt_pk_bf16_f32 v28, v36, v37
	v_lshlrev_b32_e32 v36, 16, v29
	v_and_b32_e32 v37, 0xffff0000, v29
	v_pk_mul_f32 v[54:55], v[36:37], s[24:25] op_sel_hi:[1,0]
	s_nop 0
	v_exp_f32_e32 v54, v54
	v_exp_f32_e32 v55, v55
	s_nop 0
	v_pk_add_f32 v[54:55], v[54:55], 1.0 op_sel_hi:[1,0]
	s_nop 0
	v_rcp_f32_e32 v54, v54
	v_rcp_f32_e32 v55, v55
	s_nop 0
	v_pk_mul_f32 v[36:37], v[54:55], v[36:37]
	s_nop 0
	v_pk_mul_f32 v[36:37], v[38:39], v[36:37]
	s_nop 0
	v_cvt_pk_bf16_f32 v29, v36, v37
	v_lshlrev_b32_e32 v36, 16, v30
	v_and_b32_e32 v37, 0xffff0000, v30
	v_pk_mul_f32 v[38:39], v[36:37], s[24:25] op_sel_hi:[1,0]
	s_nop 0
	v_exp_f32_e32 v38, v38
	v_exp_f32_e32 v39, v39
	s_nop 0
	v_pk_add_f32 v[38:39], v[38:39], 1.0 op_sel_hi:[1,0]
	s_nop 0
	v_rcp_f32_e32 v38, v38
	v_rcp_f32_e32 v39, v39
	s_nop 0
	v_pk_mul_f32 v[36:37], v[38:39], v[36:37]
	s_waitcnt lgkmcnt(0)
	v_pk_mul_f32 v[32:33], v[36:37], v[32:33]
	s_nop 0
	v_cvt_pk_bf16_f32 v30, v32, v33
	v_lshlrev_b32_e32 v32, 16, v31
	v_and_b32_e32 v33, 0xffff0000, v31
	v_pk_mul_f32 v[36:37], v[32:33], s[24:25] op_sel_hi:[1,0]
	s_nop 0
	v_exp_f32_e32 v36, v36
	v_exp_f32_e32 v37, v37
	s_nop 0
	v_pk_add_f32 v[36:37], v[36:37], 1.0 op_sel_hi:[1,0]
	s_nop 0
	v_rcp_f32_e32 v36, v36
	v_rcp_f32_e32 v37, v37
	s_nop 0
	v_pk_mul_f32 v[32:33], v[36:37], v[32:33]
	s_waitcnt vmcnt(6)
	v_lshlrev_b32_e32 v36, 16, v22
	v_and_b32_e32 v37, 0xffff0000, v22
	v_pk_mul_f32 v[38:39], v[36:37], s[24:25] op_sel_hi:[1,0]
	v_pk_mul_f32 v[32:33], v[32:33], v[34:35]
	v_exp_f32_e32 v38, v38
	v_exp_f32_e32 v39, v39
	v_cvt_pk_bf16_f32 v31, v32, v33
	global_store_dwordx4 v[52:53], v[28:31], off offset:2048
	ds_read_b128 v[28:31], v117 offset:4224
	ds_read_b128 v[32:35], v117 offset:4240
	v_pk_add_f32 v[38:39], v[38:39], 1.0 op_sel_hi:[1,0]
	s_nop 0
	v_rcp_f32_e32 v38, v38
	v_rcp_f32_e32 v39, v39
	s_nop 0
	v_pk_mul_f32 v[36:37], v[38:39], v[36:37]
	s_waitcnt lgkmcnt(1)
	v_pk_mul_f32 v[28:29], v[36:37], v[28:29]
	s_nop 0
	v_cvt_pk_bf16_f32 v22, v28, v29
	v_lshlrev_b32_e32 v28, 16, v23
	v_and_b32_e32 v29, 0xffff0000, v23
	v_pk_mul_f32 v[36:37], v[28:29], s[24:25] op_sel_hi:[1,0]
	s_nop 0
	v_exp_f32_e32 v36, v36
	v_exp_f32_e32 v37, v37
	s_nop 0
	v_pk_add_f32 v[36:37], v[36:37], 1.0 op_sel_hi:[1,0]
	s_nop 0
	v_rcp_f32_e32 v36, v36
	v_rcp_f32_e32 v37, v37
	s_nop 0
	v_pk_mul_f32 v[28:29], v[36:37], v[28:29]
	s_nop 0
	v_pk_mul_f32 v[28:29], v[28:29], v[30:31]
	s_nop 0
	v_cvt_pk_bf16_f32 v23, v28, v29
	v_lshlrev_b32_e32 v28, 16, v24
	v_and_b32_e32 v29, 0xffff0000, v24
	v_pk_mul_f32 v[30:31], v[28:29], s[24:25] op_sel_hi:[1,0]
	s_nop 0
	v_exp_f32_e32 v30, v30
	v_exp_f32_e32 v31, v31
	s_nop 0
	v_pk_add_f32 v[30:31], v[30:31], 1.0 op_sel_hi:[1,0]
	s_nop 0
	v_rcp_f32_e32 v30, v30
	v_rcp_f32_e32 v31, v31
	s_nop 0
	v_pk_mul_f32 v[28:29], v[30:31], v[28:29]
	s_waitcnt lgkmcnt(0)
	v_pk_mul_f32 v[28:29], v[28:29], v[32:33]
	s_waitcnt vmcnt(6)
	v_lshlrev_b32_e32 v32, 16, v18
	v_cvt_pk_bf16_f32 v24, v28, v29
	v_lshlrev_b32_e32 v28, 16, v25
	v_and_b32_e32 v29, 0xffff0000, v25
	v_pk_mul_f32 v[30:31], v[28:29], s[24:25] op_sel_hi:[1,0]
	v_and_b32_e32 v33, 0xffff0000, v18
	v_exp_f32_e32 v30, v30
	v_exp_f32_e32 v31, v31
	s_nop 0
	v_pk_add_f32 v[30:31], v[30:31], 1.0 op_sel_hi:[1,0]
	s_nop 0
	v_rcp_f32_e32 v30, v30
	v_rcp_f32_e32 v31, v31
	s_nop 0
	v_pk_mul_f32 v[28:29], v[30:31], v[28:29]
	s_nop 0
	v_pk_mul_f32 v[28:29], v[28:29], v[34:35]
	v_pk_mul_f32 v[34:35], v[32:33], s[24:25] op_sel_hi:[1,0]
	v_cvt_pk_bf16_f32 v25, v28, v29
	global_store_dwordx4 v[50:51], v[22:25], off offset:2048
	v_exp_f32_e32 v34, v34
	v_exp_f32_e32 v35, v35
	ds_read_b128 v[22:25], v117 offset:6336
	ds_read_b128 v[28:31], v117 offset:6352
	v_pk_add_f32 v[34:35], v[34:35], 1.0 op_sel_hi:[1,0]
	s_nop 0
	v_rcp_f32_e32 v34, v34
	v_rcp_f32_e32 v35, v35
	s_nop 0
	v_pk_mul_f32 v[32:33], v[34:35], v[32:33]
	s_waitcnt lgkmcnt(1)
	v_pk_mul_f32 v[22:23], v[32:33], v[22:23]
	s_nop 0
	v_cvt_pk_bf16_f32 v18, v22, v23
	v_lshlrev_b32_e32 v22, 16, v19
	v_and_b32_e32 v23, 0xffff0000, v19
	v_pk_mul_f32 v[32:33], v[22:23], s[24:25] op_sel_hi:[1,0]
	s_nop 0
	v_exp_f32_e32 v32, v32
	v_exp_f32_e32 v33, v33
	s_nop 0
	v_pk_add_f32 v[32:33], v[32:33], 1.0 op_sel_hi:[1,0]
	s_nop 0
	v_rcp_f32_e32 v32, v32
	v_rcp_f32_e32 v33, v33
	s_nop 0
	v_pk_mul_f32 v[22:23], v[32:33], v[22:23]
	s_nop 0
	v_pk_mul_f32 v[22:23], v[22:23], v[24:25]
	s_nop 0
	v_cvt_pk_bf16_f32 v19, v22, v23
	v_lshlrev_b32_e32 v22, 16, v20
	v_and_b32_e32 v23, 0xffff0000, v20
	v_pk_mul_f32 v[24:25], v[22:23], s[24:25] op_sel_hi:[1,0]
	s_nop 0
	v_exp_f32_e32 v24, v24
	v_exp_f32_e32 v25, v25
	s_nop 0
	v_pk_add_f32 v[24:25], v[24:25], 1.0 op_sel_hi:[1,0]
	s_nop 0
	v_rcp_f32_e32 v24, v24
	v_rcp_f32_e32 v25, v25
	s_nop 0
	v_pk_mul_f32 v[22:23], v[24:25], v[22:23]
	s_waitcnt lgkmcnt(0)
	v_pk_mul_f32 v[22:23], v[22:23], v[28:29]
	s_waitcnt vmcnt(6)
	v_lshlrev_b32_e32 v28, 16, v14
	v_cvt_pk_bf16_f32 v20, v22, v23
	v_lshlrev_b32_e32 v22, 16, v21
	v_and_b32_e32 v23, 0xffff0000, v21
	v_pk_mul_f32 v[24:25], v[22:23], s[24:25] op_sel_hi:[1,0]
	v_and_b32_e32 v29, 0xffff0000, v14
	v_exp_f32_e32 v24, v24
	v_exp_f32_e32 v25, v25
	s_nop 0
	v_pk_add_f32 v[24:25], v[24:25], 1.0 op_sel_hi:[1,0]
	s_nop 0
	v_rcp_f32_e32 v24, v24
	v_rcp_f32_e32 v25, v25
	s_nop 0
	v_pk_mul_f32 v[22:23], v[24:25], v[22:23]
	s_nop 0
	v_pk_mul_f32 v[22:23], v[22:23], v[30:31]
	v_pk_mul_f32 v[30:31], v[28:29], s[24:25] op_sel_hi:[1,0]
	v_cvt_pk_bf16_f32 v21, v22, v23
	global_store_dwordx4 v[48:49], v[18:21], off offset:2048
	v_exp_f32_e32 v30, v30
	v_exp_f32_e32 v31, v31
	ds_read_b128 v[18:21], v117 offset:8448
	ds_read_b128 v[22:25], v117 offset:8464
	v_pk_add_f32 v[30:31], v[30:31], 1.0 op_sel_hi:[1,0]
	s_nop 0
	v_rcp_f32_e32 v30, v30
	v_rcp_f32_e32 v31, v31
	s_nop 0
	v_pk_mul_f32 v[28:29], v[30:31], v[28:29]
	s_waitcnt lgkmcnt(1)
	v_pk_mul_f32 v[18:19], v[28:29], v[18:19]
	s_nop 0
	v_cvt_pk_bf16_f32 v14, v18, v19
	v_lshlrev_b32_e32 v18, 16, v15
	v_and_b32_e32 v19, 0xffff0000, v15
	v_pk_mul_f32 v[28:29], v[18:19], s[24:25] op_sel_hi:[1,0]
	s_nop 0
	v_exp_f32_e32 v28, v28
	v_exp_f32_e32 v29, v29
	s_nop 0
	v_pk_add_f32 v[28:29], v[28:29], 1.0 op_sel_hi:[1,0]
	s_nop 0
	v_rcp_f32_e32 v28, v28
	v_rcp_f32_e32 v29, v29
	s_nop 0
	v_pk_mul_f32 v[18:19], v[28:29], v[18:19]
	s_nop 0
	v_pk_mul_f32 v[18:19], v[18:19], v[20:21]
	s_nop 0
	v_cvt_pk_bf16_f32 v15, v18, v19
	v_lshlrev_b32_e32 v18, 16, v16
	v_and_b32_e32 v19, 0xffff0000, v16
	v_pk_mul_f32 v[20:21], v[18:19], s[24:25] op_sel_hi:[1,0]
	s_nop 0
	v_exp_f32_e32 v20, v20
	v_exp_f32_e32 v21, v21
	s_nop 0
	v_pk_add_f32 v[20:21], v[20:21], 1.0 op_sel_hi:[1,0]
	s_nop 0
	v_rcp_f32_e32 v20, v20
	v_rcp_f32_e32 v21, v21
	s_nop 0
	v_pk_mul_f32 v[18:19], v[20:21], v[18:19]
	s_waitcnt lgkmcnt(0)
	v_pk_mul_f32 v[18:19], v[18:19], v[22:23]
	s_waitcnt vmcnt(6)
	v_lshlrev_b32_e32 v22, 16, v10
	v_cvt_pk_bf16_f32 v16, v18, v19
	v_lshlrev_b32_e32 v18, 16, v17
	v_and_b32_e32 v19, 0xffff0000, v17
	v_pk_mul_f32 v[20:21], v[18:19], s[24:25] op_sel_hi:[1,0]
	v_and_b32_e32 v23, 0xffff0000, v10
	v_exp_f32_e32 v20, v20
	v_exp_f32_e32 v21, v21
	s_nop 0
	v_pk_add_f32 v[20:21], v[20:21], 1.0 op_sel_hi:[1,0]
	s_nop 0
	v_rcp_f32_e32 v20, v20
	v_rcp_f32_e32 v21, v21
	s_nop 0
	v_pk_mul_f32 v[18:19], v[20:21], v[18:19]
	s_nop 0
	v_pk_mul_f32 v[18:19], v[18:19], v[24:25]
	v_pk_mul_f32 v[24:25], v[22:23], s[24:25] op_sel_hi:[1,0]
	v_cvt_pk_bf16_f32 v17, v18, v19
	global_store_dwordx4 v[46:47], v[14:17], off offset:2048
	v_exp_f32_e32 v24, v24
	v_exp_f32_e32 v25, v25
	ds_read_b128 v[14:17], v117 offset:10560
	ds_read_b128 v[18:21], v117 offset:10576
	v_pk_add_f32 v[24:25], v[24:25], 1.0 op_sel_hi:[1,0]
	s_nop 0
	v_rcp_f32_e32 v24, v24
	v_rcp_f32_e32 v25, v25
	s_nop 0
	v_pk_mul_f32 v[22:23], v[24:25], v[22:23]
	s_waitcnt lgkmcnt(1)
	v_pk_mul_f32 v[14:15], v[22:23], v[14:15]
	s_nop 0
	v_cvt_pk_bf16_f32 v10, v14, v15
	v_lshlrev_b32_e32 v14, 16, v11
	v_and_b32_e32 v15, 0xffff0000, v11
	v_pk_mul_f32 v[22:23], v[14:15], s[24:25] op_sel_hi:[1,0]
	s_nop 0
	v_exp_f32_e32 v22, v22
	v_exp_f32_e32 v23, v23
	s_nop 0
	v_pk_add_f32 v[22:23], v[22:23], 1.0 op_sel_hi:[1,0]
	s_nop 0
	v_rcp_f32_e32 v22, v22
	v_rcp_f32_e32 v23, v23
	s_nop 0
	v_pk_mul_f32 v[14:15], v[22:23], v[14:15]
	s_nop 0
	v_pk_mul_f32 v[14:15], v[14:15], v[16:17]
	s_nop 0
	v_cvt_pk_bf16_f32 v11, v14, v15
	v_lshlrev_b32_e32 v14, 16, v12
	v_and_b32_e32 v15, 0xffff0000, v12
	v_pk_mul_f32 v[16:17], v[14:15], s[24:25] op_sel_hi:[1,0]
	s_nop 0
	v_exp_f32_e32 v16, v16
	v_exp_f32_e32 v17, v17
	s_nop 0
	v_pk_add_f32 v[16:17], v[16:17], 1.0 op_sel_hi:[1,0]
	s_nop 0
	v_rcp_f32_e32 v16, v16
	v_rcp_f32_e32 v17, v17
	s_nop 0
	v_pk_mul_f32 v[14:15], v[16:17], v[14:15]
	s_waitcnt lgkmcnt(0)
	v_pk_mul_f32 v[14:15], v[14:15], v[18:19]
	s_waitcnt vmcnt(6)
	v_lshlrev_b32_e32 v18, 16, v6
	v_cvt_pk_bf16_f32 v12, v14, v15
	v_lshlrev_b32_e32 v14, 16, v13
	v_and_b32_e32 v15, 0xffff0000, v13
	v_pk_mul_f32 v[16:17], v[14:15], s[24:25] op_sel_hi:[1,0]
	v_and_b32_e32 v19, 0xffff0000, v6
	v_exp_f32_e32 v16, v16
	v_exp_f32_e32 v17, v17
	s_nop 0
	v_pk_add_f32 v[16:17], v[16:17], 1.0 op_sel_hi:[1,0]
	s_nop 0
	v_rcp_f32_e32 v16, v16
	v_rcp_f32_e32 v17, v17
	s_nop 0
	v_pk_mul_f32 v[14:15], v[16:17], v[14:15]
	s_nop 0
	v_pk_mul_f32 v[14:15], v[14:15], v[20:21]
	v_pk_mul_f32 v[20:21], v[18:19], s[24:25] op_sel_hi:[1,0]
	v_cvt_pk_bf16_f32 v13, v14, v15
	global_store_dwordx4 v[44:45], v[10:13], off offset:2048
	v_exp_f32_e32 v20, v20
	v_exp_f32_e32 v21, v21
	ds_read_b128 v[10:13], v117 offset:12672
	ds_read_b128 v[14:17], v117 offset:12688
	v_pk_add_f32 v[20:21], v[20:21], 1.0 op_sel_hi:[1,0]
	s_nop 0
	v_rcp_f32_e32 v20, v20
	v_rcp_f32_e32 v21, v21
	s_nop 0
	v_pk_mul_f32 v[18:19], v[20:21], v[18:19]
	s_waitcnt lgkmcnt(1)
	v_pk_mul_f32 v[10:11], v[18:19], v[10:11]
	s_nop 0
	v_cvt_pk_bf16_f32 v6, v10, v11
	v_lshlrev_b32_e32 v10, 16, v7
	v_and_b32_e32 v11, 0xffff0000, v7
	v_pk_mul_f32 v[18:19], v[10:11], s[24:25] op_sel_hi:[1,0]
	s_nop 0
	v_exp_f32_e32 v18, v18
	v_exp_f32_e32 v19, v19
	s_nop 0
	v_pk_add_f32 v[18:19], v[18:19], 1.0 op_sel_hi:[1,0]
	s_nop 0
	v_rcp_f32_e32 v18, v18
	v_rcp_f32_e32 v19, v19
	s_nop 0
	v_pk_mul_f32 v[10:11], v[18:19], v[10:11]
	s_nop 0
	v_pk_mul_f32 v[10:11], v[10:11], v[12:13]
	s_nop 0
	v_cvt_pk_bf16_f32 v7, v10, v11
	v_lshlrev_b32_e32 v10, 16, v8
	v_and_b32_e32 v11, 0xffff0000, v8
	v_pk_mul_f32 v[12:13], v[10:11], s[24:25] op_sel_hi:[1,0]
	s_nop 0
	v_exp_f32_e32 v12, v12
	v_exp_f32_e32 v13, v13
	s_nop 0
	v_pk_add_f32 v[12:13], v[12:13], 1.0 op_sel_hi:[1,0]
	s_nop 0
	v_rcp_f32_e32 v12, v12
	v_rcp_f32_e32 v13, v13
	s_nop 0
	v_pk_mul_f32 v[10:11], v[12:13], v[10:11]
	s_waitcnt lgkmcnt(0)
	v_pk_mul_f32 v[10:11], v[10:11], v[14:15]
	s_waitcnt vmcnt(6)
	v_lshlrev_b32_e32 v14, 16, v2
	v_cvt_pk_bf16_f32 v8, v10, v11
	v_lshlrev_b32_e32 v10, 16, v9
	v_and_b32_e32 v11, 0xffff0000, v9
	v_pk_mul_f32 v[12:13], v[10:11], s[24:25] op_sel_hi:[1,0]
	v_and_b32_e32 v15, 0xffff0000, v2
	v_exp_f32_e32 v12, v12
	v_exp_f32_e32 v13, v13
	s_nop 0
	v_pk_add_f32 v[12:13], v[12:13], 1.0 op_sel_hi:[1,0]
	s_nop 0
	v_rcp_f32_e32 v12, v12
	v_rcp_f32_e32 v13, v13
	s_nop 0
	v_pk_mul_f32 v[10:11], v[12:13], v[10:11]
	s_nop 0
	v_pk_mul_f32 v[10:11], v[10:11], v[16:17]
	v_pk_mul_f32 v[16:17], v[14:15], s[24:25] op_sel_hi:[1,0]
	v_cvt_pk_bf16_f32 v9, v10, v11
	global_store_dwordx4 v[42:43], v[6:9], off offset:2048
	v_exp_f32_e32 v16, v16
	v_exp_f32_e32 v17, v17
	ds_read_b128 v[6:9], v117 offset:14784
	ds_read_b128 v[10:13], v117 offset:14800
	v_pk_add_f32 v[16:17], v[16:17], 1.0 op_sel_hi:[1,0]
	s_nop 0
	v_rcp_f32_e32 v16, v16
	v_rcp_f32_e32 v17, v17
	s_nop 0
	v_pk_mul_f32 v[14:15], v[16:17], v[14:15]
	s_waitcnt lgkmcnt(1)
	v_pk_mul_f32 v[6:7], v[14:15], v[6:7]
	s_nop 0
	v_cvt_pk_bf16_f32 v2, v6, v7
	v_lshlrev_b32_e32 v6, 16, v3
	v_and_b32_e32 v7, 0xffff0000, v3
	v_pk_mul_f32 v[14:15], v[6:7], s[24:25] op_sel_hi:[1,0]
	s_nop 0
	v_exp_f32_e32 v14, v14
	v_exp_f32_e32 v15, v15
	s_nop 0
	v_pk_add_f32 v[14:15], v[14:15], 1.0 op_sel_hi:[1,0]
	s_nop 0
	v_rcp_f32_e32 v14, v14
	v_rcp_f32_e32 v15, v15
	s_nop 0
	v_pk_mul_f32 v[6:7], v[14:15], v[6:7]
	s_nop 0
	v_pk_mul_f32 v[6:7], v[6:7], v[8:9]
	s_nop 0
	v_cvt_pk_bf16_f32 v3, v6, v7
	v_lshlrev_b32_e32 v6, 16, v4
	v_and_b32_e32 v7, 0xffff0000, v4
	v_pk_mul_f32 v[8:9], v[6:7], s[24:25] op_sel_hi:[1,0]
	s_nop 0
	v_exp_f32_e32 v8, v8
	v_exp_f32_e32 v9, v9
	s_nop 0
	v_pk_add_f32 v[8:9], v[8:9], 1.0 op_sel_hi:[1,0]
	s_nop 0
	v_rcp_f32_e32 v8, v8
	v_rcp_f32_e32 v9, v9
	s_nop 0
	v_pk_mul_f32 v[6:7], v[8:9], v[6:7]
	s_waitcnt lgkmcnt(0)
	v_pk_mul_f32 v[6:7], v[6:7], v[10:11]
	s_nop 0
	v_cvt_pk_bf16_f32 v4, v6, v7
	v_lshlrev_b32_e32 v6, 16, v5
	v_and_b32_e32 v7, 0xffff0000, v5
	v_pk_mul_f32 v[8:9], v[6:7], s[24:25] op_sel_hi:[1,0]
	s_nop 0
	v_exp_f32_e32 v8, v8
	v_exp_f32_e32 v9, v9
	s_nop 0
	v_pk_add_f32 v[8:9], v[8:9], 1.0 op_sel_hi:[1,0]
	s_nop 0
	v_rcp_f32_e32 v8, v8
	v_rcp_f32_e32 v9, v9
	s_nop 0
	v_pk_mul_f32 v[6:7], v[8:9], v[6:7]
	s_nop 0
	v_pk_mul_f32 v[6:7], v[6:7], v[12:13]
	s_nop 0
	v_cvt_pk_bf16_f32 v5, v6, v7
	global_store_dwordx4 v[40:41], v[2:5], off offset:2048
	s_waitcnt lgkmcnt(0)
	s_cbranch_scc1 .LBB0_463
.LBB0_392:
	s_lshl_b32 s0, s23, 3
	s_and_b32 s0, s0, 0x7f8
	v_readlane_b32 s1, v251, 3
	s_or_b32 s0, s0, s1
	s_and_b32 s1, s0, 0x3fe0
	s_mulk_i32 s1, 0x2c00
	s_add_u32 s8, s19, s1
	v_readlane_b32 s1, v251, 41
	s_addc_u32 s11, s25, 0
	s_lshl_b32 s16, s1, 1
	s_add_u32 s1, s8, s16
	s_addc_u32 s12, s11, 0
	s_add_u32 s20, s1, 0x2000
	s_addc_u32 s21, s12, 0
	s_mov_b32 s98, s1
	s_mov_b32 s99, s12
	global_load_dwordx4 v[192:195], v100, s[98:99] offset:2048
	s_add_u32 s98, s98, 0xb000
	s_addc_u32 s99, s99, 0
	global_load_dwordx4 v[196:199], v100, s[98:99] offset:2048
	s_add_u32 s98, s98, 0xb000
	s_addc_u32 s99, s99, 0
	global_load_dwordx4 v[200:203], v100, s[98:99] offset:2048
	s_add_u32 s98, s98, 0xb000
	s_addc_u32 s99, s99, 0
	global_load_dwordx4 v[204:207], v100, s[98:99] offset:2048
	s_add_u32 s98, s98, 0xb000
	s_addc_u32 s99, s99, 0
	global_load_dwordx4 v[208:211], v100, s[98:99] offset:2048
	s_add_u32 s98, s98, 0xb000
	s_addc_u32 s99, s99, 0
	global_load_dwordx4 v[212:215], v100, s[98:99] offset:2048
	s_add_u32 s98, s98, 0xb000
	s_addc_u32 s99, s99, 0
	global_load_dwordx4 v[178:181], v100, s[98:99] offset:2048
	s_add_u32 s98, s98, 0xb000
	s_addc_u32 s99, s99, 0
	global_load_dwordx4 v[182:185], v100, s[98:99] offset:2048
	s_and_b32 s17, s0, 0x1fe0
	s_cmp_lg_u32 s17, 0
	s_cselect_b64 s[28:29], -1, 0
	s_cmp_lt_i32 s5, 2
	s_mov_b64 s[0:1], -1
	s_cbranch_scc1 .LBB0_442
	s_cmp_gt_i32 s5, 2
	s_cbranch_scc0 .LBB0_426
	v_cndmask_b32_e64 v2, 0, 1, s[28:29]
	v_mov_b32_e32 v28, 0
	v_cmp_ne_u32_e64 s[0:1], 1, v2
	s_andn2_b64 vcc, exec, s[28:29]
	v_mov_b32_e32 v29, 0
	s_cbranch_vccnz .LBB0_396
	v_lshl_add_u64 v[2:3], s[20:21], 0, v[26:27]
	v_add_co_u32_e32 v2, vcc, 0xfffd7000, v2
	s_nop 1
	v_addc_co_u32_e32 v3, vcc, -1, v3, vcc
	global_load_dword v29, v[2:3], off offset:-1024

.LBB0_479:
	v_add_co_u32_e32 v20, vcc, 0x1000, v18
	s_mov_b32 s0, 0x12000
	s_nop 0
	v_addc_co_u32_e32 v21, vcc, 0, v19, vcc
	v_add_co_u32_e32 v22, vcc, 0x4000, v18
	s_nop 0
	s_nop 0
	v_addc_co_u32_e32 v23, vcc, 0, v19, vcc
	v_add_co_u32_e32 v24, vcc, 0x6000, v18
	s_nop 0
	s_nop 0
	v_addc_co_u32_e32 v25, vcc, 0, v19, vcc
	v_add_co_u32_e32 v28, vcc, 0x7000, v18
	s_nop 0
	s_nop 0
	v_addc_co_u32_e32 v29, vcc, 0, v19, vcc
	v_add_co_u32_e32 v30, vcc, 0x9000, v18
	global_load_dwordx2 v[138:139], v[20:21], off offset:1024
	global_load_dwordx2 v[140:141], v[20:21], off offset:3072
	global_load_dwordx2 v[142:143], v[22:23], off
	global_load_dwordx2 v[144:145], v[20:21], off offset:2048
	global_load_dwordx2 v[146:147], v[18:19], off offset:1024
	global_load_dwordx2 v[148:149], v[22:23], off offset:2048
	global_load_dwordx2 v[96:97], v[24:25], off offset:3072
	global_load_dwordx2 v[94:95], v[28:29], off
	global_load_dwordx2 v[108:109], v[22:23], off offset:1024
	v_addc_co_u32_e32 v31, vcc, 0, v19, vcc
	v_add_co_u32_e32 v32, vcc, 0xa000, v18
	s_nop 0
	s_nop 0
	v_addc_co_u32_e32 v33, vcc, 0, v19, vcc
	v_add_co_u32_e32 v34, vcc, 0xc000, v18
	global_load_dwordx2 v[100:101], v[28:29], off offset:1024
	global_load_dwordx2 v[90:91], v[30:31], off offset:2048
	global_load_dwordx2 v[66:67], v[32:33], off
	global_load_dwordx2 v[64:65], v[30:31], off offset:3072
	v_addc_co_u32_e32 v35, vcc, 0, v19, vcc
	v_add_co_u32_e32 v38, vcc, 0xf000, v18
	s_nop 1
	v_addc_co_u32_e32 v39, vcc, 0, v19, vcc
	v_add_co_u32_e32 v36, vcc, 0x11000, v18
	global_load_dwordx2 v[60:61], v[34:35], off offset:1024
	global_load_dwordx2 v[58:59], v[34:35], off offset:3072
	global_load_dwordx2 v[46:47], v[38:39], off
	global_load_dwordx2 v[54:55], v[34:35], off offset:2048
	v_addc_co_u32_e32 v37, vcc, 0, v19, vcc
	v_add_co_u32_e32 v40, vcc, s0, v18
	s_mov_b32 s0, 0x14000
	s_nop 0
	v_addc_co_u32_e32 v41, vcc, 0, v19, vcc
	v_add_co_u32_e32 v52, vcc, s0, v18
	s_movk_i32 s0, 0x5000
	s_nop 0
	v_addc_co_u32_e32 v53, vcc, 0, v19, vcc
	v_add_co_u32_e32 v136, vcc, 0x15000, v18
	s_nop 1
	v_addc_co_u32_e32 v137, vcc, 0, v19, vcc
	v_add_co_u32_e32 v102, vcc, 0x3000, v18
	s_nop 1
	v_addc_co_u32_e32 v103, vcc, 0, v19, vcc
	v_add_co_u32_e32 v92, vcc, s0, v18
	s_mov_b32 s0, 0x8000
	s_nop 0
	v_addc_co_u32_e32 v93, vcc, 0, v19, vcc
	v_add_co_u32_e32 v62, vcc, s0, v18
	s_mov_b32 s0, 0xb000
	s_nop 0
	v_addc_co_u32_e32 v63, vcc, 0, v19, vcc
	v_add_co_u32_e32 v50, vcc, s0, v18
	s_mov_b32 s0, 0xe000
	s_nop 0
	v_addc_co_u32_e32 v51, vcc, 0, v19, vcc
	global_load_dwordx2 v[150:151], v[102:103], off
	global_load_dwordx2 v[104:105], v[92:93], off offset:3072
	global_load_dwordx2 v[88:89], v[62:63], off offset:2048
	global_load_dwordx2 v[56:57], v[50:51], off offset:1024
	global_load_dwordx2 v[48:49], v[38:39], off offset:2048
	s_nop 0
	global_load_dwordx2 v[36:37], v[36:37], off offset:3072
	s_nop 0
	global_load_dwordx2 v[34:35], v[40:41], off
	global_load_dwordx2 v[44:45], v[38:39], off offset:1024
	v_add_co_u32_e32 v42, vcc, s0, v18
	s_mov_b32 s0, 0x10000
	s_nop 0
	v_addc_co_u32_e32 v43, vcc, 0, v19, vcc
	v_add_co_u32_e32 v32, vcc, s0, v18
	s_mov_b32 s0, 0x13000
	s_nop 0
	v_addc_co_u32_e32 v33, vcc, 0, v19, vcc
	v_add_co_u32_e32 v20, vcc, s0, v18
	global_load_dwordx2 v[40:41], v[40:41], off offset:1024
	s_nop 0
	global_load_dwordx2 v[30:31], v[52:53], off offset:2048
	global_load_dwordx2 v[28:29], v[136:137], off
	global_load_dwordx2 v[22:23], v[52:53], off offset:3072
	v_addc_co_u32_e32 v21, vcc, 0, v19, vcc
	global_load_dwordx2 v[52:53], v[42:43], off
	global_load_dwordx2 v[38:39], v[32:33], off offset:3072
	global_load_dwordx2 v[24:25], v[20:21], off offset:2048
	s_waitcnt vmcnt(32)
	v_lshlrev_b32_e32 v152, 16, v112
	v_and_b32_e32 v153, 0xffff0000, v112
	v_lshlrev_b32_e32 v112, 16, v113
	v_and_b32_e32 v113, 0xffff0000, v113
	v_lshlrev_b32_e32 v136, 16, v110
	v_and_b32_e32 v137, 0xffff0000, v110
	v_lshlrev_b32_e32 v110, 16, v111
	v_and_b32_e32 v111, 0xffff0000, v111
	v_pk_mul_f32 v[136:137], v[136:137], v[152:153]
	v_pk_mul_f32 v[110:111], v[110:111], v[112:113]
	v_lshlrev_b32_e32 v112, 16, v98
	v_and_b32_e32 v113, 0xffff0000, v98
	v_lshlrev_b32_e32 v152, 16, v106
	v_and_b32_e32 v153, 0xffff0000, v106
	v_lshlrev_b32_e32 v98, 16, v99
	v_and_b32_e32 v99, 0xffff0000, v99
	v_lshlrev_b32_e32 v106, 16, v107
	v_and_b32_e32 v107, 0xffff0000, v107
	v_pk_mul_f32 v[112:113], v[112:113], v[152:153]
	v_pk_mul_f32 v[98:99], v[98:99], v[106:107]
	s_waitcnt vmcnt(31)
	v_lshlrev_b32_e32 v106, 16, v138
	v_and_b32_e32 v107, 0xffff0000, v138
	s_waitcnt vmcnt(30)
	v_lshlrev_b32_e32 v152, 16, v140
	v_and_b32_e32 v153, 0xffff0000, v140
	v_pk_mul_f32 v[106:107], v[106:107], v[152:153]
	s_waitcnt vmcnt(27)
	v_lshlrev_b32_e32 v152, 16, v146
	v_and_b32_e32 v153, 0xffff0000, v146
	v_pk_mul_f32 v[154:155], v[152:153], s[24:25] op_sel_hi:[1,0]
	v_lshlrev_b32_e32 v146, 16, v147
	v_and_b32_e32 v147, 0xffff0000, v147
	v_exp_f32_e32 v154, v154
	v_exp_f32_e32 v155, v155
	v_pk_mul_f32 v[156:157], v[146:147], s[24:25] op_sel_hi:[1,0]
	v_pk_fma_f32 v[112:113], v[10:11], v[112:113], v[14:15]
	v_exp_f32_e32 v156, v156
	v_exp_f32_e32 v157, v157
	v_pk_add_f32 v[154:155], v[154:155], 1.0 op_sel_hi:[1,0]
	v_lshlrev_b32_e32 v138, 16, v139
	v_rcp_f32_e32 v154, v154
	v_rcp_f32_e32 v155, v155
	v_pk_add_f32 v[156:157], v[156:157], 1.0 op_sel_hi:[1,0]
	v_and_b32_e32 v139, 0xffff0000, v139
	v_rcp_f32_e32 v156, v156
	v_rcp_f32_e32 v157, v157
	v_lshlrev_b32_e32 v140, 16, v141
	v_and_b32_e32 v141, 0xffff0000, v141
	v_pk_fma_f32 v[98:99], v[12:13], v[98:99], v[16:17]
	v_pk_fma_f32 v[112:113], v[2:3], v[136:137], v[112:113]
	v_pk_mul_f32 v[138:139], v[138:139], v[140:141]
	v_pk_fma_f32 v[98:99], v[4:5], v[110:111], v[98:99]
	v_pk_fma_f32 v[112:113], v[6:7], v[106:107], v[112:113]
	v_lshlrev_b32_e32 v140, 16, v144
	v_and_b32_e32 v141, 0xffff0000, v144
	v_pk_fma_f32 v[98:99], v[8:9], v[138:139], v[98:99]
	v_lshlrev_b32_e32 v144, 16, v145
	v_and_b32_e32 v145, 0xffff0000, v145
	v_pk_mul_f32 v[152:153], v[154:155], v[152:153]
	v_pk_mul_f32 v[112:113], v[112:113], v[140:141]
	v_pk_mul_f32 v[146:147], v[156:157], v[146:147]
	v_pk_mul_f32 v[98:99], v[98:99], v[144:145]
	v_pk_mul_f32 v[112:113], v[112:113], v[152:153]
	v_pk_mul_f32 v[98:99], v[98:99], v[146:147]
	v_cvt_pk_bf16_f32 v112, v112, v113
	s_waitcnt vmcnt(14)
	v_lshlrev_b32_e32 v146, 16, v151
	v_cvt_pk_bf16_f32 v113, v98, v99
	global_store_dwordx2 v[18:19], v[112:113], off offset:1024
	v_lshlrev_b32_e32 v98, 16, v142
	v_and_b32_e32 v99, 0xffff0000, v142
	v_lshlrev_b32_e32 v112, 16, v148
	v_and_b32_e32 v113, 0xffff0000, v148
	v_pk_mul_f32 v[98:99], v[98:99], v[112:113]
	v_lshlrev_b32_e32 v112, 16, v143
	v_and_b32_e32 v113, 0xffff0000, v143
	v_lshlrev_b32_e32 v142, 16, v150
	v_and_b32_e32 v143, 0xffff0000, v150
	v_pk_mul_f32 v[144:145], v[142:143], s[24:25] op_sel_hi:[1,0]
	v_and_b32_e32 v147, 0xffff0000, v151
	v_lshlrev_b32_e32 v140, 16, v149
	v_and_b32_e32 v141, 0xffff0000, v149
	v_exp_f32_e32 v144, v144
	v_exp_f32_e32 v145, v145
	v_pk_mul_f32 v[148:149], v[146:147], s[24:25] op_sel_hi:[1,0]
	v_pk_fma_f32 v[136:137], v[10:11], v[136:137], v[14:15]
	v_exp_f32_e32 v148, v148
	v_exp_f32_e32 v149, v149
	v_pk_add_f32 v[144:145], v[144:145], 1.0 op_sel_hi:[1,0]
	v_pk_fma_f32 v[110:111], v[12:13], v[110:111], v[16:17]
	v_rcp_f32_e32 v144, v144
	v_rcp_f32_e32 v145, v145
	v_pk_add_f32 v[148:149], v[148:149], 1.0 op_sel_hi:[1,0]
	v_pk_fma_f32 v[136:137], v[2:3], v[106:107], v[136:137]
	v_rcp_f32_e32 v148, v148
	v_rcp_f32_e32 v149, v149
	v_pk_mul_f32 v[112:113], v[112:113], v[140:141]
	v_pk_fma_f32 v[110:111], v[4:5], v[138:139], v[110:111]
	v_pk_fma_f32 v[136:137], v[6:7], v[98:99], v[136:137]
	v_lshlrev_b32_e32 v140, 16, v108
	v_and_b32_e32 v141, 0xffff0000, v108
	v_pk_fma_f32 v[110:111], v[8:9], v[112:113], v[110:111]
	v_lshlrev_b32_e32 v108, 16, v109
	v_and_b32_e32 v109, 0xffff0000, v109
	v_pk_mul_f32 v[142:143], v[144:145], v[142:143]
	v_pk_mul_f32 v[136:137], v[136:137], v[140:141]
	v_pk_mul_f32 v[144:145], v[148:149], v[146:147]
	v_pk_mul_f32 v[108:109], v[110:111], v[108:109]
	v_pk_mul_f32 v[110:111], v[136:137], v[142:143]
	v_pk_mul_f32 v[108:109], v[108:109], v[144:145]
	v_cvt_pk_bf16_f32 v110, v110, v111
	v_pk_fma_f32 v[106:107], v[10:11], v[106:107], v[14:15]
	v_cvt_pk_bf16_f32 v111, v108, v109
	global_store_dwordx2 v[102:103], v[110:111], off
	s_waitcnt vmcnt(15)
	v_lshlrev_b32_e32 v110, 16, v104
	v_and_b32_e32 v111, 0xffff0000, v104
	v_lshlrev_b32_e32 v102, 16, v96
	v_and_b32_e32 v103, 0xffff0000, v96
	v_lshlrev_b32_e32 v108, 16, v100
	v_and_b32_e32 v109, 0xffff0000, v100
	v_lshlrev_b32_e32 v96, 16, v97
	v_and_b32_e32 v97, 0xffff0000, v97
	v_lshlrev_b32_e32 v100, 16, v101
	v_and_b32_e32 v101, 0xffff0000, v101
	v_pk_mul_f32 v[136:137], v[110:111], s[24:25] op_sel_hi:[1,0]
	v_lshlrev_b32_e32 v104, 16, v105
	v_and_b32_e32 v105, 0xffff0000, v105
	v_pk_mul_f32 v[96:97], v[96:97], v[100:101]
	v_pk_fma_f32 v[100:101], v[12:13], v[138:139], v[16:17]
	v_exp_f32_e32 v136, v136
	v_exp_f32_e32 v137, v137
	v_pk_mul_f32 v[138:139], v[104:105], s[24:25] op_sel_hi:[1,0]
	v_pk_mul_f32 v[102:103], v[102:103], v[108:109]
	v_exp_f32_e32 v138, v138
	v_exp_f32_e32 v139, v139
	v_pk_add_f32 v[136:137], v[136:137], 1.0 op_sel_hi:[1,0]
	v_pk_fma_f32 v[106:107], v[2:3], v[98:99], v[106:107]
	v_rcp_f32_e32 v136, v136
	v_rcp_f32_e32 v137, v137
	v_pk_add_f32 v[138:139], v[138:139], 1.0 op_sel_hi:[1,0]
	v_pk_fma_f32 v[100:101], v[4:5], v[112:113], v[100:101]
	v_rcp_f32_e32 v138, v138
	v_rcp_f32_e32 v139, v139
	v_pk_fma_f32 v[106:107], v[6:7], v[102:103], v[106:107]
	v_lshlrev_b32_e32 v108, 16, v94
	v_and_b32_e32 v109, 0xffff0000, v94
	v_pk_fma_f32 v[100:101], v[8:9], v[96:97], v[100:101]
	v_lshlrev_b32_e32 v94, 16, v95
	v_and_b32_e32 v95, 0xffff0000, v95
	v_pk_mul_f32 v[110:111], v[136:137], v[110:111]
	v_pk_mul_f32 v[106:107], v[106:107], v[108:109]
	v_pk_mul_f32 v[104:105], v[138:139], v[104:105]
	v_pk_mul_f32 v[94:95], v[100:101], v[94:95]
	v_pk_mul_f32 v[100:101], v[106:107], v[110:111]
	v_pk_mul_f32 v[94:95], v[94:95], v[104:105]
	v_cvt_pk_bf16_f32 v100, v100, v101
	s_mov_b32 s0, 0x17000
	v_cvt_pk_bf16_f32 v101, v94, v95
	global_store_dwordx2 v[92:93], v[100:101], off offset:3072
	s_waitcnt vmcnt(15)
	v_lshlrev_b32_e32 v100, 16, v88
	v_and_b32_e32 v101, 0xffff0000, v88
	v_lshlrev_b32_e32 v88, 16, v89
	v_and_b32_e32 v89, 0xffff0000, v89
	v_pk_mul_f32 v[104:105], v[100:101], s[24:25] op_sel_hi:[1,0]
	v_pk_mul_f32 v[106:107], v[88:89], s[24:25] op_sel_hi:[1,0]
	v_exp_f32_e32 v104, v104
	v_exp_f32_e32 v105, v105
	v_exp_f32_e32 v106, v106
	v_exp_f32_e32 v107, v107
	v_lshlrev_b32_e32 v92, 16, v90
	v_pk_add_f32 v[104:105], v[104:105], 1.0 op_sel_hi:[1,0]
	v_and_b32_e32 v93, 0xffff0000, v90
	v_pk_add_f32 v[106:107], v[106:107], 1.0 op_sel_hi:[1,0]
	v_lshlrev_b32_e32 v94, 16, v66
	v_and_b32_e32 v95, 0xffff0000, v66
	v_lshlrev_b32_e32 v90, 16, v91
	v_and_b32_e32 v91, 0xffff0000, v91
	v_lshlrev_b32_e32 v66, 16, v67
	v_and_b32_e32 v67, 0xffff0000, v67
	v_rcp_f32_e32 v104, v104
	v_rcp_f32_e32 v105, v105
	v_rcp_f32_e32 v106, v106
	v_rcp_f32_e32 v107, v107
	v_pk_mul_f32 v[92:93], v[92:93], v[94:95]
	v_pk_mul_f32 v[66:67], v[90:91], v[66:67]
	v_pk_fma_f32 v[90:91], v[12:13], v[112:113], v[16:17]
	v_pk_fma_f32 v[94:95], v[10:11], v[98:99], v[14:15]
	v_pk_fma_f32 v[90:91], v[4:5], v[96:97], v[90:91]
	v_pk_fma_f32 v[94:95], v[2:3], v[102:103], v[94:95]
	v_pk_fma_f32 v[90:91], v[8:9], v[66:67], v[90:91]
	v_pk_fma_f32 v[94:95], v[6:7], v[92:93], v[94:95]
	v_lshlrev_b32_e32 v98, 16, v64
	v_and_b32_e32 v99, 0xffff0000, v64
	v_lshlrev_b32_e32 v64, 16, v65
	v_and_b32_e32 v65, 0xffff0000, v65
	v_pk_mul_f32 v[100:101], v[104:105], v[100:101]
	v_pk_mul_f32 v[88:89], v[106:107], v[88:89]
	v_pk_mul_f32 v[94:95], v[94:95], v[98:99]
	v_pk_mul_f32 v[64:65], v[90:91], v[64:65]
	s_waitcnt vmcnt(14)
	v_lshlrev_b32_e32 v90, 16, v56
	v_pk_mul_f32 v[64:65], v[64:65], v[88:89]
	v_pk_mul_f32 v[88:89], v[94:95], v[100:101]
	v_and_b32_e32 v91, 0xffff0000, v56
	v_cvt_pk_bf16_f32 v88, v88, v89
	v_cvt_pk_bf16_f32 v89, v64, v65
	global_store_dwordx2 v[62:63], v[88:89], off offset:2048
	v_lshlrev_b32_e32 v62, 16, v60
	v_and_b32_e32 v63, 0xffff0000, v60
	v_lshlrev_b32_e32 v64, 16, v58
	v_and_b32_e32 v65, 0xffff0000, v58
	v_lshlrev_b32_e32 v60, 16, v61
	v_and_b32_e32 v61, 0xffff0000, v61
	v_lshlrev_b32_e32 v58, 16, v59
	v_and_b32_e32 v59, 0xffff0000, v59
	v_lshlrev_b32_e32 v56, 16, v57
	v_and_b32_e32 v57, 0xffff0000, v57
	v_pk_mul_f32 v[60:61], v[60:61], v[58:59]
	v_pk_fma_f32 v[58:59], v[12:13], v[96:97], v[16:17]
	v_pk_mul_f32 v[94:95], v[90:91], s[24:25] op_sel_hi:[1,0]
	v_pk_mul_f32 v[96:97], v[56:57], s[24:25] op_sel_hi:[1,0]
	v_exp_f32_e32 v94, v94
	v_exp_f32_e32 v95, v95
	v_exp_f32_e32 v96, v96
	v_exp_f32_e32 v97, v97
	v_pk_mul_f32 v[62:63], v[62:63], v[64:65]
	v_pk_add_f32 v[94:95], v[94:95], 1.0 op_sel_hi:[1,0]
	v_pk_fma_f32 v[64:65], v[10:11], v[102:103], v[14:15]
	v_pk_add_f32 v[96:97], v[96:97], 1.0 op_sel_hi:[1,0]
	v_rcp_f32_e32 v94, v94
	v_rcp_f32_e32 v95, v95
	v_rcp_f32_e32 v96, v96
	v_rcp_f32_e32 v97, v97
	v_pk_fma_f32 v[64:65], v[2:3], v[92:93], v[64:65]
	v_pk_fma_f32 v[58:59], v[4:5], v[66:67], v[58:59]
	v_pk_fma_f32 v[64:65], v[6:7], v[62:63], v[64:65]
	v_pk_fma_f32 v[58:59], v[8:9], v[60:61], v[58:59]
	v_lshlrev_b32_e32 v88, 16, v54
	v_and_b32_e32 v89, 0xffff0000, v54
	v_lshlrev_b32_e32 v54, 16, v55
	v_and_b32_e32 v55, 0xffff0000, v55
	v_pk_mul_f32 v[90:91], v[94:95], v[90:91]
	v_pk_mul_f32 v[56:57], v[96:97], v[56:57]
	v_pk_mul_f32 v[64:65], v[64:65], v[88:89]
	v_pk_mul_f32 v[54:55], v[58:59], v[54:55]
	s_waitcnt vmcnt(6)
	v_lshlrev_b32_e32 v58, 16, v52
	v_pk_mul_f32 v[54:55], v[54:55], v[56:57]
	v_pk_mul_f32 v[56:57], v[64:65], v[90:91]
	v_and_b32_e32 v59, 0xffff0000, v52
	v_cvt_pk_bf16_f32 v56, v56, v57
	v_cvt_pk_bf16_f32 v57, v54, v55
	global_store_dwordx2 v[50:51], v[56:57], off offset:1024
	v_lshlrev_b32_e32 v50, 16, v46
	v_and_b32_e32 v51, 0xffff0000, v46
	v_lshlrev_b32_e32 v54, 16, v48
	v_and_b32_e32 v55, 0xffff0000, v48
	v_lshlrev_b32_e32 v46, 16, v47
	v_and_b32_e32 v47, 0xffff0000, v47
	v_lshlrev_b32_e32 v48, 16, v49
	v_and_b32_e32 v49, 0xffff0000, v49
	v_lshlrev_b32_e32 v52, 16, v53
	v_and_b32_e32 v53, 0xffff0000, v53
	v_pk_mul_f32 v[46:47], v[46:47], v[48:49]
	v_pk_fma_f32 v[48:49], v[12:13], v[66:67], v[16:17]
	v_pk_mul_f32 v[64:65], v[58:59], s[24:25] op_sel_hi:[1,0]
	v_pk_mul_f32 v[66:67], v[52:53], s[24:25] op_sel_hi:[1,0]
	v_exp_f32_e32 v64, v64
	v_exp_f32_e32 v65, v65
	v_exp_f32_e32 v66, v66
	v_exp_f32_e32 v67, v67
	v_pk_mul_f32 v[50:51], v[50:51], v[54:55]
	v_pk_add_f32 v[64:65], v[64:65], 1.0 op_sel_hi:[1,0]
	v_pk_fma_f32 v[54:55], v[10:11], v[92:93], v[14:15]
	v_pk_add_f32 v[66:67], v[66:67], 1.0 op_sel_hi:[1,0]
	v_rcp_f32_e32 v64, v64
	v_rcp_f32_e32 v65, v65
	v_rcp_f32_e32 v66, v66
	v_rcp_f32_e32 v67, v67
	v_pk_fma_f32 v[54:55], v[2:3], v[62:63], v[54:55]
	v_pk_fma_f32 v[48:49], v[4:5], v[60:61], v[48:49]
	v_pk_fma_f32 v[54:55], v[6:7], v[50:51], v[54:55]
	v_pk_fma_f32 v[48:49], v[8:9], v[46:47], v[48:49]
	v_lshlrev_b32_e32 v56, 16, v44
	v_and_b32_e32 v57, 0xffff0000, v44
	v_lshlrev_b32_e32 v44, 16, v45
	v_and_b32_e32 v45, 0xffff0000, v45
	v_pk_mul_f32 v[58:59], v[64:65], v[58:59]
	v_pk_mul_f32 v[52:53], v[66:67], v[52:53]
	v_pk_mul_f32 v[54:55], v[54:55], v[56:57]
	v_pk_mul_f32 v[44:45], v[48:49], v[44:45]
	v_pk_mul_f32 v[48:49], v[54:55], v[58:59]
	v_pk_mul_f32 v[44:45], v[44:45], v[52:53]
	v_cvt_pk_bf16_f32 v48, v48, v49
	s_nop 0
	v_cvt_pk_bf16_f32 v49, v44, v45
	global_store_dwordx2 v[42:43], v[48:49], off
	v_lshlrev_b32_e32 v42, 16, v36
	v_and_b32_e32 v43, 0xffff0000, v36
	v_lshlrev_b32_e32 v44, 16, v40
	v_and_b32_e32 v45, 0xffff0000, v40
	v_pk_mul_f32 v[58:59], v[42:43], v[44:45]
	s_waitcnt vmcnt(7)
	v_lshlrev_b32_e32 v44, 16, v38
	v_and_b32_e32 v45, 0xffff0000, v38
	v_lshlrev_b32_e32 v38, 16, v39
	v_and_b32_e32 v39, 0xffff0000, v39
	v_pk_mul_f32 v[48:49], v[44:45], s[24:25] op_sel_hi:[1,0]
	v_pk_mul_f32 v[52:53], v[38:39], s[24:25] op_sel_hi:[1,0]
	v_exp_f32_e32 v48, v48
	v_exp_f32_e32 v49, v49
	v_exp_f32_e32 v52, v52
	v_exp_f32_e32 v53, v53
	v_lshlrev_b32_e32 v36, 16, v37
	v_pk_add_f32 v[48:49], v[48:49], 1.0 op_sel_hi:[1,0]
	v_and_b32_e32 v37, 0xffff0000, v37
	v_pk_add_f32 v[52:53], v[52:53], 1.0 op_sel_hi:[1,0]
	v_lshlrev_b32_e32 v40, 16, v41
	v_and_b32_e32 v41, 0xffff0000, v41
	v_rcp_f32_e32 v48, v48
	v_rcp_f32_e32 v49, v49
	v_rcp_f32_e32 v52, v52
	v_rcp_f32_e32 v53, v53
	v_pk_mul_f32 v[66:67], v[36:37], v[40:41]
	v_pk_fma_f32 v[36:37], v[12:13], v[60:61], v[16:17]
	v_pk_fma_f32 v[40:41], v[10:11], v[62:63], v[14:15]
	v_pk_fma_f32 v[36:37], v[4:5], v[46:47], v[36:37]
	v_pk_fma_f32 v[40:41], v[2:3], v[50:51], v[40:41]
	v_pk_fma_f32 v[36:37], v[8:9], v[66:67], v[36:37]
	v_pk_fma_f32 v[40:41], v[6:7], v[58:59], v[40:41]
	v_lshlrev_b32_e32 v42, 16, v34
	v_and_b32_e32 v43, 0xffff0000, v34
	v_lshlrev_b32_e32 v34, 16, v35
	v_and_b32_e32 v35, 0xffff0000, v35
	v_pk_mul_f32 v[44:45], v[48:49], v[44:45]
	v_pk_mul_f32 v[38:39], v[52:53], v[38:39]
	v_pk_mul_f32 v[40:41], v[40:41], v[42:43]
	v_pk_mul_f32 v[34:35], v[36:37], v[34:35]
	v_pk_mul_f32 v[36:37], v[40:41], v[44:45]
	v_pk_mul_f32 v[34:35], v[34:35], v[38:39]
	v_cvt_pk_bf16_f32 v36, v36, v37
	s_nop 0
	v_cvt_pk_bf16_f32 v37, v34, v35
	global_store_dwordx2 v[32:33], v[36:37], off offset:3072
	v_lshlrev_b32_e32 v32, 16, v30
	v_and_b32_e32 v33, 0xffff0000, v30
	v_lshlrev_b32_e32 v34, 16, v28
	v_and_b32_e32 v35, 0xffff0000, v28
	v_pk_mul_f32 v[60:61], v[32:33], v[34:35]
	s_waitcnt vmcnt(7)
	v_lshlrev_b32_e32 v34, 16, v24
	v_and_b32_e32 v35, 0xffff0000, v24
	v_lshlrev_b32_e32 v24, 16, v25
	v_and_b32_e32 v25, 0xffff0000, v25
	v_pk_mul_f32 v[36:37], v[34:35], s[24:25] op_sel_hi:[1,0]
	v_pk_mul_f32 v[38:39], v[24:25], s[24:25] op_sel_hi:[1,0]
	v_exp_f32_e32 v36, v36
	v_exp_f32_e32 v37, v37
	v_exp_f32_e32 v38, v38
	v_exp_f32_e32 v39, v39
	v_lshlrev_b32_e32 v30, 16, v31
	v_pk_add_f32 v[36:37], v[36:37], 1.0 op_sel_hi:[1,0]
	v_and_b32_e32 v31, 0xffff0000, v31
	v_pk_add_f32 v[38:39], v[38:39], 1.0 op_sel_hi:[1,0]
	v_lshlrev_b32_e32 v28, 16, v29
	v_and_b32_e32 v29, 0xffff0000, v29
	v_rcp_f32_e32 v36, v36
	v_rcp_f32_e32 v37, v37
	v_rcp_f32_e32 v38, v38
	v_rcp_f32_e32 v39, v39
	v_pk_mul_f32 v[88:89], v[30:31], v[28:29]
	v_pk_fma_f32 v[28:29], v[12:13], v[46:47], v[16:17]
	v_pk_fma_f32 v[30:31], v[10:11], v[50:51], v[14:15]
	v_pk_fma_f32 v[28:29], v[4:5], v[66:67], v[28:29]
	v_pk_fma_f32 v[30:31], v[2:3], v[58:59], v[30:31]
	v_pk_fma_f32 v[28:29], v[8:9], v[88:89], v[28:29]
	v_pk_fma_f32 v[30:31], v[6:7], v[60:61], v[30:31]
	v_lshlrev_b32_e32 v32, 16, v22
	v_and_b32_e32 v33, 0xffff0000, v22
	v_lshlrev_b32_e32 v22, 16, v23
	v_and_b32_e32 v23, 0xffff0000, v23
	v_pk_mul_f32 v[34:35], v[36:37], v[34:35]
	v_pk_mul_f32 v[24:25], v[38:39], v[24:25]
	v_pk_mul_f32 v[30:31], v[30:31], v[32:33]
	v_pk_mul_f32 v[22:23], v[28:29], v[22:23]
	v_pk_fma_f32 v[58:59], v[10:11], v[58:59], v[14:15]
	v_pk_mul_f32 v[22:23], v[22:23], v[24:25]
	v_pk_mul_f32 v[24:25], v[30:31], v[34:35]
	v_pk_fma_f32 v[66:67], v[12:13], v[66:67], v[16:17]
	v_cvt_pk_bf16_f32 v24, v24, v25
	v_cvt_pk_bf16_f32 v25, v22, v23
	global_store_dwordx2 v[20:21], v[24:25], off offset:2048
	v_add_co_u32_e32 v20, vcc, s0, v18
	s_mov_b32 s0, 0x1a000
	s_nop 0
	v_addc_co_u32_e32 v21, vcc, 0, v19, vcc
	v_add_co_u32_e32 v32, vcc, s0, v18
	s_mov_b32 s0, 0x1c000
	s_nop 0
	v_addc_co_u32_e32 v33, vcc, 0, v19, vcc
	v_add_co_u32_e32 v34, vcc, s0, v18
	s_mov_b32 s0, 0x1d000
	s_nop 0
	v_addc_co_u32_e32 v35, vcc, 0, v19, vcc
	v_add_co_u32_e32 v94, vcc, s0, v18
	s_mov_b32 s0, 0x1f000
	s_nop 0
	v_addc_co_u32_e32 v95, vcc, 0, v19, vcc
	v_add_co_u32_e32 v108, vcc, s0, v18
	s_mov_b32 s0, 0x20000
	s_nop 0
	v_addc_co_u32_e32 v109, vcc, 0, v19, vcc
	v_add_co_u32_e32 v100, vcc, s0, v18
	s_mov_b32 s0, 0x1e000
	s_nop 0
	v_addc_co_u32_e32 v101, vcc, 0, v19, vcc
	v_add_co_u32_e32 v52, vcc, s0, v18
	s_mov_b32 s0, 0x1b000
	s_nop 0
	v_addc_co_u32_e32 v53, vcc, 0, v19, vcc
	v_add_co_u32_e32 v92, vcc, s0, v18
	s_mov_b32 s0, 0x19000
	s_nop 0
	v_addc_co_u32_e32 v93, vcc, 0, v19, vcc
	global_load_dwordx2 v[104:105], v[20:21], off offset:1024
	global_load_dwordx2 v[106:107], v[20:21], off offset:3072
	v_add_co_u32_e32 v110, vcc, s0, v18
	global_load_dwordx2 v[98:99], v[32:33], off offset:2048
	s_nop 0
	v_addc_co_u32_e32 v111, vcc, 0, v19, vcc
	v_add_co_u32_e32 v112, vcc, s81, v18
	s_mov_b32 s0, 0x22000
	s_nop 0
	v_addc_co_u32_e32 v113, vcc, 0, v19, vcc
	global_load_dwordx2 v[62:63], v[52:53], off offset:2048
	global_load_dwordx2 v[96:97], v[92:93], off offset:3072
	global_load_dwordx2 v[136:137], v[110:111], off
	global_load_dwordx2 v[138:139], v[112:113], off offset:1024
	global_load_dwordx2 v[140:141], v[32:33], off
	global_load_dwordx2 v[142:143], v[20:21], off offset:2048
	v_add_co_u32_e32 v54, vcc, s0, v18
	s_mov_b32 s0, 0x25000
	s_nop 0
	v_addc_co_u32_e32 v55, vcc, 0, v19, vcc
	v_add_co_u32_e32 v48, vcc, s0, v18
	s_mov_b32 s0, 0x27000
	s_nop 0
	v_addc_co_u32_e32 v49, vcc, 0, v19, vcc
	v_add_co_u32_e32 v38, vcc, s0, v18
	s_mov_b32 s0, 0x28000
	s_nop 0
	v_addc_co_u32_e32 v39, vcc, 0, v19, vcc
	v_add_co_u32_e32 v42, vcc, s0, v18
	s_mov_b32 s0, 0x2a000
	s_nop 0
	v_addc_co_u32_e32 v43, vcc, 0, v19, vcc
	v_add_co_u32_e32 v22, vcc, s0, v18
	s_mov_b32 s0, 0x2b000
	s_nop 0
	v_addc_co_u32_e32 v23, vcc, 0, v19, vcc
	v_add_co_u32_e32 v24, vcc, s0, v18
	s_mov_b32 s0, 0x29000
	s_nop 0
	v_addc_co_u32_e32 v25, vcc, 0, v19, vcc
	v_add_co_u32_e32 v20, vcc, s0, v18
	s_mov_b32 s0, 0x26000
	s_nop 0
	v_addc_co_u32_e32 v21, vcc, 0, v19, vcc
	v_add_co_u32_e32 v30, vcc, s0, v18
	s_mov_b32 s0, 0x24000
	s_nop 0
	v_addc_co_u32_e32 v31, vcc, 0, v19, vcc
	global_load_dwordx2 v[36:37], v[42:43], off offset:1024
	global_load_dwordx2 v[28:29], v[22:23], off offset:2048
	s_nop 0
	global_load_dwordx2 v[24:25], v[24:25], off
	s_nop 0
	global_load_dwordx2 v[22:23], v[22:23], off offset:3072
	v_add_co_u32_e32 v40, vcc, s0, v18
	global_load_dwordx2 v[144:145], v[34:35], off offset:3072
	global_load_dwordx2 v[146:147], v[94:95], off
	global_load_dwordx2 v[148:149], v[32:33], off offset:1024
	global_load_dwordx2 v[46:47], v[48:49], off offset:2048
	s_nop 0
	global_load_dwordx2 v[38:39], v[38:39], off offset:3072
	s_nop 0
	global_load_dwordx2 v[32:33], v[42:43], off
	s_nop 0
	global_load_dwordx2 v[42:43], v[48:49], off offset:1024
	v_addc_co_u32_e32 v41, vcc, 0, v19, vcc
	s_mov_b32 s0, 0x21000
	v_add_co_u32_e32 v50, vcc, s0, v18
	v_pk_fma_f32 v[58:59], v[2:3], v[60:61], v[58:59]
	s_nop 0
	v_addc_co_u32_e32 v51, vcc, 0, v19, vcc
	global_load_dwordx2 v[18:19], v[20:21], off offset:2048
	global_load_dwordx2 v[34:35], v[30:31], off offset:3072
	global_load_dwordx2 v[44:45], v[40:41], off
	global_load_dwordx2 v[56:57], v[50:51], off offset:1024
	global_load_dwordx2 v[90:91], v[54:55], off offset:1024
	global_load_dwordx2 v[64:65], v[54:55], off offset:3072
	s_nop 0
	global_load_dwordx2 v[48:49], v[48:49], off
	s_nop 0
	global_load_dwordx2 v[54:55], v[54:55], off offset:2048
	s_nop 0
	global_load_dwordx2 v[150:151], v[94:95], off offset:1024
	global_load_dwordx2 v[102:103], v[108:109], off offset:2048
	s_nop 0
	global_load_dwordx2 v[100:101], v[100:101], off
	s_nop 0
	global_load_dwordx2 v[94:95], v[108:109], off offset:3072
	v_pk_fma_f32 v[66:67], v[4:5], v[88:89], v[66:67]
	v_pk_fma_f32 v[60:61], v[10:11], v[60:61], v[14:15]
	v_pk_fma_f32 v[88:89], v[12:13], v[88:89], v[16:17]
	s_mov_b64 s[0:1], 0
	s_waitcnt vmcnt(31)
	v_lshlrev_b32_e32 v108, 16, v104
	v_and_b32_e32 v109, 0xffff0000, v104
	s_waitcnt vmcnt(30)
	v_lshlrev_b32_e32 v152, 16, v106
	v_and_b32_e32 v153, 0xffff0000, v106
	v_pk_mul_f32 v[108:109], v[108:109], v[152:153]
	v_lshlrev_b32_e32 v104, 16, v105
	v_and_b32_e32 v105, 0xffff0000, v105
	v_lshlrev_b32_e32 v106, 16, v107
	v_and_b32_e32 v107, 0xffff0000, v107
	v_pk_mul_f32 v[104:105], v[104:105], v[106:107]
	s_waitcnt vmcnt(25)
	v_lshlrev_b32_e32 v152, 16, v138
	v_and_b32_e32 v153, 0xffff0000, v138
	v_pk_mul_f32 v[154:155], v[152:153], s[24:25] op_sel_hi:[1,0]
	v_lshlrev_b32_e32 v138, 16, v139
	v_and_b32_e32 v139, 0xffff0000, v139
	v_exp_f32_e32 v154, v154
	v_exp_f32_e32 v155, v155
	v_pk_mul_f32 v[156:157], v[138:139], s[24:25] op_sel_hi:[1,0]
	v_pk_fma_f32 v[58:59], v[6:7], v[108:109], v[58:59]
	v_exp_f32_e32 v156, v156
	v_exp_f32_e32 v157, v157
	v_pk_add_f32 v[154:155], v[154:155], 1.0 op_sel_hi:[1,0]
	s_waitcnt vmcnt(23)
	v_lshlrev_b32_e32 v106, 16, v142
	v_rcp_f32_e32 v154, v154
	v_rcp_f32_e32 v155, v155
	v_pk_add_f32 v[156:157], v[156:157], 1.0 op_sel_hi:[1,0]
	v_and_b32_e32 v107, 0xffff0000, v142
	v_rcp_f32_e32 v156, v156
	v_rcp_f32_e32 v157, v157
	v_pk_fma_f32 v[66:67], v[8:9], v[104:105], v[66:67]
	v_lshlrev_b32_e32 v142, 16, v143
	v_and_b32_e32 v143, 0xffff0000, v143
	v_pk_mul_f32 v[152:153], v[154:155], v[152:153]
	v_pk_mul_f32 v[58:59], v[58:59], v[106:107]
	v_pk_mul_f32 v[138:139], v[156:157], v[138:139]
	v_pk_mul_f32 v[66:67], v[66:67], v[142:143]
	v_pk_mul_f32 v[58:59], v[58:59], v[152:153]
	v_lshlrev_b32_e32 v106, 16, v136
	v_and_b32_e32 v107, 0xffff0000, v136
	v_pk_mul_f32 v[66:67], v[66:67], v[138:139]
	v_cvt_pk_bf16_f32 v58, v58, v59
	v_lshlrev_b32_e32 v136, 16, v137
	v_cvt_pk_bf16_f32 v59, v66, v67
	global_store_dwordx2 v[112:113], v[58:59], off offset:1024
	v_pk_mul_f32 v[112:113], v[106:107], s[24:25] op_sel_hi:[1,0]
	v_and_b32_e32 v137, 0xffff0000, v137
	v_exp_f32_e32 v112, v112
	v_exp_f32_e32 v113, v113
	v_pk_mul_f32 v[138:139], v[136:137], s[24:25] op_sel_hi:[1,0]
	v_lshlrev_b32_e32 v58, 16, v140
	v_exp_f32_e32 v138, v138
	v_exp_f32_e32 v139, v139
	v_pk_add_f32 v[112:113], v[112:113], 1.0 op_sel_hi:[1,0]
	v_and_b32_e32 v59, 0xffff0000, v140
	v_rcp_f32_e32 v112, v112
	v_rcp_f32_e32 v113, v113
	v_pk_add_f32 v[138:139], v[138:139], 1.0 op_sel_hi:[1,0]
	v_lshlrev_b32_e32 v66, 16, v98
	v_and_b32_e32 v67, 0xffff0000, v98
	v_rcp_f32_e32 v138, v138
	v_rcp_f32_e32 v139, v139
	v_pk_mul_f32 v[58:59], v[58:59], v[66:67]
	v_lshlrev_b32_e32 v66, 16, v141
	v_and_b32_e32 v67, 0xffff0000, v141
	v_lshlrev_b32_e32 v98, 16, v99
	v_and_b32_e32 v99, 0xffff0000, v99
	v_pk_fma_f32 v[60:61], v[2:3], v[108:109], v[60:61]
	v_pk_mul_f32 v[66:67], v[66:67], v[98:99]
	v_pk_fma_f32 v[88:89], v[4:5], v[104:105], v[88:89]
	v_pk_fma_f32 v[60:61], v[6:7], v[58:59], v[60:61]
	s_waitcnt vmcnt(17)
	v_lshlrev_b32_e32 v98, 16, v148
	v_and_b32_e32 v99, 0xffff0000, v148
	v_pk_fma_f32 v[88:89], v[8:9], v[66:67], v[88:89]
	v_lshlrev_b32_e32 v140, 16, v149
	v_and_b32_e32 v141, 0xffff0000, v149
	v_pk_mul_f32 v[106:107], v[112:113], v[106:107]
	v_pk_mul_f32 v[60:61], v[60:61], v[98:99]
	v_pk_mul_f32 v[112:113], v[138:139], v[136:137]
	v_pk_mul_f32 v[88:89], v[88:89], v[140:141]
	v_pk_mul_f32 v[60:61], v[60:61], v[106:107]
	v_pk_mul_f32 v[88:89], v[88:89], v[112:113]
	v_cvt_pk_bf16_f32 v60, v60, v61
	s_waitcnt vmcnt(4)
	v_lshlrev_b32_e32 v98, 16, v151
	v_cvt_pk_bf16_f32 v61, v88, v89
	global_store_dwordx2 v[110:111], v[60:61], off
	v_lshlrev_b32_e32 v60, 16, v144
	v_and_b32_e32 v61, 0xffff0000, v144
	v_lshlrev_b32_e32 v88, 16, v150
	v_and_b32_e32 v89, 0xffff0000, v150
	v_pk_mul_f32 v[60:61], v[60:61], v[88:89]
	v_lshlrev_b32_e32 v88, 16, v145
	v_and_b32_e32 v89, 0xffff0000, v145
	v_and_b32_e32 v99, 0xffff0000, v151
	v_pk_mul_f32 v[88:89], v[88:89], v[98:99]
	v_pk_fma_f32 v[98:99], v[12:13], v[104:105], v[16:17]
	v_pk_fma_f32 v[104:105], v[10:11], v[108:109], v[14:15]
	v_lshlrev_b32_e32 v108, 16, v96
	v_and_b32_e32 v109, 0xffff0000, v96
	v_lshlrev_b32_e32 v96, 16, v97
	v_and_b32_e32 v97, 0xffff0000, v97
	v_pk_mul_f32 v[110:111], v[108:109], s[24:25] op_sel_hi:[1,0]
	v_pk_mul_f32 v[112:113], v[96:97], s[24:25] op_sel_hi:[1,0]
	v_exp_f32_e32 v110, v110
	v_exp_f32_e32 v111, v111
	v_exp_f32_e32 v112, v112
	v_exp_f32_e32 v113, v113
	v_pk_fma_f32 v[104:105], v[2:3], v[58:59], v[104:105]
	v_pk_add_f32 v[110:111], v[110:111], 1.0 op_sel_hi:[1,0]
	v_pk_fma_f32 v[98:99], v[4:5], v[66:67], v[98:99]
	v_pk_add_f32 v[112:113], v[112:113], 1.0 op_sel_hi:[1,0]
	v_rcp_f32_e32 v110, v110
	v_rcp_f32_e32 v111, v111
	v_rcp_f32_e32 v112, v112
	v_rcp_f32_e32 v113, v113
	v_pk_fma_f32 v[98:99], v[8:9], v[88:89], v[98:99]
	v_pk_fma_f32 v[104:105], v[6:7], v[60:61], v[104:105]
	v_lshlrev_b32_e32 v106, 16, v146
	v_and_b32_e32 v107, 0xffff0000, v146
	v_lshlrev_b32_e32 v136, 16, v147
	v_and_b32_e32 v137, 0xffff0000, v147
	v_pk_mul_f32 v[108:109], v[110:111], v[108:109]
	v_pk_mul_f32 v[96:97], v[112:113], v[96:97]
	v_pk_mul_f32 v[104:105], v[104:105], v[106:107]
	v_pk_mul_f32 v[98:99], v[98:99], v[136:137]
	v_pk_fma_f32 v[58:59], v[10:11], v[58:59], v[14:15]
	v_pk_mul_f32 v[96:97], v[98:99], v[96:97]
	v_pk_mul_f32 v[98:99], v[104:105], v[108:109]
	v_pk_fma_f32 v[66:67], v[12:13], v[66:67], v[16:17]
	v_cvt_pk_bf16_f32 v98, v98, v99
	v_cvt_pk_bf16_f32 v99, v96, v97
	global_store_dwordx2 v[92:93], v[98:99], off offset:3072
	s_waitcnt vmcnt(5)
	v_lshlrev_b32_e32 v92, 16, v102
	v_and_b32_e32 v93, 0xffff0000, v102
	s_waitcnt vmcnt(4)
	v_lshlrev_b32_e32 v96, 16, v100
	v_and_b32_e32 v97, 0xffff0000, v100
	v_lshlrev_b32_e32 v98, 16, v101
	v_and_b32_e32 v99, 0xffff0000, v101
	v_lshlrev_b32_e32 v100, 16, v62
	v_and_b32_e32 v101, 0xffff0000, v62
	v_pk_mul_f32 v[92:93], v[92:93], v[96:97]
	v_lshlrev_b32_e32 v96, 16, v103
	v_and_b32_e32 v97, 0xffff0000, v103
	v_pk_mul_f32 v[102:103], v[100:101], s[24:25] op_sel_hi:[1,0]
	v_lshlrev_b32_e32 v62, 16, v63
	v_and_b32_e32 v63, 0xffff0000, v63
	v_exp_f32_e32 v102, v102
	v_exp_f32_e32 v103, v103
	v_pk_mul_f32 v[104:105], v[62:63], s[24:25] op_sel_hi:[1,0]
	v_pk_fma_f32 v[58:59], v[2:3], v[60:61], v[58:59]
	v_exp_f32_e32 v104, v104
	v_exp_f32_e32 v105, v105
	v_pk_add_f32 v[102:103], v[102:103], 1.0 op_sel_hi:[1,0]
	v_pk_mul_f32 v[96:97], v[96:97], v[98:99]
	v_rcp_f32_e32 v102, v102
	v_rcp_f32_e32 v103, v103
	v_pk_add_f32 v[104:105], v[104:105], 1.0 op_sel_hi:[1,0]
	v_pk_fma_f32 v[66:67], v[4:5], v[88:89], v[66:67]
	v_rcp_f32_e32 v104, v104
	v_rcp_f32_e32 v105, v105
	v_pk_fma_f32 v[58:59], v[6:7], v[92:93], v[58:59]
	s_waitcnt vmcnt(3)
	v_lshlrev_b32_e32 v98, 16, v94
	v_and_b32_e32 v99, 0xffff0000, v94
	v_pk_fma_f32 v[66:67], v[8:9], v[96:97], v[66:67]
	v_lshlrev_b32_e32 v94, 16, v95
	v_and_b32_e32 v95, 0xffff0000, v95
	v_pk_mul_f32 v[100:101], v[102:103], v[100:101]
	v_pk_mul_f32 v[58:59], v[58:59], v[98:99]
	v_pk_mul_f32 v[62:63], v[104:105], v[62:63]
	v_pk_mul_f32 v[66:67], v[66:67], v[94:95]
	v_pk_mul_f32 v[58:59], v[58:59], v[100:101]
	v_pk_mul_f32 v[62:63], v[66:67], v[62:63]
	v_cvt_pk_bf16_f32 v58, v58, v59
	v_lshlrev_b32_e32 v66, 16, v56
	v_cvt_pk_bf16_f32 v59, v62, v63
	global_store_dwordx2 v[52:53], v[58:59], off offset:2048
	v_lshlrev_b32_e32 v52, 16, v90
	v_and_b32_e32 v53, 0xffff0000, v90
	v_lshlrev_b32_e32 v58, 16, v64
	v_and_b32_e32 v59, 0xffff0000, v64
	v_pk_mul_f32 v[52:53], v[52:53], v[58:59]
	v_lshlrev_b32_e32 v58, 16, v91
	v_and_b32_e32 v59, 0xffff0000, v91
	v_lshlrev_b32_e32 v62, 16, v65
	v_and_b32_e32 v63, 0xffff0000, v65
	v_and_b32_e32 v67, 0xffff0000, v56
	v_lshlrev_b32_e32 v56, 16, v57
	v_and_b32_e32 v57, 0xffff0000, v57
	v_pk_mul_f32 v[58:59], v[58:59], v[62:63]
	v_pk_fma_f32 v[62:63], v[12:13], v[88:89], v[16:17]
	v_pk_mul_f32 v[88:89], v[66:67], s[24:25] op_sel_hi:[1,0]
	v_pk_mul_f32 v[90:91], v[56:57], s[24:25] op_sel_hi:[1,0]
	v_exp_f32_e32 v88, v88
	v_exp_f32_e32 v89, v89
	v_exp_f32_e32 v90, v90
	v_exp_f32_e32 v91, v91
	v_pk_fma_f32 v[60:61], v[10:11], v[60:61], v[14:15]
	v_pk_add_f32 v[88:89], v[88:89], 1.0 op_sel_hi:[1,0]
	v_pk_fma_f32 v[60:61], v[2:3], v[92:93], v[60:61]
	v_pk_add_f32 v[90:91], v[90:91], 1.0 op_sel_hi:[1,0]
	v_rcp_f32_e32 v88, v88
	v_rcp_f32_e32 v89, v89
	v_rcp_f32_e32 v90, v90
	v_rcp_f32_e32 v91, v91
	v_pk_fma_f32 v[62:63], v[4:5], v[96:97], v[62:63]
	v_pk_fma_f32 v[60:61], v[6:7], v[52:53], v[60:61]
	v_pk_fma_f32 v[62:63], v[8:9], v[58:59], v[62:63]
	v_lshlrev_b32_e32 v64, 16, v54
	v_and_b32_e32 v65, 0xffff0000, v54
	v_lshlrev_b32_e32 v54, 16, v55
	v_and_b32_e32 v55, 0xffff0000, v55
	v_pk_mul_f32 v[66:67], v[88:89], v[66:67]
	v_pk_mul_f32 v[56:57], v[90:91], v[56:57]
	v_pk_mul_f32 v[60:61], v[60:61], v[64:65]
	v_pk_mul_f32 v[54:55], v[62:63], v[54:55]
	s_nop 0
	v_pk_mul_f32 v[54:55], v[54:55], v[56:57]
	v_pk_mul_f32 v[56:57], v[60:61], v[66:67]
	v_lshlrev_b32_e32 v60, 16, v44
	v_and_b32_e32 v61, 0xffff0000, v44
	v_lshlrev_b32_e32 v44, 16, v45
	v_and_b32_e32 v45, 0xffff0000, v45
	v_pk_mul_f32 v[62:63], v[60:61], s[24:25] op_sel_hi:[1,0]
	v_pk_mul_f32 v[64:65], v[44:45], s[24:25] op_sel_hi:[1,0]
	v_exp_f32_e32 v62, v62
	v_exp_f32_e32 v63, v63
	v_exp_f32_e32 v64, v64
	v_exp_f32_e32 v65, v65
	v_cvt_pk_bf16_f32 v56, v56, v57
	v_pk_add_f32 v[62:63], v[62:63], 1.0 op_sel_hi:[1,0]
	v_cvt_pk_bf16_f32 v57, v54, v55
	v_pk_add_f32 v[64:65], v[64:65], 1.0 op_sel_hi:[1,0]
	global_store_dwordx2 v[50:51], v[56:57], off offset:1024
	v_lshlrev_b32_e32 v50, 16, v48
	v_and_b32_e32 v51, 0xffff0000, v48
	v_lshlrev_b32_e32 v54, 16, v46
	v_and_b32_e32 v55, 0xffff0000, v46
	v_lshlrev_b32_e32 v48, 16, v49
	v_and_b32_e32 v49, 0xffff0000, v49
	v_lshlrev_b32_e32 v46, 16, v47
	v_and_b32_e32 v47, 0xffff0000, v47
	v_rcp_f32_e32 v62, v62
	v_rcp_f32_e32 v63, v63
	v_rcp_f32_e32 v64, v64
	v_rcp_f32_e32 v65, v65
	v_pk_mul_f32 v[50:51], v[50:51], v[54:55]
	v_pk_mul_f32 v[46:47], v[48:49], v[46:47]
	v_pk_fma_f32 v[48:49], v[12:13], v[96:97], v[16:17]
	v_pk_fma_f32 v[54:55], v[10:11], v[92:93], v[14:15]
	v_pk_fma_f32 v[48:49], v[4:5], v[58:59], v[48:49]
	v_pk_fma_f32 v[54:55], v[2:3], v[52:53], v[54:55]
	v_pk_fma_f32 v[48:49], v[8:9], v[46:47], v[48:49]
	v_pk_fma_f32 v[54:55], v[6:7], v[50:51], v[54:55]
	v_lshlrev_b32_e32 v56, 16, v42
	v_and_b32_e32 v57, 0xffff0000, v42
	v_lshlrev_b32_e32 v42, 16, v43
	v_and_b32_e32 v43, 0xffff0000, v43
	v_pk_mul_f32 v[60:61], v[62:63], v[60:61]
	v_pk_mul_f32 v[44:45], v[64:65], v[44:45]
	v_pk_mul_f32 v[54:55], v[54:55], v[56:57]
	v_pk_mul_f32 v[42:43], v[48:49], v[42:43]
	v_lshlrev_b32_e32 v48, 16, v34
	v_pk_mul_f32 v[42:43], v[42:43], v[44:45]
	v_pk_mul_f32 v[44:45], v[54:55], v[60:61]
	v_and_b32_e32 v49, 0xffff0000, v34
	v_cvt_pk_bf16_f32 v44, v44, v45
	v_cvt_pk_bf16_f32 v45, v42, v43
	global_store_dwordx2 v[40:41], v[44:45], off
	v_lshlrev_b32_e32 v40, 16, v38
	v_and_b32_e32 v41, 0xffff0000, v38
	v_lshlrev_b32_e32 v42, 16, v36
	v_and_b32_e32 v43, 0xffff0000, v36
	v_lshlrev_b32_e32 v34, 16, v35
	v_and_b32_e32 v35, 0xffff0000, v35
	v_pk_mul_f32 v[40:41], v[40:41], v[42:43]
	v_pk_fma_f32 v[42:43], v[10:11], v[52:53], v[14:15]
	v_pk_mul_f32 v[52:53], v[48:49], s[24:25] op_sel_hi:[1,0]
	v_pk_mul_f32 v[54:55], v[34:35], s[24:25] op_sel_hi:[1,0]
	v_exp_f32_e32 v52, v52
	v_exp_f32_e32 v53, v53
	v_exp_f32_e32 v54, v54
	v_exp_f32_e32 v55, v55
	v_lshlrev_b32_e32 v38, 16, v39
	v_pk_add_f32 v[52:53], v[52:53], 1.0 op_sel_hi:[1,0]
	v_and_b32_e32 v39, 0xffff0000, v39
	v_pk_add_f32 v[54:55], v[54:55], 1.0 op_sel_hi:[1,0]
	v_lshlrev_b32_e32 v36, 16, v37
	v_and_b32_e32 v37, 0xffff0000, v37
	v_rcp_f32_e32 v52, v52
	v_rcp_f32_e32 v53, v53
	v_rcp_f32_e32 v54, v54
	v_rcp_f32_e32 v55, v55
	v_pk_mul_f32 v[36:37], v[38:39], v[36:37]
	v_pk_fma_f32 v[38:39], v[12:13], v[58:59], v[16:17]
	v_pk_fma_f32 v[42:43], v[2:3], v[50:51], v[42:43]
	v_pk_fma_f32 v[38:39], v[4:5], v[46:47], v[38:39]
	v_pk_fma_f32 v[42:43], v[6:7], v[40:41], v[42:43]
	v_pk_fma_f32 v[38:39], v[8:9], v[36:37], v[38:39]
	v_lshlrev_b32_e32 v44, 16, v32
	v_and_b32_e32 v45, 0xffff0000, v32
	v_lshlrev_b32_e32 v32, 16, v33
	v_and_b32_e32 v33, 0xffff0000, v33
	v_pk_mul_f32 v[48:49], v[52:53], v[48:49]
	v_pk_mul_f32 v[34:35], v[54:55], v[34:35]
	v_pk_mul_f32 v[42:43], v[42:43], v[44:45]
	v_pk_mul_f32 v[32:33], v[38:39], v[32:33]
	v_pk_fma_f32 v[12:13], v[12:13], v[46:47], v[16:17]
	v_pk_mul_f32 v[32:33], v[32:33], v[34:35]
	v_pk_mul_f32 v[34:35], v[42:43], v[48:49]
	v_pk_fma_f32 v[4:5], v[4:5], v[36:37], v[12:13]
	v_cvt_pk_bf16_f32 v34, v34, v35
	v_cvt_pk_bf16_f32 v35, v32, v33
	global_store_dwordx2 v[30:31], v[34:35], off offset:3072
	v_lshlrev_b32_e32 v30, 16, v28
	v_and_b32_e32 v31, 0xffff0000, v28
	v_lshlrev_b32_e32 v32, 16, v24
	v_and_b32_e32 v33, 0xffff0000, v24
	v_lshlrev_b32_e32 v28, 16, v29
	v_and_b32_e32 v29, 0xffff0000, v29
	v_lshlrev_b32_e32 v24, 16, v25
	v_and_b32_e32 v25, 0xffff0000, v25
	v_pk_mul_f32 v[24:25], v[28:29], v[24:25]
	v_pk_fma_f32 v[10:11], v[10:11], v[50:51], v[14:15]
	v_pk_fma_f32 v[4:5], v[8:9], v[24:25], v[4:5]
	v_lshlrev_b32_e32 v8, 16, v18
	v_and_b32_e32 v9, 0xffff0000, v18
	v_pk_fma_f32 v[2:3], v[2:3], v[40:41], v[10:11]
	v_pk_mul_f32 v[10:11], v[8:9], s[24:25] op_sel_hi:[1,0]
	v_lshlrev_b32_e32 v12, 16, v19
	v_and_b32_e32 v13, 0xffff0000, v19
	v_exp_f32_e32 v10, v10
	v_exp_f32_e32 v11, v11
	v_pk_mul_f32 v[14:15], v[12:13], s[24:25] op_sel_hi:[1,0]
	v_pk_mul_f32 v[30:31], v[30:31], v[32:33]
	v_exp_f32_e32 v14, v14
	v_exp_f32_e32 v15, v15
	v_pk_add_f32 v[10:11], v[10:11], 1.0 op_sel_hi:[1,0]
	v_pk_fma_f32 v[2:3], v[6:7], v[30:31], v[2:3]
	v_rcp_f32_e32 v10, v10
	v_rcp_f32_e32 v11, v11
	v_pk_add_f32 v[14:15], v[14:15], 1.0 op_sel_hi:[1,0]
	v_lshlrev_b32_e32 v6, 16, v22
	v_rcp_f32_e32 v14, v14
	v_rcp_f32_e32 v15, v15
	v_and_b32_e32 v7, 0xffff0000, v22
	v_lshlrev_b32_e32 v16, 16, v23
	v_and_b32_e32 v17, 0xffff0000, v23
	v_pk_mul_f32 v[8:9], v[10:11], v[8:9]
	v_pk_mul_f32 v[2:3], v[2:3], v[6:7]
	v_pk_mul_f32 v[10:11], v[14:15], v[12:13]
	v_pk_mul_f32 v[4:5], v[4:5], v[16:17]
	v_pk_mul_f32 v[2:3], v[2:3], v[8:9]
	v_pk_mul_f32 v[4:5], v[4:5], v[10:11]
	v_cvt_pk_bf16_f32 v2, v2, v3
	s_nop 0
	v_cvt_pk_bf16_f32 v3, v4, v5
	global_store_dwordx2 v[20:21], v[2:3], off offset:2048
.LBB0_480:
	s_and_b64 vcc, exec, s[0:1]
	s_cbranch_vccz .LBB0_467
	s_lshr_b32 s17, s8, 4
	s_bfe_u32 s20, s23, 0x30001
	s_mul_i32 s0, s17, 0x160000
	s_add_u32 s8, s19, s0
	s_addc_u32 s11, s25, 0
	s_lshl_b32 s16, s20, 6
	s_lshl_b32 s0, s20, 7
	s_add_u32 s0, s8, s0
	s_addc_u32 s1, s11, 0
	v_lshl_add_u64 v[88:89], s[0:1], 0, v[74:75]
	v_add_co_u32_e32 v94, vcc, s81, v88
	s_mov_b32 s0, 0x2c000
	s_nop 0
	v_addc_co_u32_e32 v95, vcc, 0, v89, vcc
	v_add_co_u32_e32 v92, vcc, s0, v88
	s_mov_b32 s0, 0x58000
	s_nop 0
	v_addc_co_u32_e32 v93, vcc, 0, v89, vcc
	v_add_co_u32_e32 v14, vcc, 0x42000, v88
	global_load_dwordx4 v[2:5], v[88:89], off offset:3072
	s_nop 0
	v_addc_co_u32_e32 v15, vcc, 0, v89, vcc
	v_add_co_u32_e32 v90, vcc, s0, v88
	global_load_dwordx4 v[6:9], v[94:95], off offset:3072
	global_load_dwordx4 v[10:13], v[92:93], off offset:3072
	v_addc_co_u32_e32 v91, vcc, 0, v89, vcc
	v_add_co_u32_e32 v22, vcc, 0x6e000, v88
	global_load_dwordx4 v[14:17], v[14:15], off offset:3072
	s_nop 0
	v_addc_co_u32_e32 v23, vcc, 0, v89, vcc
	v_add_co_u32_e32 v28, vcc, 0x84000, v88
	global_load_dwordx4 v[18:21], v[90:91], off offset:3072
	s_nop 0
	v_addc_co_u32_e32 v29, vcc, 0, v89, vcc
	v_add_co_u32_e32 v32, vcc, 0x9a000, v88
	global_load_dwordx4 v[22:25], v[22:23], off offset:3072
	s_nop 0
	v_addc_co_u32_e32 v33, vcc, 0, v89, vcc
	global_load_dwordx4 v[28:31], v[28:29], off offset:3072
	v_readlane_b32 s4, v251, 43
	global_load_dwordx4 v[32:35], v[32:33], off offset:3072
	v_readlane_b32 s5, v251, 44
	s_bitcmp1_b32 s23, 7
	s_cselect_b64 s[98:99], -1, 0
	s_xor_b64 s[4:5], s[4:5], s[98:99]
	s_mov_b64 s[0:1], -1
	v_add_u32_e32 v162, 0x880, v135
	v_add_u32_e32 v154, 0xcc0, v135
	s_andn2_b64 vcc, exec, s[4:5]
	v_add_u32_e32 v147, 0x1100, v135
	v_add_u32_e32 v138, 0x1540, v135
	v_add_u32_e32 v107, 0x1980, v135
	v_add_u32_e32 v98, 0x1dc0, v135
	s_waitcnt vmcnt(7)
	v_lshlrev_b32_e32 v197, 16, v2
	v_and_b32_e32 v196, 0xffff0000, v2
	v_lshlrev_b32_e32 v195, 16, v3
	v_and_b32_e32 v194, 0xffff0000, v3
	v_lshlrev_b32_e32 v193, 16, v4
	v_and_b32_e32 v192, 0xffff0000, v4
	v_lshlrev_b32_e32 v191, 16, v5
	v_and_b32_e32 v190, 0xffff0000, v5
	s_waitcnt vmcnt(6)
	v_lshlrev_b32_e32 v189, 16, v6
	v_and_b32_e32 v188, 0xffff0000, v6
	v_lshlrev_b32_e32 v187, 16, v7
	v_and_b32_e32 v186, 0xffff0000, v7
	v_lshlrev_b32_e32 v185, 16, v8
	v_and_b32_e32 v184, 0xffff0000, v8
	v_lshlrev_b32_e32 v183, 16, v9
	v_and_b32_e32 v182, 0xffff0000, v9
	s_waitcnt vmcnt(5)
	v_lshlrev_b32_e32 v181, 16, v10
	v_and_b32_e32 v180, 0xffff0000, v10
	v_lshlrev_b32_e32 v179, 16, v11
	v_and_b32_e32 v178, 0xffff0000, v11
	v_lshlrev_b32_e32 v177, 16, v12
	v_and_b32_e32 v176, 0xffff0000, v12
	v_lshlrev_b32_e32 v167, 16, v13
	v_and_b32_e32 v166, 0xffff0000, v13
	s_waitcnt vmcnt(4)
	v_lshlrev_b32_e32 v165, 16, v14
	v_and_b32_e32 v164, 0xffff0000, v14
	v_lshlrev_b32_e32 v163, 16, v15
	v_and_b32_e32 v161, 0xffff0000, v15
	v_lshlrev_b32_e32 v160, 16, v16
	v_and_b32_e32 v159, 0xffff0000, v16
	v_lshlrev_b32_e32 v158, 16, v17
	v_and_b32_e32 v157, 0xffff0000, v17
	s_waitcnt vmcnt(3)
	v_lshlrev_b32_e32 v156, 16, v18
	v_and_b32_e32 v155, 0xffff0000, v18
	v_lshlrev_b32_e32 v153, 16, v19
	v_and_b32_e32 v152, 0xffff0000, v19
	v_lshlrev_b32_e32 v151, 16, v20
	v_and_b32_e32 v150, 0xffff0000, v20
	v_lshlrev_b32_e32 v149, 16, v21
	v_and_b32_e32 v148, 0xffff0000, v21
	s_waitcnt vmcnt(2)
	v_lshlrev_b32_e32 v146, 16, v22
	v_and_b32_e32 v145, 0xffff0000, v22
	v_lshlrev_b32_e32 v144, 16, v23
	v_and_b32_e32 v143, 0xffff0000, v23
	v_lshlrev_b32_e32 v142, 16, v24
	v_and_b32_e32 v141, 0xffff0000, v24
	v_lshlrev_b32_e32 v140, 16, v25
	v_and_b32_e32 v139, 0xffff0000, v25
	s_waitcnt vmcnt(1)
	v_lshlrev_b32_e32 v137, 16, v28
	v_and_b32_e32 v136, 0xffff0000, v28
	v_lshlrev_b32_e32 v113, 16, v29
	v_and_b32_e32 v112, 0xffff0000, v29
	v_lshlrev_b32_e32 v111, 16, v30
	v_and_b32_e32 v110, 0xffff0000, v30
	v_lshlrev_b32_e32 v109, 16, v31
	v_and_b32_e32 v108, 0xffff0000, v31
	s_waitcnt vmcnt(0)
	v_lshlrev_b32_e32 v106, 16, v32
	v_and_b32_e32 v105, 0xffff0000, v32
	v_lshlrev_b32_e32 v104, 16, v33
	v_and_b32_e32 v103, 0xffff0000, v33
	v_lshlrev_b32_e32 v102, 16, v34
	v_and_b32_e32 v101, 0xffff0000, v34
	v_lshlrev_b32_e32 v100, 16, v35
	v_and_b32_e32 v99, 0xffff0000, v35
	s_cbranch_vccnz .LBB0_485
	v_lshl_add_u64 v[2:3], v[88:89], 0, s[86:87]
	v_add_co_u32_e32 v4, vcc, 0xb0000, v2
	s_lshl_b32 s0, s23, 14
	s_nop 0
	v_addc_co_u32_e32 v5, vcc, 0, v3, vcc
	global_load_dwordx4 v[52:55], v[4:5], off
	v_add_co_u32_e32 v4, vcc, 0xc6000, v2
	s_and_b32 s68, s0, 0x38000
	s_nop 0
	v_addc_co_u32_e32 v5, vcc, 0, v3, vcc
	global_load_dwordx4 v[48:51], v[4:5], off
	v_add_co_u32_e32 v4, vcc, 0xdc000, v2
	v_lshl_add_u64 v[96:97], v[86:87], 0, s[68:69]
	s_nop 0
	v_addc_co_u32_e32 v5, vcc, 0, v3, vcc
	global_load_dwordx4 v[44:47], v[4:5], off
	v_add_co_u32_e32 v4, vcc, 0xf2000, v2
	s_lshl_b32 s68, s17, 13
	s_nop 0
	v_addc_co_u32_e32 v5, vcc, 0, v3, vcc
	global_load_dwordx4 v[36:39], v[4:5], off
	v_add_co_u32_e32 v4, vcc, 0x108000, v2
	s_mov_b64 s[4:5], 0x1000
	s_nop 0
	v_addc_co_u32_e32 v5, vcc, 0, v3, vcc
	global_load_dwordx4 v[16:19], v[4:5], off
	v_add_co_u32_e32 v4, vcc, 0x11e000, v2
	s_mov_b32 s1, 0x3b000000
	s_nop 0
	v_addc_co_u32_e32 v5, vcc, 0, v3, vcc
	global_load_dwordx4 v[12:15], v[4:5], off
	v_add_co_u32_e32 v4, vcc, 0x134000, v2
	s_mov_b32 s0, 0
	s_nop 0
	v_addc_co_u32_e32 v5, vcc, 0, v3, vcc
	v_add_co_u32_e32 v2, vcc, 0x14a000, v2
	global_load_dwordx4 v[8:11], v[4:5], off
	s_nop 0
	v_addc_co_u32_e32 v3, vcc, 0, v3, vcc
	global_load_dwordx4 v[4:7], v[2:3], off
	v_lshl_add_u64 v[2:3], v[76:77], 0, s[68:69]
	global_load_dwordx4 v[56:59], v[2:3], off offset:48
	global_load_dwordx4 v[60:63], v[2:3], off offset:32
	global_load_dwordx4 v[64:67], v[2:3], off offset:16
	global_load_dwordx4 v[198:201], v[2:3], off
	v_lshl_add_u64 v[20:21], v[2:3], 0, s[4:5]
	v_add_co_u32_e32 v2, vcc, s10, v2
	s_lshl_b32 s68, s16, 2
	s_nop 0
	v_addc_co_u32_e32 v3, vcc, 0, v3, vcc
	global_load_dwordx4 v[202:205], v[2:3], off
	global_load_dwordx4 v[206:209], v[20:21], off offset:48
	global_load_dwordx4 v[210:213], v[20:21], off offset:32
	global_load_dwordx4 v[214:217], v[20:21], off offset:16
	v_lshl_add_u64 v[2:3], v[82:83], 0, s[68:69]
	global_load_dwordx4 v[20:23], v[2:3], off offset:16
	global_load_dwordx4 v[32:35], v[2:3], off
	v_lshl_add_u64 v[2:3], v[84:85], 0, s[68:69]
	global_load_dwordx4 v[28:31], v[2:3], off offset:16
	global_load_dwordx4 v[40:43], v[2:3], off
	s_mov_b64 s[98:99], 0x2000
	v_lshl_add_u64 v[246:247], v[96:97], 0, s[98:99]
	s_mov_b64 s[98:99], 0x3000
	v_lshl_add_u64 v[248:249], v[96:97], 0, s[98:99]
	global_load_dwordx4 v[230:233], v[96:97], off
	global_load_dwordx4 v[234:237], v[246:247], off offset:-4096
	global_load_dwordx4 v[238:241], v[246:247], off
	global_load_dwordx4 v[242:245], v[248:249], off
	s_waitcnt vmcnt(15)
	v_mov_b32_e32 v25, v58
	s_waitcnt vmcnt(14)
	v_mov_b32_e32 v24, v62
	s_waitcnt vmcnt(13)
	v_add_f32_e32 v3, v64, v66
	s_waitcnt vmcnt(12)
	v_add_f32_e32 v2, v198, v200
	v_add_f32_e32 v64, v2, v3
	v_mov_b32_e32 v2, v60
	v_mov_b32_e32 v3, v56
	v_pk_add_f32 v[2:3], v[2:3], v[24:25]
	v_add_f32_e32 v24, v65, v67
	v_add_f32_e32 v2, v64, v2
	v_add_f32_e32 v2, v2, v3
	v_add_f32_e32 v3, v199, v201
	v_add_f32_e32 v3, v3, v24
	v_add_f32_e32 v24, v61, v63
	v_add_f32_e32 v3, v3, v24
	v_add_f32_e32 v24, v57, v59
	v_mul_f32_e32 v60, 0x3b000000, v2
	v_add_f32_e32 v3, v3, v24
	v_mul_f32_e32 v2, v60, v60
	v_fma_f32 v3, v3, s1, -v2
	v_max_f32_e32 v3, 0, v3
	v_add_f32_e32 v3, 0x3727c5ac, v3
	v_rsq_f32_e32 v61, v3
	s_waitcnt vmcnt(11)
	v_add_f32_e32 v3, v202, v204
	s_waitcnt vmcnt(8)
	v_add_f32_e32 v24, v214, v216
	v_add_f32_e32 v3, v3, v24
	v_mov_b32_e32 v24, v210
	v_mov_b32_e32 v25, v206
	v_mov_b32_e32 v56, v212
	v_mov_b32_e32 v57, v208
	v_pk_add_f32 v[24:25], v[24:25], v[56:57]
	v_mov_b32_e32 v2, 0
	v_add_f32_e32 v3, v3, v24
	v_add_f32_e32 v3, v3, v25
	v_add_f32_e32 v24, v203, v205
	v_add_f32_e32 v25, v215, v217
	v_add_f32_e32 v24, v24, v25
	v_add_f32_e32 v25, v211, v213
	v_add_f32_e32 v24, v24, v25
	v_add_f32_e32 v25, v207, v209
	v_mul_f32_e32 v3, 0x3b000000, v3
	v_add_f32_e32 v24, v24, v25
	v_mul_f32_e32 v25, v3, v3
	v_fma_f32 v24, v24, s1, -v25
	v_and_b32_e32 v25, 64, v224
	v_or_b32_e32 v56, v25, v114
	v_lshlrev_b32_e32 v62, 2, v56
	ds_bpermute_b32 v59, v62, v60
	ds_bpermute_b32 v63, v62, v61
	v_max_f32_e32 v24, 0, v24
	v_add_f32_e32 v24, 0x3727c5ac, v24
	v_rsq_f32_e32 v24, v24
	s_waitcnt lgkmcnt(1)
	v_sub_f32_e32 v56, v197, v59
	v_sub_f32_e32 v57, v196, v59
	s_waitcnt lgkmcnt(0)
	v_mul_f32_e32 v56, v56, v63
	v_mul_f32_e32 v57, v57, v63
	s_waitcnt vmcnt(4)
	v_fma_f32 v56, v32, v56, v40
	v_fma_f32 v57, v33, v57, v41
	v_cvt_pk_bf16_f32 v56, v56, v57
	v_sub_f32_e32 v57, v195, v59
	v_sub_f32_e32 v58, v194, v59
	v_mul_f32_e32 v57, v57, v63
	v_mul_f32_e32 v58, v58, v63
	v_fma_f32 v57, v34, v57, v42
	v_fma_f32 v58, v35, v58, v43
	v_cvt_pk_bf16_f32 v57, v57, v58
	v_sub_f32_e32 v58, v193, v59
	v_sub_f32_e32 v64, v192, v59
	v_mul_f32_e32 v58, v58, v63
	v_mul_f32_e32 v64, v64, v63
	v_fma_f32 v58, v20, v58, v28
	v_fma_f32 v64, v21, v64, v29
	v_cvt_pk_bf16_f32 v58, v58, v64
	v_sub_f32_e32 v64, v191, v59
	v_sub_f32_e32 v59, v190, v59
	v_mul_f32_e32 v59, v59, v63
	v_mul_f32_e32 v64, v64, v63
	v_fma_f32 v59, v23, v59, v31
	v_fma_f32 v64, v22, v64, v30
	v_cvt_pk_bf16_f32 v59, v64, v59
	ds_write2_b64 v135, v[56:57], v[58:59] offset1:1
	v_or_b32_e32 v56, v25, v115
	v_lshlrev_b32_e32 v56, 2, v56
	ds_bpermute_b32 v59, v56, v60
	ds_bpermute_b32 v63, v56, v61
	v_mov_b32_e32 v65, v2
	v_mov_b32_e32 v66, v2
	v_mov_b32_e32 v67, v2
	s_waitcnt lgkmcnt(1)
	v_sub_f32_e32 v56, v189, v59
	v_sub_f32_e32 v57, v188, v59
	s_waitcnt lgkmcnt(0)
	v_mul_f32_e32 v56, v56, v63
	v_mul_f32_e32 v57, v57, v63
	v_fma_f32 v56, v32, v56, v40
	v_fma_f32 v57, v33, v57, v41
	v_cvt_pk_bf16_f32 v56, v56, v57
	v_sub_f32_e32 v57, v187, v59
	v_sub_f32_e32 v58, v186, v59
	v_mul_f32_e32 v57, v57, v63
	v_mul_f32_e32 v58, v58, v63
	v_fma_f32 v57, v34, v57, v42
	v_fma_f32 v58, v35, v58, v43
	v_cvt_pk_bf16_f32 v57, v57, v58
	v_sub_f32_e32 v58, v185, v59
	v_sub_f32_e32 v64, v184, v59
	v_mul_f32_e32 v58, v58, v63
	v_mul_f32_e32 v64, v64, v63
	v_fma_f32 v58, v20, v58, v28
	v_fma_f32 v64, v21, v64, v29
	v_cvt_pk_bf16_f32 v58, v58, v64
	v_sub_f32_e32 v64, v183, v59
	v_sub_f32_e32 v59, v182, v59
	v_mul_f32_e32 v59, v59, v63
	v_mul_f32_e32 v64, v64, v63
	v_fma_f32 v59, v23, v59, v31
	v_fma_f32 v64, v22, v64, v30
	v_cvt_pk_bf16_f32 v59, v64, v59
	ds_write2_b64 v135, v[56:57], v[58:59] offset0:136 offset1:137
	v_or_b32_e32 v56, v25, v116
	v_lshlrev_b32_e32 v56, 2, v56
	ds_bpermute_b32 v59, v56, v60
	ds_bpermute_b32 v63, v56, v61
	s_waitcnt lgkmcnt(1)
	v_sub_f32_e32 v56, v181, v59
	v_sub_f32_e32 v57, v180, v59
	s_waitcnt lgkmcnt(0)
	v_mul_f32_e32 v56, v56, v63
	v_mul_f32_e32 v57, v57, v63
	v_fma_f32 v56, v32, v56, v40
	v_fma_f32 v57, v33, v57, v41
	v_cvt_pk_bf16_f32 v56, v56, v57
	v_sub_f32_e32 v57, v179, v59
	v_sub_f32_e32 v58, v178, v59
	v_mul_f32_e32 v57, v57, v63
	v_mul_f32_e32 v58, v58, v63
	v_fma_f32 v57, v34, v57, v42
	v_fma_f32 v58, v35, v58, v43
	v_cvt_pk_bf16_f32 v57, v57, v58
	v_sub_f32_e32 v58, v177, v59
	v_sub_f32_e32 v64, v176, v59
	v_mul_f32_e32 v58, v58, v63
	v_mul_f32_e32 v64, v64, v63
	v_fma_f32 v58, v20, v58, v28
	v_fma_f32 v64, v21, v64, v29
	v_cvt_pk_bf16_f32 v58, v58, v64
	v_sub_f32_e32 v64, v167, v59
	v_sub_f32_e32 v59, v166, v59
	v_mul_f32_e32 v59, v59, v63
	v_mul_f32_e32 v64, v64, v63
	v_fma_f32 v59, v23, v59, v31
	v_fma_f32 v64, v22, v64, v30
	v_cvt_pk_bf16_f32 v59, v64, v59
	ds_write2_b64 v162, v[56:57], v[58:59] offset1:1
	v_or_b32_e32 v56, v25, v117
	v_lshlrev_b32_e32 v56, 2, v56
	ds_bpermute_b32 v59, v56, v60
	ds_bpermute_b32 v63, v56, v61
	s_waitcnt lgkmcnt(1)
	v_sub_f32_e32 v56, v165, v59
	v_sub_f32_e32 v57, v164, v59
	s_waitcnt lgkmcnt(0)
	v_mul_f32_e32 v56, v56, v63
	v_mul_f32_e32 v57, v57, v63
	v_fma_f32 v56, v32, v56, v40
	v_fma_f32 v57, v33, v57, v41
	v_cvt_pk_bf16_f32 v56, v56, v57
	v_sub_f32_e32 v57, v163, v59
	v_sub_f32_e32 v58, v161, v59
	v_mul_f32_e32 v57, v57, v63
	v_mul_f32_e32 v58, v58, v63
	v_fma_f32 v57, v34, v57, v42
	v_fma_f32 v58, v35, v58, v43
	v_cvt_pk_bf16_f32 v57, v57, v58
	v_sub_f32_e32 v58, v160, v59
	v_sub_f32_e32 v64, v159, v59
	v_mul_f32_e32 v58, v58, v63
	v_mul_f32_e32 v64, v64, v63
	v_fma_f32 v58, v20, v58, v28
	v_fma_f32 v64, v21, v64, v29
	v_cvt_pk_bf16_f32 v58, v58, v64
	v_sub_f32_e32 v64, v158, v59
	v_sub_f32_e32 v59, v157, v59
	v_mul_f32_e32 v59, v59, v63
	v_mul_f32_e32 v64, v64, v63
	v_fma_f32 v59, v23, v59, v31
	v_fma_f32 v64, v22, v64, v30
	v_cvt_pk_bf16_f32 v59, v64, v59
	ds_write2_b64 v154, v[56:57], v[58:59] offset1:1
	v_or_b32_e32 v56, v25, v118
	v_lshlrev_b32_e32 v56, 2, v56
	ds_bpermute_b32 v59, v56, v60
	ds_bpermute_b32 v63, v56, v61
	s_waitcnt lgkmcnt(1)
	v_sub_f32_e32 v56, v156, v59
	v_sub_f32_e32 v57, v155, v59
	s_waitcnt lgkmcnt(0)
	v_mul_f32_e32 v56, v56, v63
	v_mul_f32_e32 v57, v57, v63
	v_fma_f32 v56, v32, v56, v40
	v_fma_f32 v57, v33, v57, v41
	v_cvt_pk_bf16_f32 v56, v56, v57
	v_sub_f32_e32 v57, v153, v59
	v_sub_f32_e32 v58, v152, v59
	v_mul_f32_e32 v57, v57, v63
	v_mul_f32_e32 v58, v58, v63
	v_fma_f32 v57, v34, v57, v42
	v_fma_f32 v58, v35, v58, v43
	v_cvt_pk_bf16_f32 v57, v57, v58
	v_sub_f32_e32 v58, v151, v59
	v_sub_f32_e32 v64, v150, v59
	v_mul_f32_e32 v58, v58, v63
	v_mul_f32_e32 v64, v64, v63
	v_fma_f32 v58, v20, v58, v28
	v_fma_f32 v64, v21, v64, v29
	v_cvt_pk_bf16_f32 v58, v58, v64
	v_sub_f32_e32 v64, v149, v59
	v_sub_f32_e32 v59, v148, v59
	v_mul_f32_e32 v59, v59, v63
	v_mul_f32_e32 v64, v64, v63
	v_fma_f32 v59, v23, v59, v31
	v_fma_f32 v64, v22, v64, v30
	v_cvt_pk_bf16_f32 v59, v64, v59
	ds_write2_b64 v147, v[56:57], v[58:59] offset1:1
	v_or_b32_e32 v56, v25, v119
	v_lshlrev_b32_e32 v56, 2, v56
	ds_bpermute_b32 v59, v56, v60
	ds_bpermute_b32 v63, v56, v61
	s_waitcnt lgkmcnt(1)
	v_sub_f32_e32 v56, v146, v59
	v_sub_f32_e32 v57, v145, v59
	s_waitcnt lgkmcnt(0)
	v_mul_f32_e32 v56, v56, v63
	v_mul_f32_e32 v57, v57, v63
	v_fma_f32 v56, v32, v56, v40
	v_fma_f32 v57, v33, v57, v41
	v_cvt_pk_bf16_f32 v56, v56, v57
	v_sub_f32_e32 v57, v144, v59
	v_sub_f32_e32 v58, v143, v59
	v_mul_f32_e32 v57, v57, v63
	v_mul_f32_e32 v58, v58, v63
	v_fma_f32 v57, v34, v57, v42
	v_fma_f32 v58, v35, v58, v43
	v_cvt_pk_bf16_f32 v57, v57, v58
	v_sub_f32_e32 v58, v142, v59
	v_sub_f32_e32 v64, v141, v59
	v_mul_f32_e32 v58, v58, v63
	v_mul_f32_e32 v64, v64, v63
	v_fma_f32 v58, v20, v58, v28
	v_fma_f32 v64, v21, v64, v29
	v_cvt_pk_bf16_f32 v58, v58, v64
	v_sub_f32_e32 v64, v140, v59
	v_sub_f32_e32 v59, v139, v59
	v_mul_f32_e32 v59, v59, v63
	v_mul_f32_e32 v64, v64, v63
	v_fma_f32 v59, v23, v59, v31
	v_fma_f32 v64, v22, v64, v30
	v_cvt_pk_bf16_f32 v59, v64, v59
	ds_write2_b64 v138, v[56:57], v[58:59] offset1:1
	v_or_b32_e32 v56, v25, v120
	v_lshlrev_b32_e32 v56, 2, v56
	ds_bpermute_b32 v59, v56, v60
	ds_bpermute_b32 v63, v56, v61
	s_waitcnt lgkmcnt(1)
	v_sub_f32_e32 v56, v137, v59
	v_sub_f32_e32 v57, v136, v59
	s_waitcnt lgkmcnt(0)
	v_mul_f32_e32 v56, v56, v63
	v_mul_f32_e32 v57, v57, v63
	v_fma_f32 v56, v32, v56, v40
	v_fma_f32 v57, v33, v57, v41
	v_cvt_pk_bf16_f32 v56, v56, v57
	v_sub_f32_e32 v57, v113, v59
	v_sub_f32_e32 v58, v112, v59
	v_mul_f32_e32 v57, v57, v63
	v_mul_f32_e32 v58, v58, v63
	v_fma_f32 v57, v34, v57, v42
	v_fma_f32 v58, v35, v58, v43
	v_cvt_pk_bf16_f32 v57, v57, v58
	v_sub_f32_e32 v58, v111, v59
	v_sub_f32_e32 v64, v110, v59
	v_mul_f32_e32 v58, v58, v63
	v_mul_f32_e32 v64, v64, v63
	v_fma_f32 v58, v20, v58, v28
	v_fma_f32 v64, v21, v64, v29
	v_cvt_pk_bf16_f32 v58, v58, v64
	v_sub_f32_e32 v64, v109, v59
	v_sub_f32_e32 v59, v108, v59
	v_mul_f32_e32 v59, v59, v63
	v_mul_f32_e32 v64, v64, v63
	v_fma_f32 v59, v23, v59, v31
	v_fma_f32 v64, v22, v64, v30
	v_cvt_pk_bf16_f32 v59, v64, v59
	ds_write2_b64 v107, v[56:57], v[58:59] offset1:1
	v_or_b32_e32 v56, v25, v121
	v_lshlrev_b32_e32 v56, 2, v56
	ds_bpermute_b32 v59, v56, v60
	ds_bpermute_b32 v60, v56, v61
	v_mov_b32_e32 v63, v2
	v_mov_b32_e32 v64, v2
	s_waitcnt lgkmcnt(1)
	v_sub_f32_e32 v56, v106, v59
	v_sub_f32_e32 v57, v105, v59
	s_waitcnt lgkmcnt(0)
	v_mul_f32_e32 v56, v56, v60
	v_mul_f32_e32 v57, v57, v60
	v_fma_f32 v56, v32, v56, v40
	v_fma_f32 v57, v33, v57, v41
	v_cvt_pk_bf16_f32 v56, v56, v57
	v_sub_f32_e32 v57, v104, v59
	v_sub_f32_e32 v58, v103, v59
	v_mul_f32_e32 v57, v57, v60
	v_mul_f32_e32 v58, v58, v60
	v_fma_f32 v57, v34, v57, v42
	v_fma_f32 v58, v35, v58, v43
	v_cvt_pk_bf16_f32 v57, v57, v58
	v_sub_f32_e32 v58, v102, v59
	v_sub_f32_e32 v61, v101, v59
	v_mul_f32_e32 v58, v58, v60
	v_mul_f32_e32 v61, v61, v60
	v_fma_f32 v58, v20, v58, v28
	v_fma_f32 v61, v21, v61, v29
	v_cvt_pk_bf16_f32 v58, v58, v61
	v_sub_f32_e32 v61, v100, v59
	v_sub_f32_e32 v59, v99, v59
	v_mul_f32_e32 v59, v59, v60
	v_mul_f32_e32 v61, v61, v60
	v_fma_f32 v59, v23, v59, v31
	v_fma_f32 v61, v22, v61, v30
	v_cvt_pk_bf16_f32 v59, v61, v59
	ds_write2_b64 v98, v[56:57], v[58:59] offset1:1
	ds_bpermute_b32 v56, v62, v3
	ds_bpermute_b32 v57, v62, v24
	v_lshlrev_b32_e32 v58, 16, v52
	v_and_b32_e32 v52, 0xffff0000, v52
	v_mov_b32_e32 v59, v2
	s_waitcnt lgkmcnt(1)
	v_sub_f32_e32 v58, v58, v56
	v_sub_f32_e32 v52, v52, v56
	s_waitcnt lgkmcnt(0)
	v_mul_f32_e32 v58, v58, v57
	v_mul_f32_e32 v52, v52, v57
	v_fma_f32 v58, v32, v58, v40
	v_fma_f32 v52, v33, v52, v41
	v_cvt_pk_bf16_f32 v52, v58, v52
	v_lshlrev_b32_e32 v58, 16, v53
	v_and_b32_e32 v53, 0xffff0000, v53
	v_sub_f32_e32 v58, v58, v56
	v_sub_f32_e32 v53, v53, v56
	v_mul_f32_e32 v58, v58, v57
	v_mul_f32_e32 v53, v53, v57
	v_fma_f32 v58, v34, v58, v42
	v_fma_f32 v53, v35, v53, v43
	v_cvt_pk_bf16_f32 v53, v58, v53
	v_lshlrev_b32_e32 v58, 16, v54
	v_and_b32_e32 v54, 0xffff0000, v54
	v_sub_f32_e32 v58, v58, v56
	v_sub_f32_e32 v54, v54, v56
	v_mul_f32_e32 v58, v58, v57
	v_mul_f32_e32 v54, v54, v57
	v_fma_f32 v58, v20, v58, v28
	v_fma_f32 v54, v21, v54, v29
	v_cvt_pk_bf16_f32 v54, v58, v54
	v_lshlrev_b32_e32 v58, 16, v55
	v_and_b32_e32 v55, 0xffff0000, v55
	v_sub_f32_e32 v55, v55, v56
	v_sub_f32_e32 v58, v58, v56
	v_mul_f32_e32 v55, v55, v57
	v_mul_f32_e32 v58, v58, v57
	v_fma_f32 v55, v23, v55, v31
	v_add_u32_e32 v56, 0x2200, v135
	v_fma_f32 v58, v22, v58, v30
	v_cvt_pk_bf16_f32 v55, v58, v55
	ds_write2_b64 v56, v[52:53], v[54:55] offset1:1
	v_or_b32_e32 v52, v25, v122
	v_lshlrev_b32_e32 v52, 2, v52
	ds_bpermute_b32 v53, v52, v3
	ds_bpermute_b32 v52, v52, v24
	v_lshlrev_b32_e32 v54, 16, v48
	v_and_b32_e32 v48, 0xffff0000, v48
	v_mov_b32_e32 v55, v2
	s_waitcnt lgkmcnt(1)
	v_sub_f32_e32 v54, v54, v53
	v_sub_f32_e32 v48, v48, v53
	s_waitcnt lgkmcnt(0)
	v_mul_f32_e32 v54, v54, v52
	v_mul_f32_e32 v48, v48, v52
	v_fma_f32 v54, v32, v54, v40
	v_fma_f32 v48, v33, v48, v41
	v_cvt_pk_bf16_f32 v48, v54, v48
	v_lshlrev_b32_e32 v54, 16, v49
	v_and_b32_e32 v49, 0xffff0000, v49
	v_sub_f32_e32 v54, v54, v53
	v_sub_f32_e32 v49, v49, v53
	v_mul_f32_e32 v54, v54, v52
	v_mul_f32_e32 v49, v49, v52
	v_fma_f32 v54, v34, v54, v42
	v_fma_f32 v49, v35, v49, v43
	v_cvt_pk_bf16_f32 v49, v54, v49
	v_lshlrev_b32_e32 v54, 16, v50
	v_and_b32_e32 v50, 0xffff0000, v50
	v_sub_f32_e32 v54, v54, v53
	v_sub_f32_e32 v50, v50, v53
	v_mul_f32_e32 v54, v54, v52
	v_mul_f32_e32 v50, v50, v52
	v_fma_f32 v54, v20, v54, v28
	v_fma_f32 v50, v21, v50, v29
	v_cvt_pk_bf16_f32 v50, v54, v50
	v_lshlrev_b32_e32 v54, 16, v51
	v_and_b32_e32 v51, 0xffff0000, v51
	v_sub_f32_e32 v51, v51, v53
	v_sub_f32_e32 v54, v54, v53
	v_mul_f32_e32 v51, v51, v52
	v_mul_f32_e32 v54, v54, v52
	v_fma_f32 v51, v23, v51, v31
	v_add_u32_e32 v52, 0x2640, v135
	v_fma_f32 v54, v22, v54, v30
	v_cvt_pk_bf16_f32 v51, v54, v51
	ds_write2_b64 v52, v[48:49], v[50:51] offset1:1
	v_or_b32_e32 v48, v25, v123
	v_lshlrev_b32_e32 v48, 2, v48
	ds_bpermute_b32 v49, v48, v3
	ds_bpermute_b32 v48, v48, v24
	v_lshlrev_b32_e32 v50, 16, v44
	v_and_b32_e32 v44, 0xffff0000, v44
	v_mov_b32_e32 v51, v2
	s_waitcnt lgkmcnt(1)
	v_sub_f32_e32 v50, v50, v49
	v_sub_f32_e32 v44, v44, v49
	s_waitcnt lgkmcnt(0)
	v_mul_f32_e32 v50, v50, v48
	v_mul_f32_e32 v44, v44, v48
	v_fma_f32 v50, v32, v50, v40
	v_fma_f32 v44, v33, v44, v41
	v_cvt_pk_bf16_f32 v44, v50, v44
	v_lshlrev_b32_e32 v50, 16, v45
	v_and_b32_e32 v45, 0xffff0000, v45
	v_sub_f32_e32 v50, v50, v49
	v_sub_f32_e32 v45, v45, v49
	v_mul_f32_e32 v50, v50, v48
	v_mul_f32_e32 v45, v45, v48
	v_fma_f32 v50, v34, v50, v42
	v_fma_f32 v45, v35, v45, v43
	v_cvt_pk_bf16_f32 v45, v50, v45
	v_lshlrev_b32_e32 v50, 16, v46
	v_and_b32_e32 v46, 0xffff0000, v46
	v_sub_f32_e32 v50, v50, v49
	v_sub_f32_e32 v46, v46, v49
	v_mul_f32_e32 v50, v50, v48
	v_mul_f32_e32 v46, v46, v48
	v_fma_f32 v50, v20, v50, v28
	v_fma_f32 v46, v21, v46, v29
	v_cvt_pk_bf16_f32 v46, v50, v46
	v_lshlrev_b32_e32 v50, 16, v47
	v_and_b32_e32 v47, 0xffff0000, v47
	v_sub_f32_e32 v47, v47, v49
	v_sub_f32_e32 v50, v50, v49
	v_mul_f32_e32 v47, v47, v48
	v_mul_f32_e32 v50, v50, v48
	v_fma_f32 v47, v23, v47, v31
	v_add_u32_e32 v48, 0x2a80, v135
	v_fma_f32 v50, v22, v50, v30
	v_cvt_pk_bf16_f32 v47, v50, v47
	ds_write2_b64 v48, v[44:45], v[46:47] offset1:1
	v_or_b32_e32 v44, v25, v124
	v_lshlrev_b32_e32 v44, 2, v44
	ds_bpermute_b32 v45, v44, v3
	ds_bpermute_b32 v44, v44, v24
	v_lshlrev_b32_e32 v46, 16, v36
	v_and_b32_e32 v36, 0xffff0000, v36
	v_mov_b32_e32 v47, v2
	s_waitcnt lgkmcnt(1)
	v_sub_f32_e32 v46, v46, v45
	v_sub_f32_e32 v36, v36, v45
	s_waitcnt lgkmcnt(0)
	v_mul_f32_e32 v46, v46, v44
	v_mul_f32_e32 v36, v36, v44
	v_fma_f32 v46, v32, v46, v40
	v_fma_f32 v36, v33, v36, v41
	v_cvt_pk_bf16_f32 v36, v46, v36
	v_lshlrev_b32_e32 v46, 16, v37
	v_and_b32_e32 v37, 0xffff0000, v37
	v_sub_f32_e32 v46, v46, v45
	v_sub_f32_e32 v37, v37, v45
	v_mul_f32_e32 v46, v46, v44
	v_mul_f32_e32 v37, v37, v44
	v_fma_f32 v46, v34, v46, v42
	v_fma_f32 v37, v35, v37, v43
	v_cvt_pk_bf16_f32 v37, v46, v37
	v_lshlrev_b32_e32 v46, 16, v38
	v_and_b32_e32 v38, 0xffff0000, v38
	v_sub_f32_e32 v46, v46, v45
	v_sub_f32_e32 v38, v38, v45
	v_mul_f32_e32 v46, v46, v44
	v_mul_f32_e32 v38, v38, v44
	v_fma_f32 v46, v20, v46, v28
	v_fma_f32 v38, v21, v38, v29
	v_cvt_pk_bf16_f32 v38, v46, v38
	v_lshlrev_b32_e32 v46, 16, v39
	v_and_b32_e32 v39, 0xffff0000, v39
	v_sub_f32_e32 v39, v39, v45
	v_sub_f32_e32 v46, v46, v45
	v_mul_f32_e32 v39, v39, v44
	v_mul_f32_e32 v46, v46, v44
	v_fma_f32 v39, v23, v39, v31
	v_add_u32_e32 v44, 0x2ec0, v135
	v_fma_f32 v46, v22, v46, v30
	v_cvt_pk_bf16_f32 v39, v46, v39
	ds_write2_b64 v44, v[36:37], v[38:39] offset1:1
	v_or_b32_e32 v36, v25, v125
	v_lshlrev_b32_e32 v36, 2, v36
	ds_bpermute_b32 v37, v36, v3
	ds_bpermute_b32 v36, v36, v24
	v_lshlrev_b32_e32 v38, 16, v16
	v_and_b32_e32 v16, 0xffff0000, v16
	v_mov_b32_e32 v39, v2
	s_waitcnt lgkmcnt(1)
	v_sub_f32_e32 v38, v38, v37
	v_sub_f32_e32 v16, v16, v37
	s_waitcnt lgkmcnt(0)
	v_mul_f32_e32 v38, v38, v36
	v_mul_f32_e32 v16, v16, v36
	v_fma_f32 v38, v32, v38, v40
	v_fma_f32 v16, v33, v16, v41
	v_cvt_pk_bf16_f32 v16, v38, v16
	v_lshlrev_b32_e32 v38, 16, v17
	v_and_b32_e32 v17, 0xffff0000, v17
	v_sub_f32_e32 v38, v38, v37
	v_sub_f32_e32 v17, v17, v37
	v_mul_f32_e32 v38, v38, v36
	v_mul_f32_e32 v17, v17, v36
	v_fma_f32 v38, v34, v38, v42
	v_fma_f32 v17, v35, v17, v43
	v_cvt_pk_bf16_f32 v17, v38, v17
	v_lshlrev_b32_e32 v38, 16, v18
	v_and_b32_e32 v18, 0xffff0000, v18
	v_sub_f32_e32 v38, v38, v37
	v_sub_f32_e32 v18, v18, v37
	v_mul_f32_e32 v38, v38, v36
	v_mul_f32_e32 v18, v18, v36
	v_fma_f32 v38, v20, v38, v28
	v_fma_f32 v18, v21, v18, v29
	v_cvt_pk_bf16_f32 v18, v38, v18
	v_lshlrev_b32_e32 v38, 16, v19
	v_and_b32_e32 v19, 0xffff0000, v19
	v_sub_f32_e32 v19, v19, v37
	v_sub_f32_e32 v38, v38, v37
	v_mul_f32_e32 v19, v19, v36
	v_mul_f32_e32 v38, v38, v36
	v_fma_f32 v19, v23, v19, v31
	v_add_u32_e32 v36, 0x3300, v135
	v_fma_f32 v38, v22, v38, v30
	v_cvt_pk_bf16_f32 v19, v38, v19
	ds_write2_b64 v36, v[16:17], v[18:19] offset1:1
	v_or_b32_e32 v16, v25, v126
	v_lshlrev_b32_e32 v16, 2, v16
	ds_bpermute_b32 v17, v16, v3
	ds_bpermute_b32 v16, v16, v24
	v_lshlrev_b32_e32 v18, 16, v12
	v_and_b32_e32 v12, 0xffff0000, v12
	v_mov_b32_e32 v19, v2
	s_waitcnt lgkmcnt(1)
	v_sub_f32_e32 v18, v18, v17
	v_sub_f32_e32 v12, v12, v17
	s_waitcnt lgkmcnt(0)
	v_mul_f32_e32 v18, v18, v16
	v_mul_f32_e32 v12, v12, v16
	v_fma_f32 v18, v32, v18, v40
	v_fma_f32 v12, v33, v12, v41
	v_cvt_pk_bf16_f32 v12, v18, v12
	v_lshlrev_b32_e32 v18, 16, v13
	v_and_b32_e32 v13, 0xffff0000, v13
	v_sub_f32_e32 v18, v18, v17
	v_sub_f32_e32 v13, v13, v17
	v_mul_f32_e32 v18, v18, v16
	v_mul_f32_e32 v13, v13, v16
	v_fma_f32 v18, v34, v18, v42
	v_fma_f32 v13, v35, v13, v43
	v_cvt_pk_bf16_f32 v13, v18, v13
	v_lshlrev_b32_e32 v18, 16, v14
	v_and_b32_e32 v14, 0xffff0000, v14
	v_sub_f32_e32 v18, v18, v17
	v_sub_f32_e32 v14, v14, v17
	v_mul_f32_e32 v18, v18, v16
	v_mul_f32_e32 v14, v14, v16
	v_fma_f32 v18, v20, v18, v28
	v_fma_f32 v14, v21, v14, v29
	v_cvt_pk_bf16_f32 v14, v18, v14
	v_lshlrev_b32_e32 v18, 16, v15
	v_and_b32_e32 v15, 0xffff0000, v15
	v_sub_f32_e32 v15, v15, v17
	v_sub_f32_e32 v18, v18, v17
	v_mul_f32_e32 v15, v15, v16
	v_mul_f32_e32 v18, v18, v16
	v_fma_f32 v15, v23, v15, v31
	v_add_u32_e32 v16, 0x3740, v135
	v_fma_f32 v18, v22, v18, v30
	v_cvt_pk_bf16_f32 v15, v18, v15
	ds_write2_b64 v16, v[12:13], v[14:15] offset1:1
	v_or_b32_e32 v12, v25, v127
	v_lshlrev_b32_e32 v12, 2, v12
	ds_bpermute_b32 v13, v12, v3
	ds_bpermute_b32 v12, v12, v24
	v_lshlrev_b32_e32 v14, 16, v8
	v_and_b32_e32 v8, 0xffff0000, v8
	v_mov_b32_e32 v18, v2
	s_waitcnt lgkmcnt(1)
	v_sub_f32_e32 v14, v14, v13
	v_sub_f32_e32 v8, v8, v13
	s_waitcnt lgkmcnt(0)
	v_mul_f32_e32 v14, v14, v12
	v_mul_f32_e32 v8, v8, v12
	v_fma_f32 v14, v32, v14, v40
	v_fma_f32 v8, v33, v8, v41
	v_cvt_pk_bf16_f32 v8, v14, v8
	v_lshlrev_b32_e32 v14, 16, v9
	v_and_b32_e32 v9, 0xffff0000, v9
	v_sub_f32_e32 v14, v14, v13
	v_sub_f32_e32 v9, v9, v13
	v_mul_f32_e32 v14, v14, v12
	v_mul_f32_e32 v9, v9, v12
	v_fma_f32 v14, v34, v14, v42
	v_fma_f32 v9, v35, v9, v43
	v_cvt_pk_bf16_f32 v9, v14, v9
	v_lshlrev_b32_e32 v14, 16, v10
	v_and_b32_e32 v10, 0xffff0000, v10
	v_sub_f32_e32 v14, v14, v13
	v_sub_f32_e32 v10, v10, v13
	v_mul_f32_e32 v14, v14, v12
	v_mul_f32_e32 v10, v10, v12
	v_fma_f32 v14, v20, v14, v28
	v_fma_f32 v10, v21, v10, v29
	v_cvt_pk_bf16_f32 v10, v14, v10
	v_lshlrev_b32_e32 v14, 16, v11
	v_and_b32_e32 v11, 0xffff0000, v11
	v_sub_f32_e32 v11, v11, v13
	v_sub_f32_e32 v14, v14, v13
	v_mul_f32_e32 v11, v11, v12
	v_mul_f32_e32 v14, v14, v12
	v_fma_f32 v11, v23, v11, v31
	v_add_u32_e32 v12, 0x3b80, v135
	v_fma_f32 v14, v22, v14, v30
	v_cvt_pk_bf16_f32 v11, v14, v11
	ds_write2_b64 v12, v[8:9], v[10:11] offset1:1
	v_or_b32_e32 v8, v25, v128
	v_lshlrev_b32_e32 v8, 2, v8
	ds_bpermute_b32 v3, v8, v3
	ds_bpermute_b32 v8, v8, v24
	v_lshlrev_b32_e32 v9, 16, v4
	v_and_b32_e32 v4, 0xffff0000, v4
	v_mov_b32_e32 v10, v2
	s_waitcnt lgkmcnt(1)
	v_sub_f32_e32 v9, v9, v3
	v_sub_f32_e32 v4, v4, v3
	s_waitcnt lgkmcnt(0)
	v_mul_f32_e32 v9, v9, v8
	v_mul_f32_e32 v4, v4, v8
	v_fma_f32 v9, v32, v9, v40
	v_fma_f32 v4, v33, v4, v41
	v_cvt_pk_bf16_f32 v4, v9, v4
	v_lshlrev_b32_e32 v9, 16, v5
	v_sub_f32_e32 v9, v9, v3
	v_and_b32_e32 v5, 0xffff0000, v5
	v_mul_f32_e32 v9, v9, v8
	v_sub_f32_e32 v5, v5, v3
	v_fma_f32 v9, v34, v9, v42
	v_mul_f32_e32 v5, v5, v8
	v_fmac_f32_e32 v43, v35, v5
	v_cvt_pk_bf16_f32 v5, v9, v43
	v_lshlrev_b32_e32 v9, 16, v6
	v_and_b32_e32 v6, 0xffff0000, v6
	v_sub_f32_e32 v9, v9, v3
	v_sub_f32_e32 v6, v6, v3
	v_mul_f32_e32 v9, v9, v8
	v_mul_f32_e32 v6, v6, v8
	v_fma_f32 v9, v20, v9, v28
	v_fma_f32 v6, v21, v6, v29
	v_cvt_pk_bf16_f32 v6, v9, v6
	v_lshlrev_b32_e32 v9, 16, v7
	v_and_b32_e32 v7, 0xffff0000, v7
	v_sub_f32_e32 v9, v9, v3
	v_sub_f32_e32 v3, v7, v3
	v_mul_f32_e32 v3, v3, v8
	v_mul_f32_e32 v9, v9, v8
	v_fmac_f32_e32 v31, v23, v3
	v_add_u32_e32 v3, 0x3fc0, v135
	v_fma_f32 v9, v22, v9, v30
	v_cvt_pk_bf16_f32 v7, v9, v31
	ds_write2_b64 v3, v[4:5], v[6:7] offset1:1
	s_waitcnt lgkmcnt(0)
	v_mov_b32_e32 v3, v2
	v_mov_b32_e32 v4, v2
	v_mov_b32_e32 v5, v2
	v_mov_b32_e32 v6, v2
	v_mov_b32_e32 v7, v2
	v_mov_b32_e32 v8, v2
	v_mov_b32_e32 v9, v2
	v_mov_b32_e32 v11, v2
	v_mov_b32_e32 v12, v2
	v_mov_b32_e32 v13, v2
	v_mov_b32_e32 v20, v2
	v_mov_b32_e32 v21, v2
	v_mov_b32_e32 v14, v2
	v_mov_b32_e32 v15, v2
	v_mov_b32_e32 v16, v2
	v_mov_b32_e32 v17, v2
	v_mov_b32_e32 v22, v2
	v_mov_b32_e32 v23, v2
	v_mov_b32_e32 v24, v2
	v_mov_b32_e32 v25, v2
	v_mov_b32_e32 v28, v2
	v_mov_b32_e32 v29, v2
	v_mov_b32_e32 v30, v2
	v_mov_b32_e32 v31, v2
	v_mov_b32_e32 v36, v2
	v_mov_b32_e32 v37, v2
	v_mov_b32_e32 v38, v2
	v_mov_b32_e32 v32, v2
	v_mov_b32_e32 v33, v2
	v_mov_b32_e32 v34, v2
	v_mov_b32_e32 v35, v2
	v_mov_b32_e32 v40, v2
	v_mov_b32_e32 v41, v2
	v_mov_b32_e32 v42, v2
	v_mov_b32_e32 v43, v2
	v_mov_b32_e32 v44, v2
	v_mov_b32_e32 v45, v2
	v_mov_b32_e32 v46, v2
	v_mov_b32_e32 v48, v2
	v_mov_b32_e32 v49, v2
	v_mov_b32_e32 v50, v2
	v_mov_b32_e32 v52, v2
	v_mov_b32_e32 v53, v2
	v_mov_b32_e32 v54, v2
	v_mov_b32_e32 v56, v2
	v_mov_b32_e32 v57, v2
	v_mov_b32_e32 v58, v2
	v_mov_b32_e32 v60, v2
	v_mov_b32_e32 v61, v2
	v_mov_b32_e32 v62, v2
.LBB0_483:
	ds_read_b64_tr_b16 v[202:203], v134
	ds_read_b64_tr_b16 v[204:205], v134 offset:544
	ds_read_b64_tr_b16 v[208:209], v134 offset:576
	ds_read_b64_tr_b16 v[206:207], v134 offset:32
	ds_read_b64_tr_b16 v[210:211], v134 offset:64
	ds_read_b64_tr_b16 v[214:215], v134 offset:96
	ds_read_b64_tr_b16 v[212:213], v134 offset:608
	ds_read_b64_tr_b16 v[216:217], v134 offset:640
	s_waitcnt vmcnt(3) lgkmcnt(6)
	v_mfma_f32_16x16x32_bf16 v[48:51], v[202:205], v[230:233], v[48:51]
	s_waitcnt lgkmcnt(4)
	v_mfma_f32_16x16x32_bf16 v[36:39], v[206:209], v[230:233], v[36:39]
	s_waitcnt lgkmcnt(1)
	v_mfma_f32_16x16x32_bf16 v[18:21], v[210:213], v[230:233], v[18:21]
	s_waitcnt lgkmcnt(0)
	v_mfma_f32_16x16x32_bf16 v[52:55], v[214:217], v[230:233], v[52:55]
	global_load_dwordx4 v[230:233], v[96:97], off offset:64
	s_waitcnt vmcnt(3)
	v_mfma_f32_16x16x32_bf16 v[44:47], v[202:205], v[234:237], v[44:47]
	v_mfma_f32_16x16x32_bf16 v[28:31], v[206:209], v[234:237], v[28:31]
	v_mfma_f32_16x16x32_bf16 v[10:13], v[210:213], v[234:237], v[10:13]
	v_mfma_f32_16x16x32_bf16 v[56:59], v[214:217], v[234:237], v[56:59]
	global_load_dwordx4 v[234:237], v[246:247], off offset:-4032
	s_waitcnt vmcnt(3)
	v_mfma_f32_16x16x32_bf16 v[40:43], v[202:205], v[238:241], v[40:43]
	v_mfma_f32_16x16x32_bf16 v[22:25], v[206:209], v[238:241], v[22:25]
	v_mfma_f32_16x16x32_bf16 v[6:9], v[210:213], v[238:241], v[6:9]
	v_mfma_f32_16x16x32_bf16 v[60:63], v[214:217], v[238:241], v[60:63]
	global_load_dwordx4 v[238:241], v[246:247], off offset:64
	s_waitcnt vmcnt(3)
	v_mfma_f32_16x16x32_bf16 v[32:35], v[202:205], v[242:245], v[32:35]
	v_mfma_f32_16x16x32_bf16 v[14:17], v[206:209], v[242:245], v[14:17]
	v_mfma_f32_16x16x32_bf16 v[2:5], v[210:213], v[242:245], v[2:5]
	v_mfma_f32_16x16x32_bf16 v[64:67], v[214:217], v[242:245], v[64:67]
	global_load_dwordx4 v[242:245], v[248:249], off offset:64
	ds_read_b64_tr_b16 v[202:203], v134 offset:4352
	ds_read_b64_tr_b16 v[204:205], v134 offset:4896
	ds_read_b64_tr_b16 v[208:209], v134 offset:4928
	ds_read_b64_tr_b16 v[206:207], v134 offset:4384
	ds_read_b64_tr_b16 v[210:211], v134 offset:4416
	ds_read_b64_tr_b16 v[214:215], v134 offset:4448
	ds_read_b64_tr_b16 v[212:213], v134 offset:4960
	ds_read_b64_tr_b16 v[216:217], v134 offset:4992
	s_waitcnt vmcnt(3) lgkmcnt(6)
	v_mfma_f32_16x16x32_bf16 v[48:51], v[202:205], v[230:233], v[48:51]
	s_waitcnt lgkmcnt(4)
	v_mfma_f32_16x16x32_bf16 v[36:39], v[206:209], v[230:233], v[36:39]
	s_waitcnt lgkmcnt(1)
	v_mfma_f32_16x16x32_bf16 v[18:21], v[210:213], v[230:233], v[18:21]
	s_waitcnt lgkmcnt(0)
	v_mfma_f32_16x16x32_bf16 v[52:55], v[214:217], v[230:233], v[52:55]
	global_load_dwordx4 v[230:233], v[96:97], off offset:128
	s_waitcnt vmcnt(3)
	v_mfma_f32_16x16x32_bf16 v[44:47], v[202:205], v[234:237], v[44:47]
	v_mfma_f32_16x16x32_bf16 v[28:31], v[206:209], v[234:237], v[28:31]
	v_mfma_f32_16x16x32_bf16 v[10:13], v[210:213], v[234:237], v[10:13]
	v_mfma_f32_16x16x32_bf16 v[56:59], v[214:217], v[234:237], v[56:59]
	global_load_dwordx4 v[234:237], v[246:247], off offset:-3968
	s_waitcnt vmcnt(3)
	v_mfma_f32_16x16x32_bf16 v[40:43], v[202:205], v[238:241], v[40:43]
	v_mfma_f32_16x16x32_bf16 v[22:25], v[206:209], v[238:241], v[22:25]
	v_mfma_f32_16x16x32_bf16 v[6:9], v[210:213], v[238:241], v[6:9]
	v_mfma_f32_16x16x32_bf16 v[60:63], v[214:217], v[238:241], v[60:63]
	global_load_dwordx4 v[238:241], v[246:247], off offset:128
	s_waitcnt vmcnt(3)
	v_mfma_f32_16x16x32_bf16 v[32:35], v[202:205], v[242:245], v[32:35]
	v_mfma_f32_16x16x32_bf16 v[14:17], v[206:209], v[242:245], v[14:17]
	v_mfma_f32_16x16x32_bf16 v[2:5], v[210:213], v[242:245], v[2:5]
	v_mfma_f32_16x16x32_bf16 v[64:67], v[214:217], v[242:245], v[64:67]
	global_load_dwordx4 v[242:245], v[248:249], off offset:128
	ds_read_b64_tr_b16 v[202:203], v134 offset:8704
	ds_read_b64_tr_b16 v[204:205], v134 offset:9248
	ds_read_b64_tr_b16 v[208:209], v134 offset:9280
	ds_read_b64_tr_b16 v[206:207], v134 offset:8736
	ds_read_b64_tr_b16 v[210:211], v134 offset:8768
	ds_read_b64_tr_b16 v[214:215], v134 offset:8800
	ds_read_b64_tr_b16 v[212:213], v134 offset:9312
	ds_read_b64_tr_b16 v[216:217], v134 offset:9344
	s_waitcnt vmcnt(3) lgkmcnt(6)
	v_mfma_f32_16x16x32_bf16 v[48:51], v[202:205], v[230:233], v[48:51]
	s_waitcnt lgkmcnt(4)
	v_mfma_f32_16x16x32_bf16 v[36:39], v[206:209], v[230:233], v[36:39]
	s_waitcnt lgkmcnt(1)
	v_mfma_f32_16x16x32_bf16 v[18:21], v[210:213], v[230:233], v[18:21]
	s_waitcnt lgkmcnt(0)
	v_mfma_f32_16x16x32_bf16 v[52:55], v[214:217], v[230:233], v[52:55]
	global_load_dwordx4 v[230:233], v[96:97], off offset:192
	s_waitcnt vmcnt(3)
	v_mfma_f32_16x16x32_bf16 v[44:47], v[202:205], v[234:237], v[44:47]
	v_mfma_f32_16x16x32_bf16 v[28:31], v[206:209], v[234:237], v[28:31]
	v_mfma_f32_16x16x32_bf16 v[10:13], v[210:213], v[234:237], v[10:13]
	v_mfma_f32_16x16x32_bf16 v[56:59], v[214:217], v[234:237], v[56:59]
	global_load_dwordx4 v[234:237], v[246:247], off offset:-3904
	s_waitcnt vmcnt(3)
	v_mfma_f32_16x16x32_bf16 v[40:43], v[202:205], v[238:241], v[40:43]
	v_mfma_f32_16x16x32_bf16 v[22:25], v[206:209], v[238:241], v[22:25]
	v_mfma_f32_16x16x32_bf16 v[6:9], v[210:213], v[238:241], v[6:9]
	v_mfma_f32_16x16x32_bf16 v[60:63], v[214:217], v[238:241], v[60:63]
	global_load_dwordx4 v[238:241], v[246:247], off offset:192
	s_waitcnt vmcnt(3)
	v_mfma_f32_16x16x32_bf16 v[32:35], v[202:205], v[242:245], v[32:35]
	v_mfma_f32_16x16x32_bf16 v[14:17], v[206:209], v[242:245], v[14:17]
	v_mfma_f32_16x16x32_bf16 v[2:5], v[210:213], v[242:245], v[2:5]
	v_mfma_f32_16x16x32_bf16 v[64:67], v[214:217], v[242:245], v[64:67]
	global_load_dwordx4 v[242:245], v[248:249], off offset:192
	ds_read_b64_tr_b16 v[202:203], v134 offset:13056
	ds_read_b64_tr_b16 v[204:205], v134 offset:13600
	ds_read_b64_tr_b16 v[208:209], v134 offset:13632
	ds_read_b64_tr_b16 v[206:207], v134 offset:13088
	ds_read_b64_tr_b16 v[210:211], v134 offset:13120
	ds_read_b64_tr_b16 v[214:215], v134 offset:13152
	ds_read_b64_tr_b16 v[212:213], v134 offset:13664
	ds_read_b64_tr_b16 v[216:217], v134 offset:13696
	s_waitcnt vmcnt(3) lgkmcnt(6)
	v_mfma_f32_16x16x32_bf16 v[48:51], v[202:205], v[230:233], v[48:51]
	s_waitcnt lgkmcnt(4)
	v_mfma_f32_16x16x32_bf16 v[36:39], v[206:209], v[230:233], v[36:39]
	s_waitcnt lgkmcnt(1)
	v_mfma_f32_16x16x32_bf16 v[18:21], v[210:213], v[230:233], v[18:21]
	s_waitcnt lgkmcnt(0)
	v_mfma_f32_16x16x32_bf16 v[52:55], v[214:217], v[230:233], v[52:55]
	s_waitcnt vmcnt(2)
	v_mfma_f32_16x16x32_bf16 v[44:47], v[202:205], v[234:237], v[44:47]
	v_mfma_f32_16x16x32_bf16 v[28:31], v[206:209], v[234:237], v[28:31]
	v_mfma_f32_16x16x32_bf16 v[10:13], v[210:213], v[234:237], v[10:13]
	v_mfma_f32_16x16x32_bf16 v[56:59], v[214:217], v[234:237], v[56:59]
	s_waitcnt vmcnt(1)
	v_mfma_f32_16x16x32_bf16 v[40:43], v[202:205], v[238:241], v[40:43]
	v_mfma_f32_16x16x32_bf16 v[22:25], v[206:209], v[238:241], v[22:25]
	v_mfma_f32_16x16x32_bf16 v[6:9], v[210:213], v[238:241], v[6:9]
	v_mfma_f32_16x16x32_bf16 v[60:63], v[214:217], v[238:241], v[60:63]
	s_waitcnt vmcnt(0)
	v_mfma_f32_16x16x32_bf16 v[32:35], v[202:205], v[242:245], v[32:35]
	v_mfma_f32_16x16x32_bf16 v[14:17], v[206:209], v[242:245], v[14:17]
	v_mfma_f32_16x16x32_bf16 v[2:5], v[210:213], v[242:245], v[2:5]
	v_mfma_f32_16x16x32_bf16 v[64:67], v[214:217], v[242:245], v[64:67]
	s_movk_i32 s0, 0x4400
	s_lshl_b32 s0, s16, 1
	s_add_u32 s0, s8, s0
	s_waitcnt lgkmcnt(0)
	v_add_u32_e32 v96, v130, v131
	s_addc_u32 s1, s11, 0
	ds_write_b128 v96, v[48:51]
	ds_write_b128 v96, v[36:39] offset:64
	ds_write_b128 v96, v[18:21] offset:128
	ds_write_b128 v96, v[52:55] offset:192
	ds_write_b128 v96, v[44:47] offset:4352
	ds_write_b128 v96, v[28:31] offset:4416
	ds_write_b128 v96, v[10:13] offset:4480
	ds_write_b128 v96, v[56:59] offset:4544
	ds_write_b128 v96, v[40:43] offset:8704
	ds_write_b128 v96, v[22:25] offset:8768
	ds_write_b128 v96, v[6:9] offset:8832
	ds_write_b128 v96, v[60:63] offset:8896
	ds_write_b128 v96, v[32:35] offset:13056
	ds_write_b128 v96, v[14:17] offset:13120
	ds_write_b128 v96, v[2:5] offset:13184
	ds_write_b128 v96, v[64:67] offset:13248
	v_lshl_add_u64 v[44:45], s[0:1], 0, v[74:75]
	s_mov_b32 s0, 0xb0000
	v_add_co_u32_e32 v58, vcc, s0, v44
	s_mov_b32 s0, 0xb1000
	s_nop 0
	v_addc_co_u32_e32 v59, vcc, 0, v45, vcc
	s_waitcnt lgkmcnt(0)
	v_add_co_u32_e32 v2, vcc, s0, v44
	s_lshl_b32 s68, s20, 9
	s_nop 0
	v_addc_co_u32_e32 v3, vcc, 0, v45, vcc
	v_lshl_add_u64 v[42:43], v[80:81], 0, s[68:69]
	global_load_dwordx4 v[32:35], v[2:3], off offset:-4096
	global_load_dwordx4 v[28:31], v[2:3], off
	global_load_dword v60, v[42:43], off offset:256
	s_mov_b32 s0, 0xc6000
	v_add_co_u32_e32 v54, vcc, s0, v44
	s_mov_b32 s0, 0xc7000
	s_nop 0
	v_addc_co_u32_e32 v55, vcc, 0, v45, vcc
	v_add_co_u32_e32 v2, vcc, s0, v44
	s_mov_b32 s0, 0xdc000
	s_nop 0
	v_addc_co_u32_e32 v3, vcc, 0, v45, vcc
	v_add_co_u32_e32 v50, vcc, s0, v44
	v_mov_b64_e32 v[40:41], s[42:43]
	s_nop 0
	v_addc_co_u32_e32 v51, vcc, 0, v45, vcc
	s_mov_b32 s0, 0xdd000
	global_load_dwordx4 v[22:25], v[2:3], off offset:-4096
	global_load_dwordx4 v[18:21], v[2:3], off
	global_load_dword v56, v[42:43], off offset:288
	v_add_co_u32_e32 v2, vcc, s0, v44
	s_mov_b32 s0, 0xf2000
	s_nop 0
	v_addc_co_u32_e32 v3, vcc, 0, v45, vcc
	v_add_co_u32_e32 v46, vcc, s0, v44
	s_mov_b32 s0, 0xf3000
	s_nop 0
	v_addc_co_u32_e32 v47, vcc, 0, v45, vcc
	global_load_dwordx4 v[14:17], v[2:3], off offset:-4096
	global_load_dwordx4 v[10:13], v[2:3], off
	global_load_dword v52, v[42:43], off offset:320
	v_add_co_u32_e32 v2, vcc, s0, v44
	v_add_u32_e32 v61, v132, v133
	s_nop 0
	v_addc_co_u32_e32 v3, vcc, 0, v45, vcc
	global_load_dwordx4 v[6:9], v[2:3], off offset:-4096
	s_nop 0
	global_load_dwordx4 v[2:5], v[2:3], off
	s_nop 0
	global_load_dword v48, v[42:43], off offset:352
	ds_read_b128 v[62:65], v61
	ds_read_b128 v[36:39], v61 offset:16
	s_mov_b32 s0, 0x108000
	s_waitcnt vmcnt(11)
	v_lshlrev_b32_e32 v66, 16, v32
	v_and_b32_e32 v67, 0xffff0000, v32
	v_pk_mul_f32 v[96:97], v[66:67], v[66:67]
	s_waitcnt vmcnt(9) lgkmcnt(1)
	v_pk_add_f32 v[62:63], v[60:61], v[62:63] op_sel_hi:[0,1]
	v_pk_fma_f32 v[96:97], v[96:97], s[18:19], v[40:41] op_sel_hi:[1,0,0] neg_lo:[1,0,0] neg_hi:[1,0,0]
	v_lshlrev_b32_e32 v32, 16, v33
	v_pk_mul_f32 v[96:97], v[96:97], v[66:67]
	v_and_b32_e32 v33, 0xffff0000, v33
	v_exp_f32_e32 v96, v96
	v_exp_f32_e32 v97, v97
	s_nop 0
	v_pk_add_f32 v[96:97], v[96:97], 1.0 op_sel_hi:[1,0]
	s_nop 0
	v_rcp_f32_e32 v96, v96
	v_rcp_f32_e32 v97, v97
	s_nop 0
	v_pk_mul_f32 v[66:67], v[96:97], v[66:67]
	s_nop 0
	v_pk_mul_f32 v[62:63], v[62:63], v[66:67]
	v_lshlrev_b32_e32 v66, 16, v28
	v_and_b32_e32 v67, 0xffff0000, v28
	v_pk_mul_f32 v[96:97], v[66:67], s[24:25] op_sel_hi:[1,0]
	s_nop 0
	v_exp_f32_e32 v96, v96
	v_exp_f32_e32 v97, v97
	s_nop 0
	v_pk_add_f32 v[96:97], v[96:97], 1.0 op_sel_hi:[1,0]
	s_nop 0
	v_rcp_f32_e32 v96, v96
	v_rcp_f32_e32 v97, v97
	s_nop 0
	v_pk_mul_f32 v[66:67], v[96:97], v[66:67]
	s_nop 0
	v_pk_mul_f32 v[62:63], v[66:67], v[62:63]
	s_nop 0
	v_cvt_pk_bf16_f32 v28, v62, v63
	v_pk_add_f32 v[62:63], v[60:61], v[64:65] op_sel_hi:[0,1]
	v_pk_mul_f32 v[64:65], v[32:33], v[32:33]
	s_nop 0
	v_pk_fma_f32 v[64:65], v[64:65], s[18:19], v[40:41] op_sel_hi:[1,0,0] neg_lo:[1,0,0] neg_hi:[1,0,0]
	s_nop 0
	v_pk_mul_f32 v[64:65], v[64:65], v[32:33]
	s_nop 0
	v_exp_f32_e32 v64, v64
	v_exp_f32_e32 v65, v65
	s_nop 0
	v_pk_add_f32 v[64:65], v[64:65], 1.0 op_sel_hi:[1,0]
	s_nop 0
	v_rcp_f32_e32 v64, v64
	v_rcp_f32_e32 v65, v65
	s_nop 0
	v_pk_mul_f32 v[32:33], v[64:65], v[32:33]
	s_nop 0
	v_pk_mul_f32 v[32:33], v[62:63], v[32:33]
	v_lshlrev_b32_e32 v62, 16, v29
	v_and_b32_e32 v63, 0xffff0000, v29
	v_pk_mul_f32 v[64:65], v[62:63], s[24:25] op_sel_hi:[1,0]
	s_nop 0
	v_exp_f32_e32 v64, v64
	v_exp_f32_e32 v65, v65
	s_nop 0
	v_pk_add_f32 v[64:65], v[64:65], 1.0 op_sel_hi:[1,0]
	s_nop 0
	v_rcp_f32_e32 v64, v64
	v_rcp_f32_e32 v65, v65
	s_nop 0
	v_pk_mul_f32 v[62:63], v[64:65], v[62:63]
	s_nop 0
	v_pk_mul_f32 v[32:33], v[62:63], v[32:33]
	s_nop 0
	v_cvt_pk_bf16_f32 v29, v32, v33
	s_waitcnt lgkmcnt(0)
	v_pk_add_f32 v[32:33], v[60:61], v[36:37] op_sel_hi:[0,1]
	v_lshlrev_b32_e32 v36, 16, v34
	v_and_b32_e32 v37, 0xffff0000, v34
	v_pk_mul_f32 v[62:63], v[36:37], v[36:37]
	v_lshlrev_b32_e32 v34, 16, v35
	v_pk_fma_f32 v[62:63], v[62:63], s[18:19], v[40:41] op_sel_hi:[1,0,0] neg_lo:[1,0,0] neg_hi:[1,0,0]
	v_and_b32_e32 v35, 0xffff0000, v35
	v_pk_mul_f32 v[62:63], v[62:63], v[36:37]
	s_nop 0
	v_exp_f32_e32 v62, v62
	v_exp_f32_e32 v63, v63
	s_nop 0
	v_pk_add_f32 v[62:63], v[62:63], 1.0 op_sel_hi:[1,0]
	s_nop 0
	v_rcp_f32_e32 v62, v62
	v_rcp_f32_e32 v63, v63
	s_nop 0
	v_pk_mul_f32 v[36:37], v[62:63], v[36:37]
	s_nop 0
	v_pk_mul_f32 v[32:33], v[32:33], v[36:37]
	v_lshlrev_b32_e32 v36, 16, v30
	v_and_b32_e32 v37, 0xffff0000, v30
	v_pk_mul_f32 v[62:63], v[36:37], s[24:25] op_sel_hi:[1,0]
	s_nop 0
	v_exp_f32_e32 v62, v62
	v_exp_f32_e32 v63, v63
	s_nop 0
	v_pk_add_f32 v[62:63], v[62:63], 1.0 op_sel_hi:[1,0]
	s_nop 0
	v_rcp_f32_e32 v62, v62
	v_rcp_f32_e32 v63, v63
	s_nop 0
	v_pk_mul_f32 v[36:37], v[62:63], v[36:37]
	s_nop 0
	v_pk_mul_f32 v[32:33], v[36:37], v[32:33]
	v_pk_mul_f32 v[36:37], v[34:35], v[34:35]
	v_cvt_pk_bf16_f32 v30, v32, v33
	v_pk_add_f32 v[32:33], v[60:61], v[38:39] op_sel_hi:[0,1]
	v_pk_fma_f32 v[36:37], v[36:37], s[18:19], v[40:41] op_sel_hi:[1,0,0] neg_lo:[1,0,0] neg_hi:[1,0,0]
	s_nop 0
	v_pk_mul_f32 v[36:37], v[36:37], v[34:35]
	s_nop 0
	v_exp_f32_e32 v36, v36
	v_exp_f32_e32 v37, v37
	s_nop 0
	v_pk_add_f32 v[36:37], v[36:37], 1.0 op_sel_hi:[1,0]
	s_nop 0
	v_rcp_f32_e32 v36, v36
	v_rcp_f32_e32 v37, v37
	s_nop 0
	v_pk_mul_f32 v[34:35], v[36:37], v[34:35]
	s_nop 0
	v_pk_mul_f32 v[32:33], v[32:33], v[34:35]
	v_lshlrev_b32_e32 v34, 16, v31
	v_and_b32_e32 v35, 0xffff0000, v31
	v_pk_mul_f32 v[36:37], v[34:35], s[24:25] op_sel_hi:[1,0]
	s_nop 0
	v_exp_f32_e32 v36, v36
	v_exp_f32_e32 v37, v37
	s_nop 0
	v_pk_add_f32 v[36:37], v[36:37], 1.0 op_sel_hi:[1,0]
	s_nop 0
	v_rcp_f32_e32 v36, v36
	v_rcp_f32_e32 v37, v37
	s_nop 0
	v_pk_mul_f32 v[34:35], v[36:37], v[34:35]
	s_waitcnt vmcnt(8)
	v_lshlrev_b32_e32 v36, 16, v22
	v_and_b32_e32 v37, 0xffff0000, v22
	v_pk_mul_f32 v[38:39], v[36:37], v[36:37]
	v_pk_mul_f32 v[32:33], v[34:35], v[32:33]
	v_pk_fma_f32 v[38:39], v[38:39], s[18:19], v[40:41] op_sel_hi:[1,0,0] neg_lo:[1,0,0] neg_hi:[1,0,0]
	v_cvt_pk_bf16_f32 v31, v32, v33
	global_store_dwordx4 v[58:59], v[28:31], off
	v_pk_mul_f32 v[38:39], v[38:39], v[36:37]
	ds_read_b128 v[32:35], v61 offset:2176
	ds_read_b128 v[28:31], v61 offset:2192
	v_exp_f32_e32 v38, v38
	v_exp_f32_e32 v39, v39
	v_lshlrev_b32_e32 v22, 16, v23
	s_waitcnt vmcnt(7) lgkmcnt(1)
	v_pk_add_f32 v[32:33], v[56:57], v[32:33] op_sel_hi:[0,1]
	v_and_b32_e32 v23, 0xffff0000, v23
	v_pk_add_f32 v[38:39], v[38:39], 1.0 op_sel_hi:[1,0]
	s_nop 0
	v_rcp_f32_e32 v38, v38
	v_rcp_f32_e32 v39, v39
	s_nop 0
	v_pk_mul_f32 v[36:37], v[38:39], v[36:37]
	s_nop 0
	v_pk_mul_f32 v[32:33], v[32:33], v[36:37]
	v_lshlrev_b32_e32 v36, 16, v18
	v_and_b32_e32 v37, 0xffff0000, v18
	v_pk_mul_f32 v[38:39], v[36:37], s[24:25] op_sel_hi:[1,0]
	s_nop 0
	v_exp_f32_e32 v38, v38
	v_exp_f32_e32 v39, v39
	s_nop 0
	v_pk_add_f32 v[38:39], v[38:39], 1.0 op_sel_hi:[1,0]
	s_nop 0
	v_rcp_f32_e32 v38, v38
	v_rcp_f32_e32 v39, v39
	s_nop 0
	v_pk_mul_f32 v[36:37], v[38:39], v[36:37]
	s_nop 0
	v_pk_mul_f32 v[32:33], v[36:37], v[32:33]
	s_nop 0
	v_cvt_pk_bf16_f32 v18, v32, v33
	v_pk_add_f32 v[32:33], v[56:57], v[34:35] op_sel_hi:[0,1]
	v_pk_mul_f32 v[34:35], v[22:23], v[22:23]
	s_nop 0
	v_pk_fma_f32 v[34:35], v[34:35], s[18:19], v[40:41] op_sel_hi:[1,0,0] neg_lo:[1,0,0] neg_hi:[1,0,0]
	s_nop 0
	v_pk_mul_f32 v[34:35], v[34:35], v[22:23]
	s_nop 0
	v_exp_f32_e32 v34, v34
	v_exp_f32_e32 v35, v35
	s_nop 0
	v_pk_add_f32 v[34:35], v[34:35], 1.0 op_sel_hi:[1,0]
	s_nop 0
	v_rcp_f32_e32 v34, v34
	v_rcp_f32_e32 v35, v35
	s_nop 0
	v_pk_mul_f32 v[22:23], v[34:35], v[22:23]
	s_nop 0
	v_pk_mul_f32 v[22:23], v[32:33], v[22:23]
	v_lshlrev_b32_e32 v32, 16, v19
	v_and_b32_e32 v33, 0xffff0000, v19
	v_pk_mul_f32 v[34:35], v[32:33], s[24:25] op_sel_hi:[1,0]
	s_nop 0
	v_exp_f32_e32 v34, v34
	v_exp_f32_e32 v35, v35
	s_nop 0
	v_pk_add_f32 v[34:35], v[34:35], 1.0 op_sel_hi:[1,0]
	s_nop 0
	v_rcp_f32_e32 v34, v34
	v_rcp_f32_e32 v35, v35
	s_nop 0
	v_pk_mul_f32 v[32:33], v[34:35], v[32:33]
	s_nop 0
	v_pk_mul_f32 v[22:23], v[32:33], v[22:23]
	s_nop 0
	v_cvt_pk_bf16_f32 v19, v22, v23
	s_waitcnt lgkmcnt(0)
	v_pk_add_f32 v[22:23], v[56:57], v[28:29] op_sel_hi:[0,1]
	v_lshlrev_b32_e32 v28, 16, v24
	v_and_b32_e32 v29, 0xffff0000, v24
	v_pk_mul_f32 v[32:33], v[28:29], v[28:29]
	v_lshlrev_b32_e32 v24, 16, v25
	v_pk_fma_f32 v[32:33], v[32:33], s[18:19], v[40:41] op_sel_hi:[1,0,0] neg_lo:[1,0,0] neg_hi:[1,0,0]
	v_and_b32_e32 v25, 0xffff0000, v25
	v_pk_mul_f32 v[32:33], v[32:33], v[28:29]
	s_nop 0
	v_exp_f32_e32 v32, v32
	v_exp_f32_e32 v33, v33
	s_nop 0
	v_pk_add_f32 v[32:33], v[32:33], 1.0 op_sel_hi:[1,0]
	s_nop 0
	v_rcp_f32_e32 v32, v32
	v_rcp_f32_e32 v33, v33
	s_nop 0
	v_pk_mul_f32 v[28:29], v[32:33], v[28:29]
	s_nop 0
	v_pk_mul_f32 v[22:23], v[22:23], v[28:29]
	v_lshlrev_b32_e32 v28, 16, v20
	v_and_b32_e32 v29, 0xffff0000, v20
	v_pk_mul_f32 v[32:33], v[28:29], s[24:25] op_sel_hi:[1,0]
	s_nop 0
	v_exp_f32_e32 v32, v32
	v_exp_f32_e32 v33, v33
	s_nop 0
	v_pk_add_f32 v[32:33], v[32:33], 1.0 op_sel_hi:[1,0]
	s_nop 0
	v_rcp_f32_e32 v32, v32
	v_rcp_f32_e32 v33, v33
	s_nop 0
	v_pk_mul_f32 v[28:29], v[32:33], v[28:29]
	s_nop 0
	v_pk_mul_f32 v[22:23], v[28:29], v[22:23]
	v_pk_mul_f32 v[28:29], v[24:25], v[24:25]
	v_cvt_pk_bf16_f32 v20, v22, v23
	v_pk_add_f32 v[22:23], v[56:57], v[30:31] op_sel_hi:[0,1]
	v_pk_fma_f32 v[28:29], v[28:29], s[18:19], v[40:41] op_sel_hi:[1,0,0] neg_lo:[1,0,0] neg_hi:[1,0,0]
	v_add_co_u32_e32 v56, vcc, s0, v44
	v_pk_mul_f32 v[28:29], v[28:29], v[24:25]
	s_nop 0
	v_addc_co_u32_e32 v57, vcc, 0, v45, vcc
	v_exp_f32_e32 v28, v28
	v_exp_f32_e32 v29, v29
	s_mov_b32 s0, 0x109000
	v_pk_add_f32 v[28:29], v[28:29], 1.0 op_sel_hi:[1,0]
	s_nop 0
	v_rcp_f32_e32 v28, v28
	v_rcp_f32_e32 v29, v29
	s_nop 0
	v_pk_mul_f32 v[24:25], v[28:29], v[24:25]
	s_nop 0
	v_pk_mul_f32 v[22:23], v[22:23], v[24:25]
	v_lshlrev_b32_e32 v24, 16, v21
	v_and_b32_e32 v25, 0xffff0000, v21
	v_pk_mul_f32 v[28:29], v[24:25], s[24:25] op_sel_hi:[1,0]
	s_nop 0
	v_exp_f32_e32 v28, v28
	v_exp_f32_e32 v29, v29
	s_nop 0
	v_pk_add_f32 v[28:29], v[28:29], 1.0 op_sel_hi:[1,0]
	s_nop 0
	v_rcp_f32_e32 v28, v28
	v_rcp_f32_e32 v29, v29
	s_nop 0
	v_pk_mul_f32 v[24:25], v[28:29], v[24:25]
	s_waitcnt vmcnt(6)
	v_lshlrev_b32_e32 v28, 16, v14
	v_and_b32_e32 v29, 0xffff0000, v14
	v_pk_mul_f32 v[30:31], v[28:29], v[28:29]
	v_pk_mul_f32 v[22:23], v[24:25], v[22:23]
	v_pk_fma_f32 v[30:31], v[30:31], s[18:19], v[40:41] op_sel_hi:[1,0,0] neg_lo:[1,0,0] neg_hi:[1,0,0]
	v_cvt_pk_bf16_f32 v21, v22, v23
	global_store_dwordx4 v[54:55], v[18:21], off
	v_pk_mul_f32 v[30:31], v[30:31], v[28:29]
	ds_read_b128 v[22:25], v61 offset:4352
	ds_read_b128 v[18:21], v61 offset:4368
	v_exp_f32_e32 v30, v30
	v_exp_f32_e32 v31, v31
	v_lshlrev_b32_e32 v14, 16, v15
	s_waitcnt vmcnt(5) lgkmcnt(1)
	v_pk_add_f32 v[22:23], v[52:53], v[22:23] op_sel_hi:[0,1]
	v_and_b32_e32 v15, 0xffff0000, v15
	v_pk_add_f32 v[30:31], v[30:31], 1.0 op_sel_hi:[1,0]
	s_nop 0
	v_rcp_f32_e32 v30, v30
	v_rcp_f32_e32 v31, v31
	s_nop 0
	v_pk_mul_f32 v[28:29], v[30:31], v[28:29]
	s_nop 0
	v_pk_mul_f32 v[22:23], v[28:29], v[22:23]
	v_lshlrev_b32_e32 v28, 16, v10
	v_and_b32_e32 v29, 0xffff0000, v10
	v_pk_mul_f32 v[30:31], v[28:29], s[24:25] op_sel_hi:[1,0]
	s_nop 0
	v_exp_f32_e32 v30, v30
	v_exp_f32_e32 v31, v31
	s_nop 0
	v_pk_add_f32 v[30:31], v[30:31], 1.0 op_sel_hi:[1,0]
	s_nop 0
	v_rcp_f32_e32 v30, v30
	v_rcp_f32_e32 v31, v31
	s_nop 0
	v_pk_mul_f32 v[28:29], v[30:31], v[28:29]
	s_nop 0
	v_pk_mul_f32 v[22:23], v[28:29], v[22:23]
	s_nop 0
	v_cvt_pk_bf16_f32 v10, v22, v23
	v_pk_add_f32 v[22:23], v[52:53], v[24:25] op_sel_hi:[0,1]
	v_pk_mul_f32 v[24:25], v[14:15], v[14:15]
	s_nop 0
	v_pk_fma_f32 v[24:25], v[24:25], s[18:19], v[40:41] op_sel_hi:[1,0,0] neg_lo:[1,0,0] neg_hi:[1,0,0]
	s_nop 0
	v_pk_mul_f32 v[24:25], v[24:25], v[14:15]
	s_nop 0
	v_exp_f32_e32 v24, v24
	v_exp_f32_e32 v25, v25
	s_nop 0
	v_pk_add_f32 v[24:25], v[24:25], 1.0 op_sel_hi:[1,0]
	s_nop 0
	v_rcp_f32_e32 v24, v24
	v_rcp_f32_e32 v25, v25
	s_nop 0
	v_pk_mul_f32 v[14:15], v[24:25], v[14:15]
	s_nop 0
	v_pk_mul_f32 v[14:15], v[14:15], v[22:23]
	v_lshlrev_b32_e32 v22, 16, v11
	v_and_b32_e32 v23, 0xffff0000, v11
	v_pk_mul_f32 v[24:25], v[22:23], s[24:25] op_sel_hi:[1,0]
	s_nop 0
	v_exp_f32_e32 v24, v24
	v_exp_f32_e32 v25, v25
	s_nop 0
	v_pk_add_f32 v[24:25], v[24:25], 1.0 op_sel_hi:[1,0]
	s_nop 0
	v_rcp_f32_e32 v24, v24
	v_rcp_f32_e32 v25, v25
	s_nop 0
	v_pk_mul_f32 v[22:23], v[24:25], v[22:23]
	s_nop 0
	v_pk_mul_f32 v[14:15], v[22:23], v[14:15]
	s_nop 0
	v_cvt_pk_bf16_f32 v11, v14, v15
	s_waitcnt lgkmcnt(0)
	v_pk_add_f32 v[14:15], v[52:53], v[18:19] op_sel_hi:[0,1]
	v_lshlrev_b32_e32 v18, 16, v16
	v_and_b32_e32 v19, 0xffff0000, v16
	v_pk_mul_f32 v[22:23], v[18:19], v[18:19]
	v_lshlrev_b32_e32 v16, 16, v17
	v_pk_fma_f32 v[22:23], v[22:23], s[18:19], v[40:41] op_sel_hi:[1,0,0] neg_lo:[1,0,0] neg_hi:[1,0,0]
	v_and_b32_e32 v17, 0xffff0000, v17
	v_pk_mul_f32 v[22:23], v[22:23], v[18:19]
	s_nop 0
	v_exp_f32_e32 v22, v22
	v_exp_f32_e32 v23, v23
	s_nop 0
	v_pk_add_f32 v[22:23], v[22:23], 1.0 op_sel_hi:[1,0]
	s_nop 0
	v_rcp_f32_e32 v22, v22
	v_rcp_f32_e32 v23, v23
	s_nop 0
	v_pk_mul_f32 v[18:19], v[22:23], v[18:19]
	s_nop 0
	v_pk_mul_f32 v[14:15], v[18:19], v[14:15]
	v_lshlrev_b32_e32 v18, 16, v12
	v_and_b32_e32 v19, 0xffff0000, v12
	v_pk_mul_f32 v[22:23], v[18:19], s[24:25] op_sel_hi:[1,0]
	s_nop 0
	v_exp_f32_e32 v22, v22
	v_exp_f32_e32 v23, v23
	s_nop 0
	v_pk_add_f32 v[22:23], v[22:23], 1.0 op_sel_hi:[1,0]
	s_nop 0
	v_rcp_f32_e32 v22, v22
	v_rcp_f32_e32 v23, v23
	s_nop 0
	v_pk_mul_f32 v[18:19], v[22:23], v[18:19]
	s_nop 0
	v_pk_mul_f32 v[14:15], v[18:19], v[14:15]
	v_pk_mul_f32 v[18:19], v[16:17], v[16:17]
	v_cvt_pk_bf16_f32 v12, v14, v15
	v_pk_add_f32 v[14:15], v[52:53], v[20:21] op_sel_hi:[0,1]
	v_pk_fma_f32 v[18:19], v[18:19], s[18:19], v[40:41] op_sel_hi:[1,0,0] neg_lo:[1,0,0] neg_hi:[1,0,0]
	s_nop 0
	v_pk_mul_f32 v[18:19], v[18:19], v[16:17]
	s_nop 0
	v_exp_f32_e32 v18, v18
	v_exp_f32_e32 v19, v19
	s_nop 0
	v_pk_add_f32 v[18:19], v[18:19], 1.0 op_sel_hi:[1,0]
	s_nop 0
	v_rcp_f32_e32 v18, v18
	v_rcp_f32_e32 v19, v19
	s_nop 0
	v_pk_mul_f32 v[16:17], v[18:19], v[16:17]
	s_nop 0
	v_pk_mul_f32 v[14:15], v[16:17], v[14:15]
	v_lshlrev_b32_e32 v16, 16, v13
	v_and_b32_e32 v17, 0xffff0000, v13
	v_pk_mul_f32 v[18:19], v[16:17], s[24:25] op_sel_hi:[1,0]
	s_nop 0
	v_exp_f32_e32 v18, v18
	v_exp_f32_e32 v19, v19
	s_nop 0
	v_pk_add_f32 v[18:19], v[18:19], 1.0 op_sel_hi:[1,0]
	s_nop 0
	v_rcp_f32_e32 v18, v18
	v_rcp_f32_e32 v19, v19
	s_nop 0
	v_pk_mul_f32 v[16:17], v[18:19], v[16:17]
	s_waitcnt vmcnt(4)
	v_lshlrev_b32_e32 v18, 16, v6
	v_and_b32_e32 v19, 0xffff0000, v6
	v_pk_mul_f32 v[20:21], v[18:19], v[18:19]
	v_pk_mul_f32 v[14:15], v[16:17], v[14:15]
	v_pk_fma_f32 v[20:21], v[20:21], s[18:19], v[40:41] op_sel_hi:[1,0,0] neg_lo:[1,0,0] neg_hi:[1,0,0]
	v_cvt_pk_bf16_f32 v13, v14, v15
	global_store_dwordx4 v[50:51], v[10:13], off
	v_pk_mul_f32 v[20:21], v[20:21], v[18:19]
	ds_read_b128 v[14:17], v61 offset:6528
	ds_read_b128 v[10:13], v61 offset:6544
	v_exp_f32_e32 v20, v20
	v_exp_f32_e32 v21, v21
	v_lshlrev_b32_e32 v6, 16, v7
	s_waitcnt vmcnt(3) lgkmcnt(1)
	v_pk_add_f32 v[14:15], v[48:49], v[14:15] op_sel_hi:[0,1]
	v_and_b32_e32 v7, 0xffff0000, v7
	v_pk_add_f32 v[20:21], v[20:21], 1.0 op_sel_hi:[1,0]
	s_nop 0
	v_rcp_f32_e32 v20, v20
	v_rcp_f32_e32 v21, v21
	s_nop 0
	v_pk_mul_f32 v[18:19], v[20:21], v[18:19]
	s_nop 0
	v_pk_mul_f32 v[14:15], v[18:19], v[14:15]
	v_lshlrev_b32_e32 v18, 16, v2
	v_and_b32_e32 v19, 0xffff0000, v2
	v_pk_mul_f32 v[20:21], v[18:19], s[24:25] op_sel_hi:[1,0]
	s_nop 0
	v_exp_f32_e32 v20, v20
	v_exp_f32_e32 v21, v21
	s_nop 0
	v_pk_add_f32 v[20:21], v[20:21], 1.0 op_sel_hi:[1,0]
	s_nop 0
	v_rcp_f32_e32 v20, v20
	v_rcp_f32_e32 v21, v21
	s_nop 0
	v_pk_mul_f32 v[18:19], v[20:21], v[18:19]
	s_nop 0
	v_pk_mul_f32 v[14:15], v[18:19], v[14:15]
	s_nop 0
	v_cvt_pk_bf16_f32 v2, v14, v15
	v_pk_add_f32 v[14:15], v[48:49], v[16:17] op_sel_hi:[0,1]
	v_pk_mul_f32 v[16:17], v[6:7], v[6:7]
	s_nop 0
	v_pk_fma_f32 v[16:17], v[16:17], s[18:19], v[40:41] op_sel_hi:[1,0,0] neg_lo:[1,0,0] neg_hi:[1,0,0]
	s_nop 0
	v_pk_mul_f32 v[16:17], v[16:17], v[6:7]
	s_nop 0
	v_exp_f32_e32 v16, v16
	v_exp_f32_e32 v17, v17
	s_nop 0
	v_pk_add_f32 v[16:17], v[16:17], 1.0 op_sel_hi:[1,0]
	s_nop 0
	v_rcp_f32_e32 v16, v16
	v_rcp_f32_e32 v17, v17
	s_nop 0
	v_pk_mul_f32 v[6:7], v[16:17], v[6:7]
	s_nop 0
	v_pk_mul_f32 v[6:7], v[6:7], v[14:15]
	v_lshlrev_b32_e32 v14, 16, v3
	v_and_b32_e32 v15, 0xffff0000, v3
	v_pk_mul_f32 v[16:17], v[14:15], s[24:25] op_sel_hi:[1,0]
	s_nop 0
	v_exp_f32_e32 v16, v16
	v_exp_f32_e32 v17, v17
	s_nop 0
	v_pk_add_f32 v[16:17], v[16:17], 1.0 op_sel_hi:[1,0]
	s_nop 0
	v_rcp_f32_e32 v16, v16
	v_rcp_f32_e32 v17, v17
	s_nop 0
	v_pk_mul_f32 v[14:15], v[16:17], v[14:15]
	s_nop 0
	v_pk_mul_f32 v[6:7], v[14:15], v[6:7]
	s_nop 0
	v_cvt_pk_bf16_f32 v3, v6, v7
	s_waitcnt lgkmcnt(0)
	v_pk_add_f32 v[6:7], v[48:49], v[10:11] op_sel_hi:[0,1]
	v_lshlrev_b32_e32 v10, 16, v8
	v_and_b32_e32 v11, 0xffff0000, v8
	v_pk_mul_f32 v[14:15], v[10:11], v[10:11]
	v_lshlrev_b32_e32 v8, 16, v9
	v_pk_fma_f32 v[14:15], v[14:15], s[18:19], v[40:41] op_sel_hi:[1,0,0] neg_lo:[1,0,0] neg_hi:[1,0,0]
	v_and_b32_e32 v9, 0xffff0000, v9
	v_pk_mul_f32 v[14:15], v[14:15], v[10:11]
	s_nop 0
	v_exp_f32_e32 v14, v14
	v_exp_f32_e32 v15, v15
	s_nop 0
	v_pk_add_f32 v[14:15], v[14:15], 1.0 op_sel_hi:[1,0]
	s_nop 0
	v_rcp_f32_e32 v14, v14
	v_rcp_f32_e32 v15, v15
	s_nop 0
	v_pk_mul_f32 v[10:11], v[14:15], v[10:11]
	s_nop 0
	v_pk_mul_f32 v[6:7], v[10:11], v[6:7]
	v_lshlrev_b32_e32 v10, 16, v4
	v_and_b32_e32 v11, 0xffff0000, v4
	v_pk_mul_f32 v[14:15], v[10:11], s[24:25] op_sel_hi:[1,0]
	s_nop 0
	v_exp_f32_e32 v14, v14
	v_exp_f32_e32 v15, v15
	s_nop 0
	v_pk_add_f32 v[14:15], v[14:15], 1.0 op_sel_hi:[1,0]
	s_nop 0
	v_rcp_f32_e32 v14, v14
	v_rcp_f32_e32 v15, v15
	s_nop 0
	v_pk_mul_f32 v[10:11], v[14:15], v[10:11]
	s_nop 0
	v_pk_mul_f32 v[6:7], v[10:11], v[6:7]
	v_pk_mul_f32 v[10:11], v[8:9], v[8:9]
	v_cvt_pk_bf16_f32 v4, v6, v7
	v_pk_add_f32 v[6:7], v[48:49], v[12:13] op_sel_hi:[0,1]
	v_pk_fma_f32 v[10:11], v[10:11], s[18:19], v[40:41] op_sel_hi:[1,0,0] neg_lo:[1,0,0] neg_hi:[1,0,0]
	s_nop 0
	v_pk_mul_f32 v[10:11], v[10:11], v[8:9]
	s_nop 0
	v_exp_f32_e32 v10, v10
	v_exp_f32_e32 v11, v11
	s_nop 0
	v_pk_add_f32 v[10:11], v[10:11], 1.0 op_sel_hi:[1,0]
	s_nop 0
	v_rcp_f32_e32 v10, v10
	v_rcp_f32_e32 v11, v11
	s_nop 0
	v_pk_mul_f32 v[8:9], v[10:11], v[8:9]
	s_nop 0
	v_pk_mul_f32 v[6:7], v[8:9], v[6:7]
	v_lshlrev_b32_e32 v8, 16, v5
	v_and_b32_e32 v9, 0xffff0000, v5
	v_pk_mul_f32 v[10:11], v[8:9], s[24:25] op_sel_hi:[1,0]
	s_nop 0
	v_exp_f32_e32 v10, v10
	v_exp_f32_e32 v11, v11
	s_nop 0
	v_pk_add_f32 v[10:11], v[10:11], 1.0 op_sel_hi:[1,0]
	s_nop 0
	v_rcp_f32_e32 v10, v10
	v_rcp_f32_e32 v11, v11
	s_nop 0
	v_pk_mul_f32 v[8:9], v[10:11], v[8:9]
	s_nop 0
	v_pk_mul_f32 v[6:7], v[8:9], v[6:7]
	s_nop 0
	v_cvt_pk_bf16_f32 v5, v6, v7
	global_store_dwordx4 v[46:47], v[2:5], off
	s_nop 1
	v_add_co_u32_e32 v2, vcc, s0, v44
	s_mov_b32 s0, 0x11e000
	s_nop 0
	v_addc_co_u32_e32 v3, vcc, 0, v45, vcc
	global_load_dwordx4 v[32:35], v[2:3], off offset:-4096
	global_load_dwordx4 v[28:31], v[2:3], off
	global_load_dword v58, v[42:43], off offset:384
	v_add_co_u32_e32 v52, vcc, s0, v44
	s_mov_b32 s0, 0x11f000
	s_nop 0
	v_addc_co_u32_e32 v53, vcc, 0, v45, vcc
	v_add_co_u32_e32 v2, vcc, s0, v44
	s_mov_b32 s0, 0x134000
	s_nop 0
	v_addc_co_u32_e32 v3, vcc, 0, v45, vcc
	v_add_co_u32_e32 v48, vcc, s0, v44
	s_mov_b32 s0, 0x135000
	s_nop 0
	v_addc_co_u32_e32 v49, vcc, 0, v45, vcc
	global_load_dwordx4 v[22:25], v[2:3], off offset:-4096
	global_load_dwordx4 v[18:21], v[2:3], off
	global_load_dword v54, v[42:43], off offset:416
	v_add_co_u32_e32 v2, vcc, s0, v44
	s_mov_b32 s0, 0x14a000
	s_nop 0
	v_addc_co_u32_e32 v3, vcc, 0, v45, vcc
	v_add_co_u32_e32 v46, vcc, s0, v44
	s_mov_b32 s0, 0x14b000
	s_nop 0
	v_addc_co_u32_e32 v47, vcc, 0, v45, vcc
	global_load_dwordx4 v[14:17], v[2:3], off offset:-4096
	global_load_dwordx4 v[10:13], v[2:3], off
	global_load_dword v50, v[42:43], off offset:448
	v_add_co_u32_e32 v2, vcc, s0, v44
	s_mov_b64 s[0:1], 0
	s_nop 0
	v_addc_co_u32_e32 v3, vcc, 0, v45, vcc
	global_load_dwordx4 v[6:9], v[2:3], off offset:-4096
	s_nop 0
	global_load_dwordx4 v[2:5], v[2:3], off
	s_nop 0
	global_load_dword v42, v[42:43], off offset:480
	ds_read_b128 v[62:65], v61 offset:8704
	ds_read_b128 v[36:39], v61 offset:8720
	s_waitcnt vmcnt(9) lgkmcnt(1)
	v_pk_add_f32 v[44:45], v[58:59], v[62:63] op_sel_hi:[0,1]
	v_lshlrev_b32_e32 v62, 16, v32
	v_and_b32_e32 v63, 0xffff0000, v32
	v_pk_mul_f32 v[66:67], v[62:63], v[62:63]
	v_lshlrev_b32_e32 v32, 16, v33
	v_pk_fma_f32 v[66:67], v[66:67], s[18:19], v[40:41] op_sel_hi:[1,0,0] neg_lo:[1,0,0] neg_hi:[1,0,0]
	v_and_b32_e32 v33, 0xffff0000, v33
	v_pk_mul_f32 v[66:67], v[66:67], v[62:63]
	s_nop 0
	v_exp_f32_e32 v66, v66
	v_exp_f32_e32 v67, v67
	s_nop 0
	v_pk_add_f32 v[66:67], v[66:67], 1.0 op_sel_hi:[1,0]
	s_nop 0
	v_rcp_f32_e32 v66, v66
	v_rcp_f32_e32 v67, v67
	s_nop 0
	v_pk_mul_f32 v[62:63], v[66:67], v[62:63]
	s_nop 0
	v_pk_mul_f32 v[44:45], v[44:45], v[62:63]
	v_lshlrev_b32_e32 v62, 16, v28
	v_and_b32_e32 v63, 0xffff0000, v28
	v_pk_mul_f32 v[66:67], v[62:63], s[24:25] op_sel_hi:[1,0]
	s_nop 0
	v_exp_f32_e32 v66, v66
	v_exp_f32_e32 v67, v67
	s_nop 0
	v_pk_add_f32 v[66:67], v[66:67], 1.0 op_sel_hi:[1,0]
	s_nop 0
	v_rcp_f32_e32 v66, v66
	v_rcp_f32_e32 v67, v67
	s_nop 0
	v_pk_mul_f32 v[62:63], v[66:67], v[62:63]
	s_nop 0
	v_pk_mul_f32 v[44:45], v[62:63], v[44:45]
	v_pk_mul_f32 v[62:63], v[32:33], v[32:33]
	v_cvt_pk_bf16_f32 v28, v44, v45
	v_pk_add_f32 v[44:45], v[58:59], v[64:65] op_sel_hi:[0,1]
	v_pk_fma_f32 v[62:63], v[62:63], s[18:19], v[40:41] op_sel_hi:[1,0,0] neg_lo:[1,0,0] neg_hi:[1,0,0]
	s_nop 0
	v_pk_mul_f32 v[62:63], v[62:63], v[32:33]
	s_nop 0
	v_exp_f32_e32 v62, v62
	v_exp_f32_e32 v63, v63
	s_nop 0
	v_pk_add_f32 v[62:63], v[62:63], 1.0 op_sel_hi:[1,0]
	s_nop 0
	v_rcp_f32_e32 v62, v62
	v_rcp_f32_e32 v63, v63
	s_nop 0
	v_pk_mul_f32 v[32:33], v[62:63], v[32:33]
	s_nop 0
	v_pk_mul_f32 v[32:33], v[44:45], v[32:33]
	v_lshlrev_b32_e32 v44, 16, v29
	v_and_b32_e32 v45, 0xffff0000, v29
	v_pk_mul_f32 v[62:63], v[44:45], s[24:25] op_sel_hi:[1,0]
	s_nop 0
	v_exp_f32_e32 v62, v62
	v_exp_f32_e32 v63, v63
	s_nop 0
	v_pk_add_f32 v[62:63], v[62:63], 1.0 op_sel_hi:[1,0]
	s_nop 0
	v_rcp_f32_e32 v62, v62
	v_rcp_f32_e32 v63, v63
	s_nop 0
	v_pk_mul_f32 v[44:45], v[62:63], v[44:45]
	s_nop 0
	v_pk_mul_f32 v[32:33], v[44:45], v[32:33]
	s_nop 0
	v_cvt_pk_bf16_f32 v29, v32, v33
	s_waitcnt lgkmcnt(0)
	v_pk_add_f32 v[32:33], v[58:59], v[36:37] op_sel_hi:[0,1]
	v_lshlrev_b32_e32 v36, 16, v34
	v_and_b32_e32 v37, 0xffff0000, v34
	v_pk_mul_f32 v[44:45], v[36:37], v[36:37]
	v_lshlrev_b32_e32 v34, 16, v35
	v_pk_fma_f32 v[44:45], v[44:45], s[18:19], v[40:41] op_sel_hi:[1,0,0] neg_lo:[1,0,0] neg_hi:[1,0,0]
	v_and_b32_e32 v35, 0xffff0000, v35
	v_pk_mul_f32 v[44:45], v[44:45], v[36:37]
	s_nop 0
	v_exp_f32_e32 v44, v44
	v_exp_f32_e32 v45, v45
	s_nop 0
	v_pk_add_f32 v[44:45], v[44:45], 1.0 op_sel_hi:[1,0]
	s_nop 0
	v_rcp_f32_e32 v44, v44
	v_rcp_f32_e32 v45, v45
	s_nop 0
	v_pk_mul_f32 v[36:37], v[44:45], v[36:37]
	s_nop 0
	v_pk_mul_f32 v[32:33], v[32:33], v[36:37]
	v_lshlrev_b32_e32 v36, 16, v30
	v_and_b32_e32 v37, 0xffff0000, v30
	v_pk_mul_f32 v[44:45], v[36:37], s[24:25] op_sel_hi:[1,0]
	s_nop 0
	v_exp_f32_e32 v44, v44
	v_exp_f32_e32 v45, v45
	s_nop 0
	v_pk_add_f32 v[44:45], v[44:45], 1.0 op_sel_hi:[1,0]
	s_nop 0
	v_rcp_f32_e32 v44, v44
	v_rcp_f32_e32 v45, v45
	s_nop 0
	v_pk_mul_f32 v[36:37], v[44:45], v[36:37]
	s_nop 0
	v_pk_mul_f32 v[32:33], v[36:37], v[32:33]
	v_pk_mul_f32 v[36:37], v[34:35], v[34:35]
	v_cvt_pk_bf16_f32 v30, v32, v33
	v_pk_add_f32 v[32:33], v[58:59], v[38:39] op_sel_hi:[0,1]
	v_pk_fma_f32 v[36:37], v[36:37], s[18:19], v[40:41] op_sel_hi:[1,0,0] neg_lo:[1,0,0] neg_hi:[1,0,0]
	s_nop 0
	v_pk_mul_f32 v[36:37], v[36:37], v[34:35]
	s_nop 0
	v_exp_f32_e32 v36, v36
	v_exp_f32_e32 v37, v37
	s_nop 0
	v_pk_add_f32 v[36:37], v[36:37], 1.0 op_sel_hi:[1,0]
	s_nop 0
	v_rcp_f32_e32 v36, v36
	v_rcp_f32_e32 v37, v37
	s_nop 0
	v_pk_mul_f32 v[34:35], v[36:37], v[34:35]
	s_nop 0
	v_pk_mul_f32 v[32:33], v[32:33], v[34:35]
	v_lshlrev_b32_e32 v34, 16, v31
	v_and_b32_e32 v35, 0xffff0000, v31
	v_pk_mul_f32 v[36:37], v[34:35], s[24:25] op_sel_hi:[1,0]
	s_nop 0
	v_exp_f32_e32 v36, v36
	v_exp_f32_e32 v37, v37
	s_nop 0
	v_pk_add_f32 v[36:37], v[36:37], 1.0 op_sel_hi:[1,0]
	s_nop 0
	v_rcp_f32_e32 v36, v36
	v_rcp_f32_e32 v37, v37
	s_nop 0
	v_pk_mul_f32 v[34:35], v[36:37], v[34:35]
	s_waitcnt vmcnt(8)
	v_lshlrev_b32_e32 v36, 16, v22
	v_and_b32_e32 v37, 0xffff0000, v22
	v_pk_mul_f32 v[38:39], v[36:37], v[36:37]
	v_pk_mul_f32 v[32:33], v[34:35], v[32:33]
	v_pk_fma_f32 v[38:39], v[38:39], s[18:19], v[40:41] op_sel_hi:[1,0,0] neg_lo:[1,0,0] neg_hi:[1,0,0]
	v_cvt_pk_bf16_f32 v31, v32, v33
	global_store_dwordx4 v[56:57], v[28:31], off
	v_pk_mul_f32 v[38:39], v[38:39], v[36:37]
	ds_read_b128 v[32:35], v61 offset:10880
	ds_read_b128 v[28:31], v61 offset:10896
	v_exp_f32_e32 v38, v38
	v_exp_f32_e32 v39, v39
	v_lshlrev_b32_e32 v22, 16, v23
	s_waitcnt vmcnt(7) lgkmcnt(1)
	v_pk_add_f32 v[32:33], v[54:55], v[32:33] op_sel_hi:[0,1]
	v_and_b32_e32 v23, 0xffff0000, v23
	v_pk_add_f32 v[38:39], v[38:39], 1.0 op_sel_hi:[1,0]
	s_nop 0
	v_rcp_f32_e32 v38, v38
	v_rcp_f32_e32 v39, v39
	s_nop 0
	v_pk_mul_f32 v[36:37], v[38:39], v[36:37]
	s_nop 0
	v_pk_mul_f32 v[32:33], v[32:33], v[36:37]
	v_lshlrev_b32_e32 v36, 16, v18
	v_and_b32_e32 v37, 0xffff0000, v18
	v_pk_mul_f32 v[38:39], v[36:37], s[24:25] op_sel_hi:[1,0]
	s_nop 0
	v_exp_f32_e32 v38, v38
	v_exp_f32_e32 v39, v39
	s_nop 0
	v_pk_add_f32 v[38:39], v[38:39], 1.0 op_sel_hi:[1,0]
	s_nop 0
	v_rcp_f32_e32 v38, v38
	v_rcp_f32_e32 v39, v39
	s_nop 0
	v_pk_mul_f32 v[36:37], v[38:39], v[36:37]
	s_nop 0
	v_pk_mul_f32 v[32:33], v[36:37], v[32:33]
	s_nop 0
	v_cvt_pk_bf16_f32 v18, v32, v33
	v_pk_add_f32 v[32:33], v[54:55], v[34:35] op_sel_hi:[0,1]
	v_pk_mul_f32 v[34:35], v[22:23], v[22:23]
	s_nop 0
	v_pk_fma_f32 v[34:35], v[34:35], s[18:19], v[40:41] op_sel_hi:[1,0,0] neg_lo:[1,0,0] neg_hi:[1,0,0]
	s_nop 0
	v_pk_mul_f32 v[34:35], v[34:35], v[22:23]
	s_nop 0
	v_exp_f32_e32 v34, v34
	v_exp_f32_e32 v35, v35
	s_nop 0
	v_pk_add_f32 v[34:35], v[34:35], 1.0 op_sel_hi:[1,0]
	s_nop 0
	v_rcp_f32_e32 v34, v34
	v_rcp_f32_e32 v35, v35
	s_nop 0
	v_pk_mul_f32 v[22:23], v[34:35], v[22:23]
	s_nop 0
	v_pk_mul_f32 v[22:23], v[32:33], v[22:23]
	v_lshlrev_b32_e32 v32, 16, v19
	v_and_b32_e32 v33, 0xffff0000, v19
	v_pk_mul_f32 v[34:35], v[32:33], s[24:25] op_sel_hi:[1,0]
	s_nop 0
	v_exp_f32_e32 v34, v34
	v_exp_f32_e32 v35, v35
	s_nop 0
	v_pk_add_f32 v[34:35], v[34:35], 1.0 op_sel_hi:[1,0]
	s_nop 0
	v_rcp_f32_e32 v34, v34
	v_rcp_f32_e32 v35, v35
	s_nop 0
	v_pk_mul_f32 v[32:33], v[34:35], v[32:33]
	s_nop 0
	v_pk_mul_f32 v[22:23], v[32:33], v[22:23]
	s_nop 0
	v_cvt_pk_bf16_f32 v19, v22, v23
	s_waitcnt lgkmcnt(0)
	v_pk_add_f32 v[22:23], v[54:55], v[28:29] op_sel_hi:[0,1]
	v_lshlrev_b32_e32 v28, 16, v24
	v_and_b32_e32 v29, 0xffff0000, v24
	v_pk_mul_f32 v[32:33], v[28:29], v[28:29]
	v_lshlrev_b32_e32 v24, 16, v25
	v_pk_fma_f32 v[32:33], v[32:33], s[18:19], v[40:41] op_sel_hi:[1,0,0] neg_lo:[1,0,0] neg_hi:[1,0,0]
	v_and_b32_e32 v25, 0xffff0000, v25
	v_pk_mul_f32 v[32:33], v[32:33], v[28:29]
	s_nop 0
	v_exp_f32_e32 v32, v32
	v_exp_f32_e32 v33, v33
	s_nop 0
	v_pk_add_f32 v[32:33], v[32:33], 1.0 op_sel_hi:[1,0]
	s_nop 0
	v_rcp_f32_e32 v32, v32
	v_rcp_f32_e32 v33, v33
	s_nop 0
	v_pk_mul_f32 v[28:29], v[32:33], v[28:29]
	s_nop 0
	v_pk_mul_f32 v[22:23], v[22:23], v[28:29]
	v_lshlrev_b32_e32 v28, 16, v20
	v_and_b32_e32 v29, 0xffff0000, v20
	v_pk_mul_f32 v[32:33], v[28:29], s[24:25] op_sel_hi:[1,0]
	s_nop 0
	v_exp_f32_e32 v32, v32
	v_exp_f32_e32 v33, v33
	s_nop 0
	v_pk_add_f32 v[32:33], v[32:33], 1.0 op_sel_hi:[1,0]
	s_nop 0
	v_rcp_f32_e32 v32, v32
	v_rcp_f32_e32 v33, v33
	s_nop 0
	v_pk_mul_f32 v[28:29], v[32:33], v[28:29]
	s_nop 0
	v_pk_mul_f32 v[22:23], v[28:29], v[22:23]
	v_pk_mul_f32 v[28:29], v[24:25], v[24:25]
	v_cvt_pk_bf16_f32 v20, v22, v23
	v_pk_add_f32 v[22:23], v[54:55], v[30:31] op_sel_hi:[0,1]
	v_pk_fma_f32 v[28:29], v[28:29], s[18:19], v[40:41] op_sel_hi:[1,0,0] neg_lo:[1,0,0] neg_hi:[1,0,0]
	s_nop 0
	v_pk_mul_f32 v[28:29], v[28:29], v[24:25]
	s_nop 0
	v_exp_f32_e32 v28, v28
	v_exp_f32_e32 v29, v29
	s_nop 0
	v_pk_add_f32 v[28:29], v[28:29], 1.0 op_sel_hi:[1,0]
	s_nop 0
	v_rcp_f32_e32 v28, v28
	v_rcp_f32_e32 v29, v29
	s_nop 0
	v_pk_mul_f32 v[24:25], v[28:29], v[24:25]
	s_nop 0
	v_pk_mul_f32 v[22:23], v[22:23], v[24:25]
	v_lshlrev_b32_e32 v24, 16, v21
	v_and_b32_e32 v25, 0xffff0000, v21
	v_pk_mul_f32 v[28:29], v[24:25], s[24:25] op_sel_hi:[1,0]
	s_nop 0
	v_exp_f32_e32 v28, v28
	v_exp_f32_e32 v29, v29
	s_nop 0
	v_pk_add_f32 v[28:29], v[28:29], 1.0 op_sel_hi:[1,0]
	s_nop 0
	v_rcp_f32_e32 v28, v28
	v_rcp_f32_e32 v29, v29
	s_nop 0
	v_pk_mul_f32 v[24:25], v[28:29], v[24:25]
	s_waitcnt vmcnt(6)
	v_lshlrev_b32_e32 v28, 16, v14
	v_and_b32_e32 v29, 0xffff0000, v14
	v_pk_mul_f32 v[30:31], v[28:29], v[28:29]
	v_pk_mul_f32 v[22:23], v[24:25], v[22:23]
	v_pk_fma_f32 v[30:31], v[30:31], s[18:19], v[40:41] op_sel_hi:[1,0,0] neg_lo:[1,0,0] neg_hi:[1,0,0]
	v_cvt_pk_bf16_f32 v21, v22, v23
	global_store_dwordx4 v[52:53], v[18:21], off
	v_pk_mul_f32 v[30:31], v[30:31], v[28:29]
	ds_read_b128 v[22:25], v61 offset:13056
	ds_read_b128 v[18:21], v61 offset:13072
	v_exp_f32_e32 v30, v30
	v_exp_f32_e32 v31, v31
	v_lshlrev_b32_e32 v14, 16, v15
	s_waitcnt vmcnt(5) lgkmcnt(1)
	v_pk_add_f32 v[22:23], v[50:51], v[22:23] op_sel_hi:[0,1]
	v_and_b32_e32 v15, 0xffff0000, v15
	v_pk_add_f32 v[30:31], v[30:31], 1.0 op_sel_hi:[1,0]
	s_nop 0
	v_rcp_f32_e32 v30, v30
	v_rcp_f32_e32 v31, v31
	s_nop 0
	v_pk_mul_f32 v[28:29], v[30:31], v[28:29]
	s_nop 0
	v_pk_mul_f32 v[22:23], v[28:29], v[22:23]
	v_lshlrev_b32_e32 v28, 16, v10
	v_and_b32_e32 v29, 0xffff0000, v10
	v_pk_mul_f32 v[30:31], v[28:29], s[24:25] op_sel_hi:[1,0]
	s_nop 0
	v_exp_f32_e32 v30, v30
	v_exp_f32_e32 v31, v31
	s_nop 0
	v_pk_add_f32 v[30:31], v[30:31], 1.0 op_sel_hi:[1,0]
	s_nop 0
	v_rcp_f32_e32 v30, v30
	v_rcp_f32_e32 v31, v31
	s_nop 0
	v_pk_mul_f32 v[28:29], v[30:31], v[28:29]
	s_nop 0
	v_pk_mul_f32 v[22:23], v[28:29], v[22:23]
	s_nop 0
	v_cvt_pk_bf16_f32 v10, v22, v23
	v_pk_add_f32 v[22:23], v[50:51], v[24:25] op_sel_hi:[0,1]
	v_pk_mul_f32 v[24:25], v[14:15], v[14:15]
	s_nop 0
	v_pk_fma_f32 v[24:25], v[24:25], s[18:19], v[40:41] op_sel_hi:[1,0,0] neg_lo:[1,0,0] neg_hi:[1,0,0]
	s_nop 0
	v_pk_mul_f32 v[24:25], v[24:25], v[14:15]
	s_nop 0
	v_exp_f32_e32 v24, v24
	v_exp_f32_e32 v25, v25
	s_nop 0
	v_pk_add_f32 v[24:25], v[24:25], 1.0 op_sel_hi:[1,0]
	s_nop 0
	v_rcp_f32_e32 v24, v24
	v_rcp_f32_e32 v25, v25
	s_nop 0
	v_pk_mul_f32 v[14:15], v[24:25], v[14:15]
	s_nop 0
	v_pk_mul_f32 v[14:15], v[14:15], v[22:23]
	v_lshlrev_b32_e32 v22, 16, v11
	v_and_b32_e32 v23, 0xffff0000, v11
	v_pk_mul_f32 v[24:25], v[22:23], s[24:25] op_sel_hi:[1,0]
	s_nop 0
	v_exp_f32_e32 v24, v24
	v_exp_f32_e32 v25, v25
	s_nop 0
	v_pk_add_f32 v[24:25], v[24:25], 1.0 op_sel_hi:[1,0]
	s_nop 0
	v_rcp_f32_e32 v24, v24
	v_rcp_f32_e32 v25, v25
	s_nop 0
	v_pk_mul_f32 v[22:23], v[24:25], v[22:23]
	s_nop 0
	v_pk_mul_f32 v[14:15], v[22:23], v[14:15]
	s_nop 0
	v_cvt_pk_bf16_f32 v11, v14, v15
	s_waitcnt lgkmcnt(0)
	v_pk_add_f32 v[14:15], v[50:51], v[18:19] op_sel_hi:[0,1]
	v_lshlrev_b32_e32 v18, 16, v16
	v_and_b32_e32 v19, 0xffff0000, v16
	v_pk_mul_f32 v[22:23], v[18:19], v[18:19]
	v_lshlrev_b32_e32 v16, 16, v17
	v_pk_fma_f32 v[22:23], v[22:23], s[18:19], v[40:41] op_sel_hi:[1,0,0] neg_lo:[1,0,0] neg_hi:[1,0,0]
	v_and_b32_e32 v17, 0xffff0000, v17
	v_pk_mul_f32 v[22:23], v[22:23], v[18:19]
	s_nop 0
	v_exp_f32_e32 v22, v22
	v_exp_f32_e32 v23, v23
	s_nop 0
	v_pk_add_f32 v[22:23], v[22:23], 1.0 op_sel_hi:[1,0]
	s_nop 0
	v_rcp_f32_e32 v22, v22
	v_rcp_f32_e32 v23, v23
	s_nop 0
	v_pk_mul_f32 v[18:19], v[22:23], v[18:19]
	s_nop 0
	v_pk_mul_f32 v[14:15], v[18:19], v[14:15]
	v_lshlrev_b32_e32 v18, 16, v12
	v_and_b32_e32 v19, 0xffff0000, v12
	v_pk_mul_f32 v[22:23], v[18:19], s[24:25] op_sel_hi:[1,0]
	s_nop 0
	v_exp_f32_e32 v22, v22
	v_exp_f32_e32 v23, v23
	s_nop 0
	v_pk_add_f32 v[22:23], v[22:23], 1.0 op_sel_hi:[1,0]
	s_nop 0
	v_rcp_f32_e32 v22, v22
	v_rcp_f32_e32 v23, v23
	s_nop 0
	v_pk_mul_f32 v[18:19], v[22:23], v[18:19]
	s_nop 0
	v_pk_mul_f32 v[14:15], v[18:19], v[14:15]
	v_pk_mul_f32 v[18:19], v[16:17], v[16:17]
	v_cvt_pk_bf16_f32 v12, v14, v15
	v_pk_add_f32 v[14:15], v[50:51], v[20:21] op_sel_hi:[0,1]
	v_pk_fma_f32 v[18:19], v[18:19], s[18:19], v[40:41] op_sel_hi:[1,0,0] neg_lo:[1,0,0] neg_hi:[1,0,0]
	s_nop 0
	v_pk_mul_f32 v[18:19], v[18:19], v[16:17]
	s_nop 0
	v_exp_f32_e32 v18, v18
	v_exp_f32_e32 v19, v19
	s_nop 0
	v_pk_add_f32 v[18:19], v[18:19], 1.0 op_sel_hi:[1,0]
	s_nop 0
	v_rcp_f32_e32 v18, v18
	v_rcp_f32_e32 v19, v19
	s_nop 0
	v_pk_mul_f32 v[16:17], v[18:19], v[16:17]
	s_nop 0
	v_pk_mul_f32 v[14:15], v[16:17], v[14:15]
	v_lshlrev_b32_e32 v16, 16, v13
	v_and_b32_e32 v17, 0xffff0000, v13
	v_pk_mul_f32 v[18:19], v[16:17], s[24:25] op_sel_hi:[1,0]
	s_nop 0
	v_exp_f32_e32 v18, v18
	v_exp_f32_e32 v19, v19
	s_nop 0
	v_pk_add_f32 v[18:19], v[18:19], 1.0 op_sel_hi:[1,0]
	s_nop 0
	v_rcp_f32_e32 v18, v18
	v_rcp_f32_e32 v19, v19
	s_nop 0
	v_pk_mul_f32 v[16:17], v[18:19], v[16:17]
	s_waitcnt vmcnt(4)
	v_lshlrev_b32_e32 v18, 16, v6
	v_and_b32_e32 v19, 0xffff0000, v6
	v_pk_mul_f32 v[20:21], v[18:19], v[18:19]
	v_pk_mul_f32 v[14:15], v[16:17], v[14:15]
	v_pk_fma_f32 v[20:21], v[20:21], s[18:19], v[40:41] op_sel_hi:[1,0,0] neg_lo:[1,0,0] neg_hi:[1,0,0]
	v_cvt_pk_bf16_f32 v13, v14, v15
	global_store_dwordx4 v[48:49], v[10:13], off
	v_pk_mul_f32 v[20:21], v[20:21], v[18:19]
	ds_read_b128 v[14:17], v61 offset:15232
	ds_read_b128 v[10:13], v61 offset:15248
	v_exp_f32_e32 v20, v20
	v_exp_f32_e32 v21, v21
	v_lshlrev_b32_e32 v6, 16, v7
	s_waitcnt vmcnt(3) lgkmcnt(1)
	v_pk_add_f32 v[14:15], v[42:43], v[14:15] op_sel_hi:[0,1]
	v_and_b32_e32 v7, 0xffff0000, v7
	v_pk_add_f32 v[20:21], v[20:21], 1.0 op_sel_hi:[1,0]
	s_nop 0
	v_rcp_f32_e32 v20, v20
	v_rcp_f32_e32 v21, v21
	s_nop 0
	v_pk_mul_f32 v[18:19], v[20:21], v[18:19]
	s_nop 0
	v_pk_mul_f32 v[14:15], v[18:19], v[14:15]
	v_lshlrev_b32_e32 v18, 16, v2
	v_and_b32_e32 v19, 0xffff0000, v2
	v_pk_mul_f32 v[20:21], v[18:19], s[24:25] op_sel_hi:[1,0]
	s_nop 0
	v_exp_f32_e32 v20, v20
	v_exp_f32_e32 v21, v21
	s_nop 0
	v_pk_add_f32 v[20:21], v[20:21], 1.0 op_sel_hi:[1,0]
	s_nop 0
	v_rcp_f32_e32 v20, v20
	v_rcp_f32_e32 v21, v21
	s_nop 0
	v_pk_mul_f32 v[18:19], v[20:21], v[18:19]
	s_nop 0
	v_pk_mul_f32 v[14:15], v[18:19], v[14:15]
	s_nop 0
	v_cvt_pk_bf16_f32 v2, v14, v15
	v_pk_add_f32 v[14:15], v[42:43], v[16:17] op_sel_hi:[0,1]
	v_pk_mul_f32 v[16:17], v[6:7], v[6:7]
	s_nop 0
	v_pk_fma_f32 v[16:17], v[16:17], s[18:19], v[40:41] op_sel_hi:[1,0,0] neg_lo:[1,0,0] neg_hi:[1,0,0]
	s_nop 0
	v_pk_mul_f32 v[16:17], v[16:17], v[6:7]
	s_nop 0
	v_exp_f32_e32 v16, v16
	v_exp_f32_e32 v17, v17
	s_nop 0
	v_pk_add_f32 v[16:17], v[16:17], 1.0 op_sel_hi:[1,0]
	s_nop 0
	v_rcp_f32_e32 v16, v16
	v_rcp_f32_e32 v17, v17
	s_nop 0
	v_pk_mul_f32 v[6:7], v[16:17], v[6:7]
	s_nop 0
	v_pk_mul_f32 v[6:7], v[6:7], v[14:15]
	v_lshlrev_b32_e32 v14, 16, v3
	v_and_b32_e32 v15, 0xffff0000, v3
	v_pk_mul_f32 v[16:17], v[14:15], s[24:25] op_sel_hi:[1,0]
	s_nop 0
	v_exp_f32_e32 v16, v16
	v_exp_f32_e32 v17, v17
	s_nop 0
	v_pk_add_f32 v[16:17], v[16:17], 1.0 op_sel_hi:[1,0]
	s_nop 0
	v_rcp_f32_e32 v16, v16
	v_rcp_f32_e32 v17, v17
	s_nop 0
	v_pk_mul_f32 v[14:15], v[16:17], v[14:15]
	s_nop 0
	v_pk_mul_f32 v[6:7], v[14:15], v[6:7]
	s_nop 0
	v_cvt_pk_bf16_f32 v3, v6, v7
	s_waitcnt lgkmcnt(0)
	v_pk_add_f32 v[6:7], v[42:43], v[10:11] op_sel_hi:[0,1]
	v_lshlrev_b32_e32 v10, 16, v8
	v_and_b32_e32 v11, 0xffff0000, v8
	v_pk_mul_f32 v[14:15], v[10:11], v[10:11]
	v_lshlrev_b32_e32 v8, 16, v9
	v_pk_fma_f32 v[14:15], v[14:15], s[18:19], v[40:41] op_sel_hi:[1,0,0] neg_lo:[1,0,0] neg_hi:[1,0,0]
	v_and_b32_e32 v9, 0xffff0000, v9
	v_pk_mul_f32 v[14:15], v[14:15], v[10:11]
	s_nop 0
	v_exp_f32_e32 v14, v14
	v_exp_f32_e32 v15, v15
	s_nop 0
	v_pk_add_f32 v[14:15], v[14:15], 1.0 op_sel_hi:[1,0]
	s_nop 0
	v_rcp_f32_e32 v14, v14
	v_rcp_f32_e32 v15, v15
	s_nop 0
	v_pk_mul_f32 v[10:11], v[14:15], v[10:11]
	s_nop 0
	v_pk_mul_f32 v[6:7], v[10:11], v[6:7]
	v_lshlrev_b32_e32 v10, 16, v4
	v_and_b32_e32 v11, 0xffff0000, v4
	v_pk_mul_f32 v[14:15], v[10:11], s[24:25] op_sel_hi:[1,0]
	s_nop 0
	v_exp_f32_e32 v14, v14
	v_exp_f32_e32 v15, v15
	s_nop 0
	v_pk_add_f32 v[14:15], v[14:15], 1.0 op_sel_hi:[1,0]
	s_nop 0
	v_rcp_f32_e32 v14, v14
	v_rcp_f32_e32 v15, v15
	s_nop 0
	v_pk_mul_f32 v[10:11], v[14:15], v[10:11]
	s_nop 0
	v_pk_mul_f32 v[6:7], v[10:11], v[6:7]
	v_pk_mul_f32 v[10:11], v[8:9], v[8:9]
	v_cvt_pk_bf16_f32 v4, v6, v7
	v_pk_add_f32 v[6:7], v[42:43], v[12:13] op_sel_hi:[0,1]
	v_pk_fma_f32 v[10:11], v[10:11], s[18:19], v[40:41] op_sel_hi:[1,0,0] neg_lo:[1,0,0] neg_hi:[1,0,0]
	s_nop 0
	v_pk_mul_f32 v[10:11], v[10:11], v[8:9]
	s_nop 0
	v_exp_f32_e32 v10, v10
	v_exp_f32_e32 v11, v11
	s_nop 0
	v_pk_add_f32 v[10:11], v[10:11], 1.0 op_sel_hi:[1,0]
	s_nop 0
	v_rcp_f32_e32 v10, v10
	v_rcp_f32_e32 v11, v11
	s_nop 0
	v_pk_mul_f32 v[8:9], v[10:11], v[8:9]
	s_nop 0
	v_pk_mul_f32 v[6:7], v[8:9], v[6:7]
	v_lshlrev_b32_e32 v8, 16, v5
	v_and_b32_e32 v9, 0xffff0000, v5
	v_pk_mul_f32 v[10:11], v[8:9], s[24:25] op_sel_hi:[1,0]
	s_nop 0
	v_exp_f32_e32 v10, v10
	v_exp_f32_e32 v11, v11
	s_nop 0
	v_pk_add_f32 v[10:11], v[10:11], 1.0 op_sel_hi:[1,0]
	s_nop 0
	v_rcp_f32_e32 v10, v10
	v_rcp_f32_e32 v11, v11
	s_nop 0
	v_pk_mul_f32 v[8:9], v[10:11], v[8:9]
	s_nop 0
	v_pk_mul_f32 v[6:7], v[8:9], v[6:7]
	s_nop 0
	v_cvt_pk_bf16_f32 v5, v6, v7
	global_store_dwordx4 v[46:47], v[2:5], off
	s_waitcnt lgkmcnt(0)
.LBB0_485:
	s_and_b64 vcc, exec, s[0:1]
	s_cbranch_vccz .LBB0_467
	s_lshl_b32 s68, s17, 13
	v_lshl_add_u64 v[2:3], v[76:77], 0, s[68:69]
	global_load_dwordx4 v[20:23], v[2:3], off offset:48
	global_load_dwordx4 v[28:31], v[2:3], off offset:32
	global_load_dwordx4 v[32:35], v[2:3], off offset:16
	global_load_dwordx4 v[36:39], v[2:3], off
	s_lshl_b32 s68, s16, 2
	v_lshl_add_u64 v[2:3], v[82:83], 0, s[68:69]
	global_load_dwordx4 v[4:7], v[2:3], off offset:16
	global_load_dwordx4 v[12:15], v[2:3], off
	v_lshl_add_u64 v[2:3], v[84:85], 0, s[68:69]
	global_load_dwordx4 v[8:11], v[2:3], off offset:16
	global_load_dwordx4 v[16:19], v[2:3], off
	s_mov_b32 s0, 0x3b000000
	s_lshl_b32 s68, s20, 15
	s_mov_b32 s8, 0
	v_lshl_add_u64 v[96:97], v[78:79], 0, s[68:69]
	s_mov_b64 s[98:99], 0x2000
	v_lshl_add_u64 v[246:247], v[96:97], 0, s[98:99]
	s_mov_b64 s[98:99], 0x3000
	v_lshl_add_u64 v[248:249], v[96:97], 0, s[98:99]
	global_load_dwordx4 v[230:233], v[96:97], off
	global_load_dwordx4 v[234:237], v[246:247], off offset:-4096
	global_load_dwordx4 v[238:241], v[246:247], off
	global_load_dwordx4 v[242:245], v[248:249], off
	s_waitcnt vmcnt(11)
	v_mov_b32_e32 v25, v22
	s_waitcnt vmcnt(10)
	v_mov_b32_e32 v24, v30
	s_waitcnt vmcnt(9)
	v_add_f32_e32 v3, v32, v34
	s_waitcnt vmcnt(8)
	v_add_f32_e32 v2, v36, v38
	v_add_f32_e32 v32, v2, v3
	v_mov_b32_e32 v2, v28
	v_mov_b32_e32 v3, v20
	v_pk_add_f32 v[2:3], v[2:3], v[24:25]
	v_add_f32_e32 v20, v33, v35
	v_add_f32_e32 v2, v32, v2
	v_add_f32_e32 v2, v2, v3
	v_add_f32_e32 v3, v37, v39
	v_add_f32_e32 v3, v3, v20
	v_add_f32_e32 v20, v29, v31
	v_add_f32_e32 v3, v3, v20
	v_add_f32_e32 v20, v21, v23
	v_add_f32_e32 v20, v3, v20
	v_mul_f32_e32 v3, 0x3b000000, v2
	v_mul_f32_e32 v2, v3, v3
	v_fma_f32 v20, v20, s0, -v2
	v_max_f32_e32 v20, 0, v20
	v_add_f32_e32 v20, 0x3727c5ac, v20
	v_rsq_f32_e32 v20, v20
	v_and_b32_e32 v21, 64, v224
	v_or_b32_e32 v22, v21, v114
	v_lshlrev_b32_e32 v22, 2, v22
	ds_bpermute_b32 v25, v22, v3
	ds_bpermute_b32 v28, v22, v20
	v_mov_b32_e32 v2, 0
	s_mov_b64 s[0:1], -1
	v_mov_b32_e32 v30, v2
	s_waitcnt lgkmcnt(1)
	v_sub_f32_e32 v22, v197, v25
	v_sub_f32_e32 v23, v196, v25
	s_waitcnt lgkmcnt(0)
	v_mul_f32_e32 v22, v22, v28
	v_mul_f32_e32 v23, v23, v28
	s_waitcnt vmcnt(4)
	v_fma_f32 v22, v12, v22, v16
	v_fma_f32 v23, v13, v23, v17
	v_cvt_pk_bf16_f32 v22, v22, v23
	v_sub_f32_e32 v23, v195, v25
	v_sub_f32_e32 v24, v194, v25
	v_mul_f32_e32 v23, v23, v28
	v_mul_f32_e32 v24, v24, v28
	v_fma_f32 v23, v14, v23, v18
	v_fma_f32 v24, v15, v24, v19
	v_cvt_pk_bf16_f32 v23, v23, v24
	v_sub_f32_e32 v24, v193, v25
	v_sub_f32_e32 v29, v192, v25
	v_mul_f32_e32 v24, v24, v28
	v_mul_f32_e32 v29, v29, v28
	v_fma_f32 v24, v4, v24, v8
	v_fma_f32 v29, v5, v29, v9
	v_cvt_pk_bf16_f32 v24, v24, v29
	v_sub_f32_e32 v29, v191, v25
	v_sub_f32_e32 v25, v190, v25
	v_mul_f32_e32 v25, v25, v28
	v_mul_f32_e32 v29, v29, v28
	v_fma_f32 v25, v7, v25, v11
	v_fma_f32 v29, v6, v29, v10
	v_cvt_pk_bf16_f32 v25, v29, v25
	ds_write2_b64 v135, v[22:23], v[24:25] offset1:1
	v_or_b32_e32 v22, v21, v115
	v_lshlrev_b32_e32 v22, 2, v22
	ds_bpermute_b32 v25, v22, v3
	ds_bpermute_b32 v28, v22, v20
	v_mov_b32_e32 v31, v2
	v_mov_b32_e32 v36, v2
	v_mov_b32_e32 v37, v2
	s_waitcnt lgkmcnt(1)
	v_sub_f32_e32 v22, v189, v25
	v_sub_f32_e32 v23, v188, v25
	s_waitcnt lgkmcnt(0)
	v_mul_f32_e32 v22, v22, v28
	v_mul_f32_e32 v23, v23, v28
	v_fma_f32 v22, v12, v22, v16
	v_fma_f32 v23, v13, v23, v17
	v_cvt_pk_bf16_f32 v22, v22, v23
	v_sub_f32_e32 v23, v187, v25
	v_sub_f32_e32 v24, v186, v25
	v_mul_f32_e32 v23, v23, v28
	v_mul_f32_e32 v24, v24, v28
	v_fma_f32 v23, v14, v23, v18
	v_fma_f32 v24, v15, v24, v19
	v_cvt_pk_bf16_f32 v23, v23, v24
	v_sub_f32_e32 v24, v185, v25
	v_sub_f32_e32 v29, v184, v25
	v_mul_f32_e32 v24, v24, v28
	v_mul_f32_e32 v29, v29, v28
	v_fma_f32 v24, v4, v24, v8
	v_fma_f32 v29, v5, v29, v9
	v_cvt_pk_bf16_f32 v24, v24, v29
	v_sub_f32_e32 v29, v183, v25
	v_sub_f32_e32 v25, v182, v25
	v_mul_f32_e32 v25, v25, v28
	v_mul_f32_e32 v29, v29, v28
	v_fma_f32 v25, v7, v25, v11
	v_fma_f32 v29, v6, v29, v10
	v_cvt_pk_bf16_f32 v25, v29, v25
	ds_write2_b64 v135, v[22:23], v[24:25] offset0:136 offset1:137
	v_or_b32_e32 v22, v21, v116
	v_lshlrev_b32_e32 v22, 2, v22
	ds_bpermute_b32 v25, v22, v3
	ds_bpermute_b32 v28, v22, v20
	v_mov_b32_e32 v38, v2
	v_mov_b32_e32 v39, v2
	v_mov_b32_e32 v32, v2
	s_waitcnt lgkmcnt(1)
	v_sub_f32_e32 v22, v181, v25
	v_sub_f32_e32 v23, v180, v25
	s_waitcnt lgkmcnt(0)
	v_mul_f32_e32 v22, v22, v28
	v_mul_f32_e32 v23, v23, v28
	v_fma_f32 v22, v12, v22, v16
	v_fma_f32 v23, v13, v23, v17
	v_cvt_pk_bf16_f32 v22, v22, v23
	v_sub_f32_e32 v23, v179, v25
	v_sub_f32_e32 v24, v178, v25
	v_mul_f32_e32 v23, v23, v28
	v_mul_f32_e32 v24, v24, v28
	v_fma_f32 v23, v14, v23, v18
	v_fma_f32 v24, v15, v24, v19
	v_cvt_pk_bf16_f32 v23, v23, v24
	v_sub_f32_e32 v24, v177, v25
	v_sub_f32_e32 v29, v176, v25
	v_mul_f32_e32 v24, v24, v28
	v_mul_f32_e32 v29, v29, v28
	v_fma_f32 v24, v4, v24, v8
	v_fma_f32 v29, v5, v29, v9
	v_cvt_pk_bf16_f32 v24, v24, v29
	v_sub_f32_e32 v29, v167, v25
	v_sub_f32_e32 v25, v166, v25
	v_mul_f32_e32 v25, v25, v28
	v_mul_f32_e32 v29, v29, v28
	v_fma_f32 v25, v7, v25, v11
	v_fma_f32 v29, v6, v29, v10
	v_cvt_pk_bf16_f32 v25, v29, v25
	ds_write2_b64 v162, v[22:23], v[24:25] offset1:1
	v_or_b32_e32 v22, v21, v117
	v_lshlrev_b32_e32 v22, 2, v22
	ds_bpermute_b32 v25, v22, v3
	ds_bpermute_b32 v28, v22, v20
	v_mov_b32_e32 v33, v2
	v_mov_b32_e32 v34, v2
	v_mov_b32_e32 v35, v2
	s_waitcnt lgkmcnt(1)
	v_sub_f32_e32 v22, v165, v25
	v_sub_f32_e32 v23, v164, v25
	s_waitcnt lgkmcnt(0)
	v_mul_f32_e32 v22, v22, v28
	v_mul_f32_e32 v23, v23, v28
	v_fma_f32 v22, v12, v22, v16
	v_fma_f32 v23, v13, v23, v17
	v_cvt_pk_bf16_f32 v22, v22, v23
	v_sub_f32_e32 v23, v163, v25
	v_sub_f32_e32 v24, v161, v25
	v_mul_f32_e32 v23, v23, v28
	v_mul_f32_e32 v24, v24, v28
	v_fma_f32 v23, v14, v23, v18
	v_fma_f32 v24, v15, v24, v19
	v_cvt_pk_bf16_f32 v23, v23, v24
	v_sub_f32_e32 v24, v160, v25
	v_sub_f32_e32 v29, v159, v25
	v_mul_f32_e32 v24, v24, v28
	v_mul_f32_e32 v29, v29, v28
	v_fma_f32 v24, v4, v24, v8
	v_fma_f32 v29, v5, v29, v9
	v_cvt_pk_bf16_f32 v24, v24, v29
	v_sub_f32_e32 v29, v158, v25
	v_sub_f32_e32 v25, v157, v25
	v_mul_f32_e32 v25, v25, v28
	v_mul_f32_e32 v29, v29, v28
	v_fma_f32 v25, v7, v25, v11
	v_fma_f32 v29, v6, v29, v10
	v_cvt_pk_bf16_f32 v25, v29, v25
	ds_write2_b64 v154, v[22:23], v[24:25] offset1:1
	v_or_b32_e32 v22, v21, v118
	v_lshlrev_b32_e32 v22, 2, v22
	ds_bpermute_b32 v25, v22, v3
	ds_bpermute_b32 v28, v22, v20
	v_mov_b32_e32 v40, v2
	v_mov_b32_e32 v41, v2
	v_mov_b32_e32 v42, v2
	s_waitcnt lgkmcnt(1)
	v_sub_f32_e32 v22, v156, v25
	v_sub_f32_e32 v23, v155, v25
	s_waitcnt lgkmcnt(0)
	v_mul_f32_e32 v22, v22, v28
	v_mul_f32_e32 v23, v23, v28
	v_fma_f32 v22, v12, v22, v16
	v_fma_f32 v23, v13, v23, v17
	v_cvt_pk_bf16_f32 v22, v22, v23
	v_sub_f32_e32 v23, v153, v25
	v_sub_f32_e32 v24, v152, v25
	v_mul_f32_e32 v23, v23, v28
	v_mul_f32_e32 v24, v24, v28
	v_fma_f32 v23, v14, v23, v18
	v_fma_f32 v24, v15, v24, v19
	v_cvt_pk_bf16_f32 v23, v23, v24
	v_sub_f32_e32 v24, v151, v25
	v_sub_f32_e32 v29, v150, v25
	v_mul_f32_e32 v24, v24, v28
	v_mul_f32_e32 v29, v29, v28
	v_fma_f32 v24, v4, v24, v8
	v_fma_f32 v29, v5, v29, v9
	v_cvt_pk_bf16_f32 v24, v24, v29
	v_sub_f32_e32 v29, v149, v25
	v_sub_f32_e32 v25, v148, v25
	v_mul_f32_e32 v25, v25, v28
	v_mul_f32_e32 v29, v29, v28
	v_fma_f32 v25, v7, v25, v11
	v_fma_f32 v29, v6, v29, v10
	v_cvt_pk_bf16_f32 v25, v29, v25
	ds_write2_b64 v147, v[22:23], v[24:25] offset1:1
	v_or_b32_e32 v22, v21, v119
	v_lshlrev_b32_e32 v22, 2, v22
	ds_bpermute_b32 v25, v22, v3
	ds_bpermute_b32 v28, v22, v20
	v_mov_b32_e32 v43, v2
	v_mov_b32_e32 v44, v2
	v_mov_b32_e32 v45, v2
	s_waitcnt lgkmcnt(1)
	v_sub_f32_e32 v22, v146, v25
	v_sub_f32_e32 v23, v145, v25
	s_waitcnt lgkmcnt(0)
	v_mul_f32_e32 v22, v22, v28
	v_mul_f32_e32 v23, v23, v28
	v_fma_f32 v22, v12, v22, v16
	v_fma_f32 v23, v13, v23, v17
	v_cvt_pk_bf16_f32 v22, v22, v23
	v_sub_f32_e32 v23, v144, v25
	v_sub_f32_e32 v24, v143, v25
	v_mul_f32_e32 v23, v23, v28
	v_mul_f32_e32 v24, v24, v28
	v_fma_f32 v23, v14, v23, v18
	v_fma_f32 v24, v15, v24, v19
	v_cvt_pk_bf16_f32 v23, v23, v24
	v_sub_f32_e32 v24, v142, v25
	v_sub_f32_e32 v29, v141, v25
	v_mul_f32_e32 v24, v24, v28
	v_mul_f32_e32 v29, v29, v28
	v_fma_f32 v24, v4, v24, v8
	v_fma_f32 v29, v5, v29, v9
	v_cvt_pk_bf16_f32 v24, v24, v29
	v_sub_f32_e32 v29, v140, v25
	v_sub_f32_e32 v25, v139, v25
	v_mul_f32_e32 v25, v25, v28
	v_mul_f32_e32 v29, v29, v28
	v_fma_f32 v25, v7, v25, v11
	v_fma_f32 v29, v6, v29, v10
	v_cvt_pk_bf16_f32 v25, v29, v25
	ds_write2_b64 v138, v[22:23], v[24:25] offset1:1
	v_or_b32_e32 v22, v21, v120
	v_lshlrev_b32_e32 v22, 2, v22
	ds_bpermute_b32 v25, v22, v3
	ds_bpermute_b32 v28, v22, v20
	v_or_b32_e32 v21, v21, v121
	v_lshlrev_b32_e32 v21, 2, v21
	ds_bpermute_b32 v3, v21, v3
	s_waitcnt lgkmcnt(2)
	v_sub_f32_e32 v22, v137, v25
	v_sub_f32_e32 v23, v136, v25
	s_waitcnt lgkmcnt(1)
	v_mul_f32_e32 v22, v22, v28
	v_mul_f32_e32 v23, v23, v28
	v_fma_f32 v22, v12, v22, v16
	v_fma_f32 v23, v13, v23, v17
	v_cvt_pk_bf16_f32 v22, v22, v23
	v_sub_f32_e32 v23, v113, v25
	v_sub_f32_e32 v24, v112, v25
	ds_bpermute_b32 v20, v21, v20
	v_mul_f32_e32 v23, v23, v28
	v_mul_f32_e32 v24, v24, v28
	v_fma_f32 v23, v14, v23, v18
	v_fma_f32 v24, v15, v24, v19
	v_cvt_pk_bf16_f32 v23, v23, v24
	v_sub_f32_e32 v24, v111, v25
	v_sub_f32_e32 v29, v110, v25
	v_mul_f32_e32 v24, v24, v28
	v_mul_f32_e32 v29, v29, v28
	s_waitcnt lgkmcnt(1)
	v_sub_f32_e32 v21, v106, v3
	v_fma_f32 v24, v4, v24, v8
	v_fma_f32 v29, v5, v29, v9
	s_waitcnt lgkmcnt(0)
	v_mul_f32_e32 v21, v21, v20
	v_cvt_pk_bf16_f32 v24, v24, v29
	v_sub_f32_e32 v29, v109, v25
	v_sub_f32_e32 v25, v108, v25
	v_fma_f32 v12, v12, v21, v16
	v_sub_f32_e32 v16, v105, v3
	v_mul_f32_e32 v25, v25, v28
	v_mul_f32_e32 v16, v16, v20
	v_mul_f32_e32 v29, v29, v28
	v_fma_f32 v25, v7, v25, v11
	v_fma_f32 v13, v13, v16, v17
	v_fma_f32 v29, v6, v29, v10
	v_cvt_pk_bf16_f32 v25, v29, v25
	ds_write2_b64 v107, v[22:23], v[24:25] offset1:1
	v_cvt_pk_bf16_f32 v12, v12, v13
	v_sub_f32_e32 v13, v104, v3
	v_mul_f32_e32 v13, v13, v20
	v_fma_f32 v13, v14, v13, v18
	v_sub_f32_e32 v14, v103, v3
	v_mul_f32_e32 v14, v14, v20
	v_fmac_f32_e32 v19, v15, v14
	v_sub_f32_e32 v14, v102, v3
	v_mul_f32_e32 v14, v14, v20
	v_fma_f32 v4, v4, v14, v8
	v_sub_f32_e32 v8, v101, v3
	v_mul_f32_e32 v8, v8, v20
	v_fma_f32 v5, v5, v8, v9
	v_cvt_pk_bf16_f32 v13, v13, v19
	v_cvt_pk_bf16_f32 v4, v4, v5
	v_sub_f32_e32 v5, v100, v3
	v_mul_f32_e32 v5, v5, v20
	v_sub_f32_e32 v3, v99, v3
	v_fma_f32 v5, v6, v5, v10
	v_mul_f32_e32 v3, v3, v20
	v_fmac_f32_e32 v11, v7, v3
	v_cvt_pk_bf16_f32 v5, v5, v11
	ds_write2_b64 v98, v[12:13], v[4:5] offset1:1
	s_waitcnt lgkmcnt(0)
	v_mov_b32_e32 v3, v2
	v_mov_b32_e32 v4, v2
	v_mov_b32_e32 v5, v2
	v_mov_b32_e32 v6, v2
	v_mov_b32_e32 v7, v2
	v_mov_b32_e32 v8, v2
	v_mov_b32_e32 v9, v2
	v_mov_b32_e32 v10, v2
	v_mov_b32_e32 v11, v2
	v_mov_b32_e32 v12, v2
	v_mov_b32_e32 v13, v2
	v_mov_b32_e32 v18, v2
	v_mov_b32_e32 v19, v2
	v_mov_b32_e32 v20, v2
	v_mov_b32_e32 v21, v2
	v_mov_b32_e32 v14, v2
	v_mov_b32_e32 v15, v2
	v_mov_b32_e32 v16, v2
	v_mov_b32_e32 v17, v2
	v_mov_b32_e32 v22, v2
	v_mov_b32_e32 v23, v2
	v_mov_b32_e32 v24, v2
	v_mov_b32_e32 v25, v2
	v_mov_b32_e32 v28, v2
	v_mov_b32_e32 v29, v2
	v_mov_b32_e32 v46, v2
	v_mov_b32_e32 v47, v2
	v_mov_b32_e32 v48, v2
	v_mov_b32_e32 v49, v2
	v_mov_b32_e32 v50, v2
	v_mov_b32_e32 v51, v2
	v_mov_b32_e32 v52, v2
	v_mov_b32_e32 v53, v2
	v_mov_b32_e32 v54, v2
	v_mov_b32_e32 v55, v2
	v_mov_b32_e32 v56, v2
	v_mov_b32_e32 v57, v2
	v_mov_b32_e32 v58, v2
	v_mov_b32_e32 v59, v2
	v_mov_b32_e32 v60, v2
	v_mov_b32_e32 v61, v2
	v_mov_b32_e32 v62, v2
	v_mov_b32_e32 v63, v2
	v_mov_b32_e32 v64, v2
	v_mov_b32_e32 v65, v2
	v_mov_b32_e32 v66, v2
	v_mov_b32_e32 v67, v2
.LBB0_487:
	ds_read_b64_tr_b16 v[104:105], v129 offset:544
	ds_read_b64_tr_b16 v[102:103], v129
	ds_read_b64_tr_b16 v[108:109], v129 offset:576
	ds_read_b64_tr_b16 v[106:107], v129 offset:32
	ds_read_b64_tr_b16 v[110:111], v129 offset:64
	ds_read_b64_tr_b16 v[136:137], v129 offset:96
	ds_read_b64_tr_b16 v[112:113], v129 offset:608
	ds_read_b64_tr_b16 v[138:139], v129 offset:640
	s_waitcnt vmcnt(3) lgkmcnt(6)
	v_mfma_f32_16x16x32_bf16 v[48:51], v[102:105], v[230:233], v[48:51]
	s_waitcnt lgkmcnt(4)
	v_mfma_f32_16x16x32_bf16 v[36:39], v[106:109], v[230:233], v[36:39]
	s_waitcnt lgkmcnt(1)
	v_mfma_f32_16x16x32_bf16 v[18:21], v[110:113], v[230:233], v[18:21]
	s_waitcnt lgkmcnt(0)
	v_mfma_f32_16x16x32_bf16 v[52:55], v[136:139], v[230:233], v[52:55]
	global_load_dwordx4 v[230:233], v[96:97], off offset:64
	s_waitcnt vmcnt(3)
	v_mfma_f32_16x16x32_bf16 v[44:47], v[102:105], v[234:237], v[44:47]
	v_mfma_f32_16x16x32_bf16 v[28:31], v[106:109], v[234:237], v[28:31]
	v_mfma_f32_16x16x32_bf16 v[10:13], v[110:113], v[234:237], v[10:13]
	v_mfma_f32_16x16x32_bf16 v[56:59], v[136:139], v[234:237], v[56:59]
	global_load_dwordx4 v[234:237], v[246:247], off offset:-4032
	s_waitcnt vmcnt(3)
	v_mfma_f32_16x16x32_bf16 v[40:43], v[102:105], v[238:241], v[40:43]
	v_mfma_f32_16x16x32_bf16 v[22:25], v[106:109], v[238:241], v[22:25]
	v_mfma_f32_16x16x32_bf16 v[6:9], v[110:113], v[238:241], v[6:9]
	v_mfma_f32_16x16x32_bf16 v[60:63], v[136:139], v[238:241], v[60:63]
	global_load_dwordx4 v[238:241], v[246:247], off offset:64
	s_waitcnt vmcnt(3)
	v_mfma_f32_16x16x32_bf16 v[32:35], v[102:105], v[242:245], v[32:35]
	v_mfma_f32_16x16x32_bf16 v[14:17], v[106:109], v[242:245], v[14:17]
	v_mfma_f32_16x16x32_bf16 v[2:5], v[110:113], v[242:245], v[2:5]
	v_mfma_f32_16x16x32_bf16 v[64:67], v[136:139], v[242:245], v[64:67]
	global_load_dwordx4 v[242:245], v[248:249], off offset:64
	ds_read_b64_tr_b16 v[104:105], v129 offset:4896
	ds_read_b64_tr_b16 v[102:103], v129 offset:4352
	ds_read_b64_tr_b16 v[108:109], v129 offset:4928
	ds_read_b64_tr_b16 v[106:107], v129 offset:4384
	ds_read_b64_tr_b16 v[110:111], v129 offset:4416
	ds_read_b64_tr_b16 v[136:137], v129 offset:4448
	ds_read_b64_tr_b16 v[112:113], v129 offset:4960
	ds_read_b64_tr_b16 v[138:139], v129 offset:4992
	s_waitcnt vmcnt(3) lgkmcnt(6)
	v_mfma_f32_16x16x32_bf16 v[48:51], v[102:105], v[230:233], v[48:51]
	s_waitcnt lgkmcnt(4)
	v_mfma_f32_16x16x32_bf16 v[36:39], v[106:109], v[230:233], v[36:39]
	s_waitcnt lgkmcnt(1)
	v_mfma_f32_16x16x32_bf16 v[18:21], v[110:113], v[230:233], v[18:21]
	s_waitcnt lgkmcnt(0)
	v_mfma_f32_16x16x32_bf16 v[52:55], v[136:139], v[230:233], v[52:55]
	s_waitcnt vmcnt(2)
	v_mfma_f32_16x16x32_bf16 v[44:47], v[102:105], v[234:237], v[44:47]
	v_mfma_f32_16x16x32_bf16 v[28:31], v[106:109], v[234:237], v[28:31]
	v_mfma_f32_16x16x32_bf16 v[10:13], v[110:113], v[234:237], v[10:13]
	v_mfma_f32_16x16x32_bf16 v[56:59], v[136:139], v[234:237], v[56:59]
	s_waitcnt vmcnt(1)
	v_mfma_f32_16x16x32_bf16 v[40:43], v[102:105], v[238:241], v[40:43]
	v_mfma_f32_16x16x32_bf16 v[22:25], v[106:109], v[238:241], v[22:25]
	v_mfma_f32_16x16x32_bf16 v[6:9], v[110:113], v[238:241], v[6:9]
	v_mfma_f32_16x16x32_bf16 v[60:63], v[136:139], v[238:241], v[60:63]
	s_waitcnt vmcnt(0)
	v_mfma_f32_16x16x32_bf16 v[32:35], v[102:105], v[242:245], v[32:35]
	v_mfma_f32_16x16x32_bf16 v[14:17], v[106:109], v[242:245], v[14:17]
	v_mfma_f32_16x16x32_bf16 v[2:5], v[110:113], v[242:245], v[2:5]
	v_mfma_f32_16x16x32_bf16 v[64:67], v[136:139], v[242:245], v[64:67]
	s_mov_b32 s8, 1
	s_mov_b64 s[0:1], 0
	s_mov_b64 vcc, 0
	s_waitcnt lgkmcnt(0)
	v_add_u32_e32 v96, v130, v131
	ds_write_b128 v96, v[48:51]
	ds_write_b128 v96, v[36:39] offset:64
	ds_write_b128 v96, v[18:21] offset:128
	ds_write_b128 v96, v[52:55] offset:192
	ds_write_b128 v96, v[44:47] offset:4352
	ds_write_b128 v96, v[28:31] offset:4416
	ds_write_b128 v96, v[10:13] offset:4480
	ds_write_b128 v96, v[56:59] offset:4544
	ds_write_b128 v96, v[40:43] offset:8704
	ds_write_b128 v96, v[22:25] offset:8768
	ds_write_b128 v96, v[6:9] offset:8832
	ds_write_b128 v96, v[60:63] offset:8896
	ds_write_b128 v96, v[32:35] offset:13056
	ds_write_b128 v96, v[14:17] offset:13120
	ds_write_b128 v96, v[2:5] offset:13184
	ds_write_b128 v96, v[64:67] offset:13248
	s_waitcnt lgkmcnt(0)
	global_load_dwordx4 v[32:35], v[88:89], off
	v_add_co_u32_e32 v2, vcc, s10, v88
	s_lshl_b32 s68, s20, 9
	s_nop 0
	v_addc_co_u32_e32 v3, vcc, 0, v89, vcc
	v_lshl_add_u64 v[42:43], v[80:81], 0, s[68:69]
	global_load_dwordx4 v[28:31], v[2:3], off
	global_load_dword v52, v[42:43], off
	s_mov_b32 s0, 0x17000
	v_add_co_u32_e32 v2, vcc, s0, v88
	v_mov_b64_e32 v[40:41], s[42:43]
	s_nop 0
	v_addc_co_u32_e32 v3, vcc, 0, v89, vcc
	s_mov_b32 s0, 0x2d000
	global_load_dwordx4 v[22:25], v[2:3], off offset:-4096
	global_load_dwordx4 v[18:21], v[2:3], off
	global_load_dword v50, v[42:43], off offset:32
	v_add_co_u32_e32 v2, vcc, s0, v88
	s_mov_b32 s0, 0x42000
	s_nop 0
	v_addc_co_u32_e32 v3, vcc, 0, v89, vcc
	v_add_co_u32_e32 v44, vcc, s0, v88
	s_mov_b32 s0, 0x43000
	s_nop 0
	v_addc_co_u32_e32 v45, vcc, 0, v89, vcc
	global_load_dwordx4 v[14:17], v[2:3], off offset:-4096
	global_load_dwordx4 v[10:13], v[2:3], off
	global_load_dword v48, v[42:43], off offset:64
	v_add_co_u32_e32 v2, vcc, s0, v88
	v_add_u32_e32 v47, v132, v133
	s_nop 0
	v_addc_co_u32_e32 v3, vcc, 0, v89, vcc
	global_load_dwordx4 v[6:9], v[2:3], off offset:-4096
	s_nop 0
	global_load_dwordx4 v[2:5], v[2:3], off
	s_nop 0
	global_load_dword v46, v[42:43], off offset:96
	ds_read_b128 v[54:57], v47
	ds_read_b128 v[36:39], v47 offset:16
	s_mov_b32 s0, 0x59000
	s_waitcnt vmcnt(11)
	v_lshlrev_b32_e32 v58, 16, v32
	v_and_b32_e32 v59, 0xffff0000, v32
	v_pk_mul_f32 v[60:61], v[58:59], v[58:59]
	v_lshlrev_b32_e32 v32, 16, v33
	v_pk_fma_f32 v[60:61], v[60:61], s[18:19], v[40:41] op_sel_hi:[1,0,0] neg_lo:[1,0,0] neg_hi:[1,0,0]
	v_and_b32_e32 v33, 0xffff0000, v33
	v_pk_mul_f32 v[60:61], v[60:61], v[58:59]
	s_waitcnt vmcnt(9) lgkmcnt(1)
	v_pk_add_f32 v[54:55], v[52:53], v[54:55] op_sel_hi:[0,1]
	v_exp_f32_e32 v60, v60
	v_exp_f32_e32 v61, v61
	s_nop 0
	v_pk_add_f32 v[60:61], v[60:61], 1.0 op_sel_hi:[1,0]
	s_nop 0
	v_rcp_f32_e32 v60, v60
	v_rcp_f32_e32 v61, v61
	s_nop 0
	v_pk_mul_f32 v[58:59], v[60:61], v[58:59]
	s_nop 0
	v_pk_mul_f32 v[54:55], v[54:55], v[58:59]
	v_lshlrev_b32_e32 v58, 16, v28
	v_and_b32_e32 v59, 0xffff0000, v28
	v_pk_mul_f32 v[60:61], v[58:59], s[24:25] op_sel_hi:[1,0]
	s_nop 0
	v_exp_f32_e32 v60, v60
	v_exp_f32_e32 v61, v61
	s_nop 0
	v_pk_add_f32 v[60:61], v[60:61], 1.0 op_sel_hi:[1,0]
	s_nop 0
	v_rcp_f32_e32 v60, v60
	v_rcp_f32_e32 v61, v61
	s_nop 0
	v_pk_mul_f32 v[58:59], v[60:61], v[58:59]
	s_nop 0
	v_pk_mul_f32 v[54:55], v[58:59], v[54:55]
	s_nop 0
	v_cvt_pk_bf16_f32 v28, v54, v55
	v_pk_add_f32 v[54:55], v[52:53], v[56:57] op_sel_hi:[0,1]
	v_pk_mul_f32 v[56:57], v[32:33], v[32:33]
	s_nop 0
	v_pk_fma_f32 v[56:57], v[56:57], s[18:19], v[40:41] op_sel_hi:[1,0,0] neg_lo:[1,0,0] neg_hi:[1,0,0]
	s_nop 0
	v_pk_mul_f32 v[56:57], v[56:57], v[32:33]
	s_nop 0
	v_exp_f32_e32 v56, v56
	v_exp_f32_e32 v57, v57
	s_nop 0
	v_pk_add_f32 v[56:57], v[56:57], 1.0 op_sel_hi:[1,0]
	s_nop 0
	v_rcp_f32_e32 v56, v56
	v_rcp_f32_e32 v57, v57
	s_nop 0
	v_pk_mul_f32 v[32:33], v[56:57], v[32:33]
	s_nop 0
	v_pk_mul_f32 v[32:33], v[54:55], v[32:33]
	v_lshlrev_b32_e32 v54, 16, v29
	v_and_b32_e32 v55, 0xffff0000, v29
	v_pk_mul_f32 v[56:57], v[54:55], s[24:25] op_sel_hi:[1,0]
	s_nop 0
	v_exp_f32_e32 v56, v56
	v_exp_f32_e32 v57, v57
	s_nop 0
	v_pk_add_f32 v[56:57], v[56:57], 1.0 op_sel_hi:[1,0]
	s_nop 0
	v_rcp_f32_e32 v56, v56
	v_rcp_f32_e32 v57, v57
	s_nop 0
	v_pk_mul_f32 v[54:55], v[56:57], v[54:55]
	s_nop 0
	v_pk_mul_f32 v[32:33], v[54:55], v[32:33]
	s_nop 0
	v_cvt_pk_bf16_f32 v29, v32, v33
	s_waitcnt lgkmcnt(0)
	v_pk_add_f32 v[32:33], v[52:53], v[36:37] op_sel_hi:[0,1]
	v_lshlrev_b32_e32 v36, 16, v34
	v_and_b32_e32 v37, 0xffff0000, v34
	v_pk_mul_f32 v[54:55], v[36:37], v[36:37]
	v_lshlrev_b32_e32 v34, 16, v35
	v_pk_fma_f32 v[54:55], v[54:55], s[18:19], v[40:41] op_sel_hi:[1,0,0] neg_lo:[1,0,0] neg_hi:[1,0,0]
	v_and_b32_e32 v35, 0xffff0000, v35
	v_pk_mul_f32 v[54:55], v[54:55], v[36:37]
	s_nop 0
	v_exp_f32_e32 v54, v54
	v_exp_f32_e32 v55, v55
	s_nop 0
	v_pk_add_f32 v[54:55], v[54:55], 1.0 op_sel_hi:[1,0]
	s_nop 0
	v_rcp_f32_e32 v54, v54
	v_rcp_f32_e32 v55, v55
	s_nop 0
	v_pk_mul_f32 v[36:37], v[54:55], v[36:37]
	s_nop 0
	v_pk_mul_f32 v[32:33], v[32:33], v[36:37]
	v_lshlrev_b32_e32 v36, 16, v30
	v_and_b32_e32 v37, 0xffff0000, v30
	v_pk_mul_f32 v[54:55], v[36:37], s[24:25] op_sel_hi:[1,0]
	s_nop 0
	v_exp_f32_e32 v54, v54
	v_exp_f32_e32 v55, v55
	s_nop 0
	v_pk_add_f32 v[54:55], v[54:55], 1.0 op_sel_hi:[1,0]
	s_nop 0
	v_rcp_f32_e32 v54, v54
	v_rcp_f32_e32 v55, v55
	s_nop 0
	v_pk_mul_f32 v[36:37], v[54:55], v[36:37]
	s_nop 0
	v_pk_mul_f32 v[32:33], v[36:37], v[32:33]
	v_pk_mul_f32 v[36:37], v[34:35], v[34:35]
	v_cvt_pk_bf16_f32 v30, v32, v33
	v_pk_add_f32 v[32:33], v[52:53], v[38:39] op_sel_hi:[0,1]
	v_pk_fma_f32 v[36:37], v[36:37], s[18:19], v[40:41] op_sel_hi:[1,0,0] neg_lo:[1,0,0] neg_hi:[1,0,0]
	s_nop 0
	v_pk_mul_f32 v[36:37], v[36:37], v[34:35]
	s_nop 0
	v_exp_f32_e32 v36, v36
	v_exp_f32_e32 v37, v37
	s_nop 0
	v_pk_add_f32 v[36:37], v[36:37], 1.0 op_sel_hi:[1,0]
	s_nop 0
	v_rcp_f32_e32 v36, v36
	v_rcp_f32_e32 v37, v37
	s_nop 0
	v_pk_mul_f32 v[34:35], v[36:37], v[34:35]
	s_nop 0
	v_pk_mul_f32 v[32:33], v[32:33], v[34:35]
	v_lshlrev_b32_e32 v34, 16, v31
	v_and_b32_e32 v35, 0xffff0000, v31
	v_pk_mul_f32 v[36:37], v[34:35], s[24:25] op_sel_hi:[1,0]
	s_nop 0
	v_exp_f32_e32 v36, v36
	v_exp_f32_e32 v37, v37
	s_nop 0
	v_pk_add_f32 v[36:37], v[36:37], 1.0 op_sel_hi:[1,0]
	s_nop 0
	v_rcp_f32_e32 v36, v36
	v_rcp_f32_e32 v37, v37
	s_nop 0
	v_pk_mul_f32 v[34:35], v[36:37], v[34:35]
	s_waitcnt vmcnt(8)
	v_lshlrev_b32_e32 v36, 16, v22
	v_and_b32_e32 v37, 0xffff0000, v22
	v_pk_mul_f32 v[38:39], v[36:37], v[36:37]
	v_pk_mul_f32 v[32:33], v[34:35], v[32:33]
	v_pk_fma_f32 v[38:39], v[38:39], s[18:19], v[40:41] op_sel_hi:[1,0,0] neg_lo:[1,0,0] neg_hi:[1,0,0]
	v_cvt_pk_bf16_f32 v31, v32, v33
	global_store_dwordx4 v[88:89], v[28:31], off
	v_pk_mul_f32 v[38:39], v[38:39], v[36:37]
	ds_read_b128 v[32:35], v47 offset:2176
	ds_read_b128 v[28:31], v47 offset:2192
	v_exp_f32_e32 v38, v38
	v_exp_f32_e32 v39, v39
	v_lshlrev_b32_e32 v22, 16, v23
	s_waitcnt vmcnt(7) lgkmcnt(1)
	v_pk_add_f32 v[32:33], v[50:51], v[32:33] op_sel_hi:[0,1]
	v_and_b32_e32 v23, 0xffff0000, v23
	v_pk_add_f32 v[38:39], v[38:39], 1.0 op_sel_hi:[1,0]
	s_nop 0
	v_rcp_f32_e32 v38, v38
	v_rcp_f32_e32 v39, v39
	s_nop 0
	v_pk_mul_f32 v[36:37], v[38:39], v[36:37]
	s_nop 0
	v_pk_mul_f32 v[32:33], v[32:33], v[36:37]
	v_lshlrev_b32_e32 v36, 16, v18
	v_and_b32_e32 v37, 0xffff0000, v18
	v_pk_mul_f32 v[38:39], v[36:37], s[24:25] op_sel_hi:[1,0]
	s_nop 0
	v_exp_f32_e32 v38, v38
	v_exp_f32_e32 v39, v39
	s_nop 0
	v_pk_add_f32 v[38:39], v[38:39], 1.0 op_sel_hi:[1,0]
	s_nop 0
	v_rcp_f32_e32 v38, v38
	v_rcp_f32_e32 v39, v39
	s_nop 0
	v_pk_mul_f32 v[36:37], v[38:39], v[36:37]
	s_nop 0
	v_pk_mul_f32 v[32:33], v[36:37], v[32:33]
	s_nop 0
	v_cvt_pk_bf16_f32 v18, v32, v33
	v_pk_add_f32 v[32:33], v[50:51], v[34:35] op_sel_hi:[0,1]
	v_pk_mul_f32 v[34:35], v[22:23], v[22:23]
	s_nop 0
	v_pk_fma_f32 v[34:35], v[34:35], s[18:19], v[40:41] op_sel_hi:[1,0,0] neg_lo:[1,0,0] neg_hi:[1,0,0]
	s_nop 0
	v_pk_mul_f32 v[34:35], v[34:35], v[22:23]
	s_nop 0
	v_exp_f32_e32 v34, v34
	v_exp_f32_e32 v35, v35
	s_nop 0
	v_pk_add_f32 v[34:35], v[34:35], 1.0 op_sel_hi:[1,0]
	s_nop 0
	v_rcp_f32_e32 v34, v34
	v_rcp_f32_e32 v35, v35
	s_nop 0
	v_pk_mul_f32 v[22:23], v[34:35], v[22:23]
	s_nop 0
	v_pk_mul_f32 v[22:23], v[32:33], v[22:23]
	v_lshlrev_b32_e32 v32, 16, v19
	v_and_b32_e32 v33, 0xffff0000, v19
	v_pk_mul_f32 v[34:35], v[32:33], s[24:25] op_sel_hi:[1,0]
	s_nop 0
	v_exp_f32_e32 v34, v34
	v_exp_f32_e32 v35, v35
	s_nop 0
	v_pk_add_f32 v[34:35], v[34:35], 1.0 op_sel_hi:[1,0]
	s_nop 0
	v_rcp_f32_e32 v34, v34
	v_rcp_f32_e32 v35, v35
	s_nop 0
	v_pk_mul_f32 v[32:33], v[34:35], v[32:33]
	s_nop 0
	v_pk_mul_f32 v[22:23], v[32:33], v[22:23]
	s_nop 0
	v_cvt_pk_bf16_f32 v19, v22, v23
	s_waitcnt lgkmcnt(0)
	v_pk_add_f32 v[22:23], v[50:51], v[28:29] op_sel_hi:[0,1]
	v_lshlrev_b32_e32 v28, 16, v24
	v_and_b32_e32 v29, 0xffff0000, v24
	v_pk_mul_f32 v[32:33], v[28:29], v[28:29]
	v_lshlrev_b32_e32 v24, 16, v25
	v_pk_fma_f32 v[32:33], v[32:33], s[18:19], v[40:41] op_sel_hi:[1,0,0] neg_lo:[1,0,0] neg_hi:[1,0,0]
	v_and_b32_e32 v25, 0xffff0000, v25
	v_pk_mul_f32 v[32:33], v[32:33], v[28:29]
	s_nop 0
	v_exp_f32_e32 v32, v32
	v_exp_f32_e32 v33, v33
	s_nop 0
	v_pk_add_f32 v[32:33], v[32:33], 1.0 op_sel_hi:[1,0]
	s_nop 0
	v_rcp_f32_e32 v32, v32
	v_rcp_f32_e32 v33, v33
	s_nop 0
	v_pk_mul_f32 v[28:29], v[32:33], v[28:29]
	s_nop 0
	v_pk_mul_f32 v[22:23], v[22:23], v[28:29]
	v_lshlrev_b32_e32 v28, 16, v20
	v_and_b32_e32 v29, 0xffff0000, v20
	v_pk_mul_f32 v[32:33], v[28:29], s[24:25] op_sel_hi:[1,0]
	s_nop 0
	v_exp_f32_e32 v32, v32
	v_exp_f32_e32 v33, v33
	s_nop 0
	v_pk_add_f32 v[32:33], v[32:33], 1.0 op_sel_hi:[1,0]
	s_nop 0
	v_rcp_f32_e32 v32, v32
	v_rcp_f32_e32 v33, v33
	s_nop 0
	v_pk_mul_f32 v[28:29], v[32:33], v[28:29]
	s_nop 0
	v_pk_mul_f32 v[22:23], v[28:29], v[22:23]
	v_pk_mul_f32 v[28:29], v[24:25], v[24:25]
	v_cvt_pk_bf16_f32 v20, v22, v23
	v_pk_add_f32 v[22:23], v[50:51], v[30:31] op_sel_hi:[0,1]
	v_pk_fma_f32 v[28:29], v[28:29], s[18:19], v[40:41] op_sel_hi:[1,0,0] neg_lo:[1,0,0] neg_hi:[1,0,0]
	s_nop 0
	v_pk_mul_f32 v[28:29], v[28:29], v[24:25]
	s_nop 0
	v_exp_f32_e32 v28, v28
	v_exp_f32_e32 v29, v29
	s_nop 0
	v_pk_add_f32 v[28:29], v[28:29], 1.0 op_sel_hi:[1,0]
	s_nop 0
	v_rcp_f32_e32 v28, v28
	v_rcp_f32_e32 v29, v29
	s_nop 0
	v_pk_mul_f32 v[24:25], v[28:29], v[24:25]
	s_nop 0
	v_pk_mul_f32 v[22:23], v[22:23], v[24:25]
	v_lshlrev_b32_e32 v24, 16, v21
	v_and_b32_e32 v25, 0xffff0000, v21
	v_pk_mul_f32 v[28:29], v[24:25], s[24:25] op_sel_hi:[1,0]
	s_nop 0
	v_exp_f32_e32 v28, v28
	v_exp_f32_e32 v29, v29
	s_nop 0
	v_pk_add_f32 v[28:29], v[28:29], 1.0 op_sel_hi:[1,0]
	s_nop 0
	v_rcp_f32_e32 v28, v28
	v_rcp_f32_e32 v29, v29
	s_nop 0
	v_pk_mul_f32 v[24:25], v[28:29], v[24:25]
	s_waitcnt vmcnt(6)
	v_lshlrev_b32_e32 v28, 16, v14
	v_and_b32_e32 v29, 0xffff0000, v14
	v_pk_mul_f32 v[30:31], v[28:29], v[28:29]
	v_pk_mul_f32 v[22:23], v[24:25], v[22:23]
	v_pk_fma_f32 v[30:31], v[30:31], s[18:19], v[40:41] op_sel_hi:[1,0,0] neg_lo:[1,0,0] neg_hi:[1,0,0]
	v_cvt_pk_bf16_f32 v21, v22, v23
	global_store_dwordx4 v[94:95], v[18:21], off
	v_pk_mul_f32 v[30:31], v[30:31], v[28:29]
	ds_read_b128 v[22:25], v47 offset:4352
	ds_read_b128 v[18:21], v47 offset:4368
	v_exp_f32_e32 v30, v30
	v_exp_f32_e32 v31, v31
	v_lshlrev_b32_e32 v14, 16, v15
	s_waitcnt vmcnt(5) lgkmcnt(1)
	v_pk_add_f32 v[22:23], v[48:49], v[22:23] op_sel_hi:[0,1]
	v_and_b32_e32 v15, 0xffff0000, v15
	v_pk_add_f32 v[30:31], v[30:31], 1.0 op_sel_hi:[1,0]
	s_nop 0
	v_rcp_f32_e32 v30, v30
	v_rcp_f32_e32 v31, v31
	s_nop 0
	v_pk_mul_f32 v[28:29], v[30:31], v[28:29]
	s_nop 0
	v_pk_mul_f32 v[22:23], v[28:29], v[22:23]
	v_lshlrev_b32_e32 v28, 16, v10
	v_and_b32_e32 v29, 0xffff0000, v10
	v_pk_mul_f32 v[30:31], v[28:29], s[24:25] op_sel_hi:[1,0]
	s_nop 0
	v_exp_f32_e32 v30, v30
	v_exp_f32_e32 v31, v31
	s_nop 0
	v_pk_add_f32 v[30:31], v[30:31], 1.0 op_sel_hi:[1,0]
	s_nop 0
	v_rcp_f32_e32 v30, v30
	v_rcp_f32_e32 v31, v31
	s_nop 0
	v_pk_mul_f32 v[28:29], v[30:31], v[28:29]
	s_nop 0
	v_pk_mul_f32 v[22:23], v[28:29], v[22:23]
	s_nop 0
	v_cvt_pk_bf16_f32 v10, v22, v23
	v_pk_add_f32 v[22:23], v[48:49], v[24:25] op_sel_hi:[0,1]
	v_pk_mul_f32 v[24:25], v[14:15], v[14:15]
	s_nop 0
	v_pk_fma_f32 v[24:25], v[24:25], s[18:19], v[40:41] op_sel_hi:[1,0,0] neg_lo:[1,0,0] neg_hi:[1,0,0]
	s_nop 0
	v_pk_mul_f32 v[24:25], v[24:25], v[14:15]
	s_nop 0
	v_exp_f32_e32 v24, v24
	v_exp_f32_e32 v25, v25
	s_nop 0
	v_pk_add_f32 v[24:25], v[24:25], 1.0 op_sel_hi:[1,0]
	s_nop 0
	v_rcp_f32_e32 v24, v24
	v_rcp_f32_e32 v25, v25
	s_nop 0
	v_pk_mul_f32 v[14:15], v[24:25], v[14:15]
	s_nop 0
	v_pk_mul_f32 v[14:15], v[14:15], v[22:23]
	v_lshlrev_b32_e32 v22, 16, v11
	v_and_b32_e32 v23, 0xffff0000, v11
	v_pk_mul_f32 v[24:25], v[22:23], s[24:25] op_sel_hi:[1,0]
	s_nop 0
	v_exp_f32_e32 v24, v24
	v_exp_f32_e32 v25, v25
	s_nop 0
	v_pk_add_f32 v[24:25], v[24:25], 1.0 op_sel_hi:[1,0]
	s_nop 0
	v_rcp_f32_e32 v24, v24
	v_rcp_f32_e32 v25, v25
	s_nop 0
	v_pk_mul_f32 v[22:23], v[24:25], v[22:23]
	s_nop 0
	v_pk_mul_f32 v[14:15], v[22:23], v[14:15]
	s_nop 0
	v_cvt_pk_bf16_f32 v11, v14, v15
	s_waitcnt lgkmcnt(0)
	v_pk_add_f32 v[14:15], v[48:49], v[18:19] op_sel_hi:[0,1]
	v_lshlrev_b32_e32 v18, 16, v16
	v_and_b32_e32 v19, 0xffff0000, v16
	v_pk_mul_f32 v[22:23], v[18:19], v[18:19]
	v_lshlrev_b32_e32 v16, 16, v17
	v_pk_fma_f32 v[22:23], v[22:23], s[18:19], v[40:41] op_sel_hi:[1,0,0] neg_lo:[1,0,0] neg_hi:[1,0,0]
	v_and_b32_e32 v17, 0xffff0000, v17
	v_pk_mul_f32 v[22:23], v[22:23], v[18:19]
	s_nop 0
	v_exp_f32_e32 v22, v22
	v_exp_f32_e32 v23, v23
	s_nop 0
	v_pk_add_f32 v[22:23], v[22:23], 1.0 op_sel_hi:[1,0]
	s_nop 0
	v_rcp_f32_e32 v22, v22
	v_rcp_f32_e32 v23, v23
	s_nop 0
	v_pk_mul_f32 v[18:19], v[22:23], v[18:19]
	s_nop 0
	v_pk_mul_f32 v[14:15], v[18:19], v[14:15]
	v_lshlrev_b32_e32 v18, 16, v12
	v_and_b32_e32 v19, 0xffff0000, v12
	v_pk_mul_f32 v[22:23], v[18:19], s[24:25] op_sel_hi:[1,0]
	s_nop 0
	v_exp_f32_e32 v22, v22
	v_exp_f32_e32 v23, v23
	s_nop 0
	v_pk_add_f32 v[22:23], v[22:23], 1.0 op_sel_hi:[1,0]
	s_nop 0
	v_rcp_f32_e32 v22, v22
	v_rcp_f32_e32 v23, v23
	s_nop 0
	v_pk_mul_f32 v[18:19], v[22:23], v[18:19]
	s_nop 0
	v_pk_mul_f32 v[14:15], v[18:19], v[14:15]
	v_pk_mul_f32 v[18:19], v[16:17], v[16:17]
	v_cvt_pk_bf16_f32 v12, v14, v15
	v_pk_add_f32 v[14:15], v[48:49], v[20:21] op_sel_hi:[0,1]
	v_pk_fma_f32 v[18:19], v[18:19], s[18:19], v[40:41] op_sel_hi:[1,0,0] neg_lo:[1,0,0] neg_hi:[1,0,0]
	s_nop 0
	v_pk_mul_f32 v[18:19], v[18:19], v[16:17]
	s_nop 0
	v_exp_f32_e32 v18, v18
	v_exp_f32_e32 v19, v19
	s_nop 0
	v_pk_add_f32 v[18:19], v[18:19], 1.0 op_sel_hi:[1,0]
	s_nop 0
	v_rcp_f32_e32 v18, v18
	v_rcp_f32_e32 v19, v19
	s_nop 0
	v_pk_mul_f32 v[16:17], v[18:19], v[16:17]
	s_nop 0
	v_pk_mul_f32 v[14:15], v[16:17], v[14:15]
	v_lshlrev_b32_e32 v16, 16, v13
	v_and_b32_e32 v17, 0xffff0000, v13
	v_pk_mul_f32 v[18:19], v[16:17], s[24:25] op_sel_hi:[1,0]
	s_nop 0
	v_exp_f32_e32 v18, v18
	v_exp_f32_e32 v19, v19
	s_nop 0
	v_pk_add_f32 v[18:19], v[18:19], 1.0 op_sel_hi:[1,0]
	s_nop 0
	v_rcp_f32_e32 v18, v18
	v_rcp_f32_e32 v19, v19
	s_nop 0
	v_pk_mul_f32 v[16:17], v[18:19], v[16:17]
	s_waitcnt vmcnt(4)
	v_lshlrev_b32_e32 v18, 16, v6
	v_and_b32_e32 v19, 0xffff0000, v6
	v_pk_mul_f32 v[20:21], v[18:19], v[18:19]
	v_pk_mul_f32 v[14:15], v[16:17], v[14:15]
	v_pk_fma_f32 v[20:21], v[20:21], s[18:19], v[40:41] op_sel_hi:[1,0,0] neg_lo:[1,0,0] neg_hi:[1,0,0]
	v_cvt_pk_bf16_f32 v13, v14, v15
	global_store_dwordx4 v[92:93], v[10:13], off
	v_pk_mul_f32 v[20:21], v[20:21], v[18:19]
	ds_read_b128 v[14:17], v47 offset:6528
	ds_read_b128 v[10:13], v47 offset:6544
	v_exp_f32_e32 v20, v20
	v_exp_f32_e32 v21, v21
	v_lshlrev_b32_e32 v6, 16, v7
	s_waitcnt vmcnt(3) lgkmcnt(1)
	v_pk_add_f32 v[14:15], v[46:47], v[14:15] op_sel_hi:[0,1]
	v_and_b32_e32 v7, 0xffff0000, v7
	v_pk_add_f32 v[20:21], v[20:21], 1.0 op_sel_hi:[1,0]
	s_nop 0
	v_rcp_f32_e32 v20, v20
	v_rcp_f32_e32 v21, v21
	s_nop 0
	v_pk_mul_f32 v[18:19], v[20:21], v[18:19]
	s_nop 0
	v_pk_mul_f32 v[14:15], v[18:19], v[14:15]
	v_lshlrev_b32_e32 v18, 16, v2
	v_and_b32_e32 v19, 0xffff0000, v2
	v_pk_mul_f32 v[20:21], v[18:19], s[24:25] op_sel_hi:[1,0]
	s_nop 0
	v_exp_f32_e32 v20, v20
	v_exp_f32_e32 v21, v21
	s_nop 0
	v_pk_add_f32 v[20:21], v[20:21], 1.0 op_sel_hi:[1,0]
	s_nop 0
	v_rcp_f32_e32 v20, v20
	v_rcp_f32_e32 v21, v21
	s_nop 0
	v_pk_mul_f32 v[18:19], v[20:21], v[18:19]
	s_nop 0
	v_pk_mul_f32 v[14:15], v[18:19], v[14:15]
	s_nop 0
	v_cvt_pk_bf16_f32 v2, v14, v15
	v_pk_add_f32 v[14:15], v[46:47], v[16:17] op_sel_hi:[0,1]
	v_pk_mul_f32 v[16:17], v[6:7], v[6:7]
	s_nop 0
	v_pk_fma_f32 v[16:17], v[16:17], s[18:19], v[40:41] op_sel_hi:[1,0,0] neg_lo:[1,0,0] neg_hi:[1,0,0]
	s_nop 0
	v_pk_mul_f32 v[16:17], v[16:17], v[6:7]
	s_nop 0
	v_exp_f32_e32 v16, v16
	v_exp_f32_e32 v17, v17
	s_nop 0
	v_pk_add_f32 v[16:17], v[16:17], 1.0 op_sel_hi:[1,0]
	s_nop 0
	v_rcp_f32_e32 v16, v16
	v_rcp_f32_e32 v17, v17
	s_nop 0
	v_pk_mul_f32 v[6:7], v[16:17], v[6:7]
	s_nop 0
	v_pk_mul_f32 v[6:7], v[6:7], v[14:15]
	v_lshlrev_b32_e32 v14, 16, v3
	v_and_b32_e32 v15, 0xffff0000, v3
	v_pk_mul_f32 v[16:17], v[14:15], s[24:25] op_sel_hi:[1,0]
	s_nop 0
	v_exp_f32_e32 v16, v16
	v_exp_f32_e32 v17, v17
	s_nop 0
	v_pk_add_f32 v[16:17], v[16:17], 1.0 op_sel_hi:[1,0]
	s_nop 0
	v_rcp_f32_e32 v16, v16
	v_rcp_f32_e32 v17, v17
	s_nop 0
	v_pk_mul_f32 v[14:15], v[16:17], v[14:15]
	s_nop 0
	v_pk_mul_f32 v[6:7], v[14:15], v[6:7]
	s_nop 0
	v_cvt_pk_bf16_f32 v3, v6, v7
	s_waitcnt lgkmcnt(0)
	v_pk_add_f32 v[6:7], v[46:47], v[10:11] op_sel_hi:[0,1]
	v_lshlrev_b32_e32 v10, 16, v8
	v_and_b32_e32 v11, 0xffff0000, v8
	v_pk_mul_f32 v[14:15], v[10:11], v[10:11]
	v_lshlrev_b32_e32 v8, 16, v9
	v_pk_fma_f32 v[14:15], v[14:15], s[18:19], v[40:41] op_sel_hi:[1,0,0] neg_lo:[1,0,0] neg_hi:[1,0,0]
	v_and_b32_e32 v9, 0xffff0000, v9
	v_pk_mul_f32 v[14:15], v[14:15], v[10:11]
	s_nop 0
	v_exp_f32_e32 v14, v14
	v_exp_f32_e32 v15, v15
	s_nop 0
	v_pk_add_f32 v[14:15], v[14:15], 1.0 op_sel_hi:[1,0]
	s_nop 0
	v_rcp_f32_e32 v14, v14
	v_rcp_f32_e32 v15, v15
	s_nop 0
	v_pk_mul_f32 v[10:11], v[14:15], v[10:11]
	s_nop 0
	v_pk_mul_f32 v[6:7], v[10:11], v[6:7]
	v_lshlrev_b32_e32 v10, 16, v4
	v_and_b32_e32 v11, 0xffff0000, v4
	v_pk_mul_f32 v[14:15], v[10:11], s[24:25] op_sel_hi:[1,0]
	s_nop 0
	v_exp_f32_e32 v14, v14
	v_exp_f32_e32 v15, v15
	s_nop 0
	v_pk_add_f32 v[14:15], v[14:15], 1.0 op_sel_hi:[1,0]
	s_nop 0
	v_rcp_f32_e32 v14, v14
	v_rcp_f32_e32 v15, v15
	s_nop 0
	v_pk_mul_f32 v[10:11], v[14:15], v[10:11]
	s_nop 0
	v_pk_mul_f32 v[6:7], v[10:11], v[6:7]
	v_pk_mul_f32 v[10:11], v[8:9], v[8:9]
	v_cvt_pk_bf16_f32 v4, v6, v7
	v_pk_add_f32 v[6:7], v[46:47], v[12:13] op_sel_hi:[0,1]
	v_pk_fma_f32 v[10:11], v[10:11], s[18:19], v[40:41] op_sel_hi:[1,0,0] neg_lo:[1,0,0] neg_hi:[1,0,0]
	s_nop 0
	v_pk_mul_f32 v[10:11], v[10:11], v[8:9]
	s_nop 0
	v_exp_f32_e32 v10, v10
	v_exp_f32_e32 v11, v11
	s_nop 0
	v_pk_add_f32 v[10:11], v[10:11], 1.0 op_sel_hi:[1,0]
	s_nop 0
	v_rcp_f32_e32 v10, v10
	v_rcp_f32_e32 v11, v11
	s_nop 0
	v_pk_mul_f32 v[8:9], v[10:11], v[8:9]
	s_nop 0
	v_pk_mul_f32 v[6:7], v[8:9], v[6:7]
	v_lshlrev_b32_e32 v8, 16, v5
	v_and_b32_e32 v9, 0xffff0000, v5
	v_pk_mul_f32 v[10:11], v[8:9], s[24:25] op_sel_hi:[1,0]
	s_nop 0
	v_exp_f32_e32 v10, v10
	v_exp_f32_e32 v11, v11
	s_nop 0
	v_pk_add_f32 v[10:11], v[10:11], 1.0 op_sel_hi:[1,0]
	s_nop 0
	v_rcp_f32_e32 v10, v10
	v_rcp_f32_e32 v11, v11
	s_nop 0
	v_pk_mul_f32 v[8:9], v[10:11], v[8:9]
	s_nop 0
	v_pk_mul_f32 v[6:7], v[8:9], v[6:7]
	s_nop 0
	v_cvt_pk_bf16_f32 v5, v6, v7
	global_store_dwordx4 v[44:45], v[2:5], off
	s_nop 1
	v_add_co_u32_e32 v2, vcc, s0, v88
	s_mov_b32 s0, 0x6e000
	s_nop 0
	v_addc_co_u32_e32 v3, vcc, 0, v89, vcc
	global_load_dwordx4 v[32:35], v[2:3], off offset:-4096
	global_load_dwordx4 v[28:31], v[2:3], off
	global_load_dword v52, v[42:43], off offset:128
	v_add_co_u32_e32 v48, vcc, s0, v88
	s_mov_b32 s0, 0x6f000
	s_nop 0
	v_addc_co_u32_e32 v49, vcc, 0, v89, vcc
	v_add_co_u32_e32 v2, vcc, s0, v88
	s_mov_b32 s0, 0x84000
	s_nop 0
	v_addc_co_u32_e32 v3, vcc, 0, v89, vcc
	v_add_co_u32_e32 v44, vcc, s0, v88
	s_mov_b32 s0, 0x85000
	s_nop 0
	v_addc_co_u32_e32 v45, vcc, 0, v89, vcc
	global_load_dwordx4 v[22:25], v[2:3], off offset:-4096
	global_load_dwordx4 v[18:21], v[2:3], off
	global_load_dword v50, v[42:43], off offset:160
	v_add_co_u32_e32 v2, vcc, s0, v88
	s_mov_b32 s0, 0x9b000
	s_nop 0
	v_addc_co_u32_e32 v3, vcc, 0, v89, vcc
	global_load_dwordx4 v[14:17], v[2:3], off offset:-4096
	global_load_dwordx4 v[10:13], v[2:3], off
	global_load_dword v46, v[42:43], off offset:192
	v_add_co_u32_e32 v2, vcc, s0, v88
	s_waitcnt vmcnt(8)
	v_lshlrev_b32_e32 v58, 16, v32
	v_and_b32_e32 v59, 0xffff0000, v32
	v_pk_mul_f32 v[60:61], v[58:59], v[58:59]
	v_addc_co_u32_e32 v3, vcc, 0, v89, vcc
	v_pk_fma_f32 v[60:61], v[60:61], s[18:19], v[40:41] op_sel_hi:[1,0,0] neg_lo:[1,0,0] neg_hi:[1,0,0]
	global_load_dwordx4 v[6:9], v[2:3], off offset:-4096
	s_nop 0
	global_load_dwordx4 v[2:5], v[2:3], off
	s_nop 0
	global_load_dword v42, v[42:43], off offset:224
	v_pk_mul_f32 v[60:61], v[60:61], v[58:59]
	ds_read_b128 v[54:57], v47 offset:8704
	ds_read_b128 v[36:39], v47 offset:8720
	v_exp_f32_e32 v60, v60
	v_exp_f32_e32 v61, v61
	v_lshlrev_b32_e32 v32, 16, v33
	s_waitcnt vmcnt(9) lgkmcnt(1)
	v_pk_add_f32 v[54:55], v[52:53], v[54:55] op_sel_hi:[0,1]
	v_and_b32_e32 v33, 0xffff0000, v33
	v_pk_add_f32 v[60:61], v[60:61], 1.0 op_sel_hi:[1,0]
	s_nop 0
	v_rcp_f32_e32 v60, v60
	v_rcp_f32_e32 v61, v61
	s_nop 0
	v_pk_mul_f32 v[58:59], v[60:61], v[58:59]
	s_nop 0
	v_pk_mul_f32 v[54:55], v[54:55], v[58:59]
	v_lshlrev_b32_e32 v58, 16, v28
	v_and_b32_e32 v59, 0xffff0000, v28
	v_pk_mul_f32 v[60:61], v[58:59], s[24:25] op_sel_hi:[1,0]
	s_nop 0
	v_exp_f32_e32 v60, v60
	v_exp_f32_e32 v61, v61
	s_nop 0
	v_pk_add_f32 v[60:61], v[60:61], 1.0 op_sel_hi:[1,0]
	s_nop 0
	v_rcp_f32_e32 v60, v60
	v_rcp_f32_e32 v61, v61
	s_nop 0
	v_pk_mul_f32 v[58:59], v[60:61], v[58:59]
	s_nop 0
	v_pk_mul_f32 v[54:55], v[58:59], v[54:55]
	s_nop 0
	v_cvt_pk_bf16_f32 v28, v54, v55
	v_pk_add_f32 v[54:55], v[52:53], v[56:57] op_sel_hi:[0,1]
	v_pk_mul_f32 v[56:57], v[32:33], v[32:33]
	s_nop 0
	v_pk_fma_f32 v[56:57], v[56:57], s[18:19], v[40:41] op_sel_hi:[1,0,0] neg_lo:[1,0,0] neg_hi:[1,0,0]
	s_nop 0
	v_pk_mul_f32 v[56:57], v[56:57], v[32:33]
	s_nop 0
	v_exp_f32_e32 v56, v56
	v_exp_f32_e32 v57, v57
	s_nop 0
	v_pk_add_f32 v[56:57], v[56:57], 1.0 op_sel_hi:[1,0]
	s_nop 0
	v_rcp_f32_e32 v56, v56
	v_rcp_f32_e32 v57, v57
	s_nop 0
	v_pk_mul_f32 v[32:33], v[56:57], v[32:33]
	s_nop 0
	v_pk_mul_f32 v[32:33], v[54:55], v[32:33]
	v_lshlrev_b32_e32 v54, 16, v29
	v_and_b32_e32 v55, 0xffff0000, v29
	v_pk_mul_f32 v[56:57], v[54:55], s[24:25] op_sel_hi:[1,0]
	s_nop 0
	v_exp_f32_e32 v56, v56
	v_exp_f32_e32 v57, v57
	s_nop 0
	v_pk_add_f32 v[56:57], v[56:57], 1.0 op_sel_hi:[1,0]
	s_nop 0
	v_rcp_f32_e32 v56, v56
	v_rcp_f32_e32 v57, v57
	s_nop 0
	v_pk_mul_f32 v[54:55], v[56:57], v[54:55]
	s_nop 0
	v_pk_mul_f32 v[32:33], v[54:55], v[32:33]
	s_nop 0
	v_cvt_pk_bf16_f32 v29, v32, v33
	s_waitcnt lgkmcnt(0)
	v_pk_add_f32 v[32:33], v[52:53], v[36:37] op_sel_hi:[0,1]
	v_lshlrev_b32_e32 v36, 16, v34
	v_and_b32_e32 v37, 0xffff0000, v34
	v_pk_mul_f32 v[54:55], v[36:37], v[36:37]
	v_lshlrev_b32_e32 v34, 16, v35
	v_pk_fma_f32 v[54:55], v[54:55], s[18:19], v[40:41] op_sel_hi:[1,0,0] neg_lo:[1,0,0] neg_hi:[1,0,0]
	v_and_b32_e32 v35, 0xffff0000, v35
	v_pk_mul_f32 v[54:55], v[54:55], v[36:37]
	s_nop 0
	v_exp_f32_e32 v54, v54
	v_exp_f32_e32 v55, v55
	s_nop 0
	v_pk_add_f32 v[54:55], v[54:55], 1.0 op_sel_hi:[1,0]
	s_nop 0
	v_rcp_f32_e32 v54, v54
	v_rcp_f32_e32 v55, v55
	s_nop 0
	v_pk_mul_f32 v[36:37], v[54:55], v[36:37]
	s_nop 0
	v_pk_mul_f32 v[32:33], v[32:33], v[36:37]
	v_lshlrev_b32_e32 v36, 16, v30
	v_and_b32_e32 v37, 0xffff0000, v30
	v_pk_mul_f32 v[54:55], v[36:37], s[24:25] op_sel_hi:[1,0]
	s_nop 0
	v_exp_f32_e32 v54, v54
	v_exp_f32_e32 v55, v55
	s_nop 0
	v_pk_add_f32 v[54:55], v[54:55], 1.0 op_sel_hi:[1,0]
	s_nop 0
	v_rcp_f32_e32 v54, v54
	v_rcp_f32_e32 v55, v55
	s_nop 0
	v_pk_mul_f32 v[36:37], v[54:55], v[36:37]
	s_nop 0
	v_pk_mul_f32 v[32:33], v[36:37], v[32:33]
	v_pk_mul_f32 v[36:37], v[34:35], v[34:35]
	v_cvt_pk_bf16_f32 v30, v32, v33
	v_pk_add_f32 v[32:33], v[52:53], v[38:39] op_sel_hi:[0,1]
	v_pk_fma_f32 v[36:37], v[36:37], s[18:19], v[40:41] op_sel_hi:[1,0,0] neg_lo:[1,0,0] neg_hi:[1,0,0]
	s_nop 0
	v_pk_mul_f32 v[36:37], v[36:37], v[34:35]
	s_nop 0
	v_exp_f32_e32 v36, v36
	v_exp_f32_e32 v37, v37
	s_nop 0
	v_pk_add_f32 v[36:37], v[36:37], 1.0 op_sel_hi:[1,0]
	s_nop 0
	v_rcp_f32_e32 v36, v36
	v_rcp_f32_e32 v37, v37
	s_nop 0
	v_pk_mul_f32 v[34:35], v[36:37], v[34:35]
	s_nop 0
	v_pk_mul_f32 v[32:33], v[32:33], v[34:35]
	v_lshlrev_b32_e32 v34, 16, v31
	v_and_b32_e32 v35, 0xffff0000, v31
	v_pk_mul_f32 v[36:37], v[34:35], s[24:25] op_sel_hi:[1,0]
	s_nop 0
	v_exp_f32_e32 v36, v36
	v_exp_f32_e32 v37, v37
	s_nop 0
	v_pk_add_f32 v[36:37], v[36:37], 1.0 op_sel_hi:[1,0]
	s_nop 0
	v_rcp_f32_e32 v36, v36
	v_rcp_f32_e32 v37, v37
	s_nop 0
	v_pk_mul_f32 v[34:35], v[36:37], v[34:35]
	s_waitcnt vmcnt(8)
	v_lshlrev_b32_e32 v36, 16, v22
	v_and_b32_e32 v37, 0xffff0000, v22
	v_pk_mul_f32 v[38:39], v[36:37], v[36:37]
	v_pk_mul_f32 v[32:33], v[34:35], v[32:33]
	v_pk_fma_f32 v[38:39], v[38:39], s[18:19], v[40:41] op_sel_hi:[1,0,0] neg_lo:[1,0,0] neg_hi:[1,0,0]
	v_cvt_pk_bf16_f32 v31, v32, v33
	global_store_dwordx4 v[90:91], v[28:31], off
	v_pk_mul_f32 v[38:39], v[38:39], v[36:37]
	ds_read_b128 v[32:35], v47 offset:10880
	ds_read_b128 v[28:31], v47 offset:10896
	v_exp_f32_e32 v38, v38
	v_exp_f32_e32 v39, v39
	v_lshlrev_b32_e32 v22, 16, v23
	s_waitcnt vmcnt(7) lgkmcnt(1)
	v_pk_add_f32 v[32:33], v[50:51], v[32:33] op_sel_hi:[0,1]
	v_and_b32_e32 v23, 0xffff0000, v23
	v_pk_add_f32 v[38:39], v[38:39], 1.0 op_sel_hi:[1,0]
	s_nop 0
	v_rcp_f32_e32 v38, v38
	v_rcp_f32_e32 v39, v39
	s_nop 0
	v_pk_mul_f32 v[36:37], v[38:39], v[36:37]
	s_nop 0
	v_pk_mul_f32 v[32:33], v[32:33], v[36:37]
	v_lshlrev_b32_e32 v36, 16, v18
	v_and_b32_e32 v37, 0xffff0000, v18
	v_pk_mul_f32 v[38:39], v[36:37], s[24:25] op_sel_hi:[1,0]
	s_nop 0
	v_exp_f32_e32 v38, v38
	v_exp_f32_e32 v39, v39
	s_nop 0
	v_pk_add_f32 v[38:39], v[38:39], 1.0 op_sel_hi:[1,0]
	s_nop 0
	v_rcp_f32_e32 v38, v38
	v_rcp_f32_e32 v39, v39
	s_nop 0
	v_pk_mul_f32 v[36:37], v[38:39], v[36:37]
	s_nop 0
	v_pk_mul_f32 v[32:33], v[36:37], v[32:33]
	s_nop 0
	v_cvt_pk_bf16_f32 v18, v32, v33
	v_pk_add_f32 v[32:33], v[50:51], v[34:35] op_sel_hi:[0,1]
	v_pk_mul_f32 v[34:35], v[22:23], v[22:23]
	s_nop 0
	v_pk_fma_f32 v[34:35], v[34:35], s[18:19], v[40:41] op_sel_hi:[1,0,0] neg_lo:[1,0,0] neg_hi:[1,0,0]
	s_nop 0
	v_pk_mul_f32 v[34:35], v[34:35], v[22:23]
	s_nop 0
	v_exp_f32_e32 v34, v34
	v_exp_f32_e32 v35, v35
	s_nop 0
	v_pk_add_f32 v[34:35], v[34:35], 1.0 op_sel_hi:[1,0]
	s_nop 0
	v_rcp_f32_e32 v34, v34
	v_rcp_f32_e32 v35, v35
	s_nop 0
	v_pk_mul_f32 v[22:23], v[34:35], v[22:23]
	s_nop 0
	v_pk_mul_f32 v[22:23], v[32:33], v[22:23]
	v_lshlrev_b32_e32 v32, 16, v19
	v_and_b32_e32 v33, 0xffff0000, v19
	v_pk_mul_f32 v[34:35], v[32:33], s[24:25] op_sel_hi:[1,0]
	s_nop 0
	v_exp_f32_e32 v34, v34
	v_exp_f32_e32 v35, v35
	s_nop 0
	v_pk_add_f32 v[34:35], v[34:35], 1.0 op_sel_hi:[1,0]
	s_nop 0
	v_rcp_f32_e32 v34, v34
	v_rcp_f32_e32 v35, v35
	s_nop 0
	v_pk_mul_f32 v[32:33], v[34:35], v[32:33]
	s_nop 0
	v_pk_mul_f32 v[22:23], v[32:33], v[22:23]
	s_nop 0
	v_cvt_pk_bf16_f32 v19, v22, v23
	s_waitcnt lgkmcnt(0)
	v_pk_add_f32 v[22:23], v[50:51], v[28:29] op_sel_hi:[0,1]
	v_lshlrev_b32_e32 v28, 16, v24
	v_and_b32_e32 v29, 0xffff0000, v24
	v_pk_mul_f32 v[32:33], v[28:29], v[28:29]
	v_lshlrev_b32_e32 v24, 16, v25
	v_pk_fma_f32 v[32:33], v[32:33], s[18:19], v[40:41] op_sel_hi:[1,0,0] neg_lo:[1,0,0] neg_hi:[1,0,0]
	v_and_b32_e32 v25, 0xffff0000, v25
	v_pk_mul_f32 v[32:33], v[32:33], v[28:29]
	s_nop 0
	v_exp_f32_e32 v32, v32
	v_exp_f32_e32 v33, v33
	s_nop 0
	v_pk_add_f32 v[32:33], v[32:33], 1.0 op_sel_hi:[1,0]
	s_nop 0
	v_rcp_f32_e32 v32, v32
	v_rcp_f32_e32 v33, v33
	s_nop 0
	v_pk_mul_f32 v[28:29], v[32:33], v[28:29]
	s_nop 0
	v_pk_mul_f32 v[22:23], v[22:23], v[28:29]
	v_lshlrev_b32_e32 v28, 16, v20
	v_and_b32_e32 v29, 0xffff0000, v20
	v_pk_mul_f32 v[32:33], v[28:29], s[24:25] op_sel_hi:[1,0]
	s_nop 0
	v_exp_f32_e32 v32, v32
	v_exp_f32_e32 v33, v33
	s_nop 0
	v_pk_add_f32 v[32:33], v[32:33], 1.0 op_sel_hi:[1,0]
	s_nop 0
	v_rcp_f32_e32 v32, v32
	v_rcp_f32_e32 v33, v33
	s_nop 0
	v_pk_mul_f32 v[28:29], v[32:33], v[28:29]
	s_nop 0
	v_pk_mul_f32 v[22:23], v[28:29], v[22:23]
	v_pk_mul_f32 v[28:29], v[24:25], v[24:25]
	v_cvt_pk_bf16_f32 v20, v22, v23
	v_pk_add_f32 v[22:23], v[50:51], v[30:31] op_sel_hi:[0,1]
	v_pk_fma_f32 v[28:29], v[28:29], s[18:19], v[40:41] op_sel_hi:[1,0,0] neg_lo:[1,0,0] neg_hi:[1,0,0]
	s_nop 0
	v_pk_mul_f32 v[28:29], v[28:29], v[24:25]
	s_nop 0
	v_exp_f32_e32 v28, v28
	v_exp_f32_e32 v29, v29
	s_nop 0
	v_pk_add_f32 v[28:29], v[28:29], 1.0 op_sel_hi:[1,0]
	s_nop 0
	v_rcp_f32_e32 v28, v28
	v_rcp_f32_e32 v29, v29
	s_nop 0
	v_pk_mul_f32 v[24:25], v[28:29], v[24:25]
	s_nop 0
	v_pk_mul_f32 v[22:23], v[22:23], v[24:25]
	v_lshlrev_b32_e32 v24, 16, v21
	v_and_b32_e32 v25, 0xffff0000, v21
	v_pk_mul_f32 v[28:29], v[24:25], s[24:25] op_sel_hi:[1,0]
	s_nop 0
	v_exp_f32_e32 v28, v28
	v_exp_f32_e32 v29, v29
	s_nop 0
	v_pk_add_f32 v[28:29], v[28:29], 1.0 op_sel_hi:[1,0]
	s_nop 0
	v_rcp_f32_e32 v28, v28
	v_rcp_f32_e32 v29, v29
	s_nop 0
	v_pk_mul_f32 v[24:25], v[28:29], v[24:25]
	s_waitcnt vmcnt(6)
	v_lshlrev_b32_e32 v28, 16, v14
	v_and_b32_e32 v29, 0xffff0000, v14
	v_pk_mul_f32 v[30:31], v[28:29], v[28:29]
	v_pk_mul_f32 v[22:23], v[24:25], v[22:23]
	v_pk_fma_f32 v[30:31], v[30:31], s[18:19], v[40:41] op_sel_hi:[1,0,0] neg_lo:[1,0,0] neg_hi:[1,0,0]
	v_cvt_pk_bf16_f32 v21, v22, v23
	global_store_dwordx4 v[48:49], v[18:21], off
	v_pk_mul_f32 v[30:31], v[30:31], v[28:29]
	ds_read_b128 v[22:25], v47 offset:13056
	ds_read_b128 v[18:21], v47 offset:13072
	v_exp_f32_e32 v30, v30
	v_exp_f32_e32 v31, v31
	v_lshlrev_b32_e32 v14, 16, v15
	s_waitcnt vmcnt(5) lgkmcnt(1)
	v_pk_add_f32 v[22:23], v[46:47], v[22:23] op_sel_hi:[0,1]
	v_and_b32_e32 v15, 0xffff0000, v15
	v_pk_add_f32 v[30:31], v[30:31], 1.0 op_sel_hi:[1,0]
	s_nop 0
	v_rcp_f32_e32 v30, v30
	v_rcp_f32_e32 v31, v31
	s_nop 0
	v_pk_mul_f32 v[28:29], v[30:31], v[28:29]
	s_nop 0
	v_pk_mul_f32 v[22:23], v[28:29], v[22:23]
	v_lshlrev_b32_e32 v28, 16, v10
	v_and_b32_e32 v29, 0xffff0000, v10
	v_pk_mul_f32 v[30:31], v[28:29], s[24:25] op_sel_hi:[1,0]
	s_nop 0
	v_exp_f32_e32 v30, v30
	v_exp_f32_e32 v31, v31
	s_nop 0
	v_pk_add_f32 v[30:31], v[30:31], 1.0 op_sel_hi:[1,0]
	s_nop 0
	v_rcp_f32_e32 v30, v30
	v_rcp_f32_e32 v31, v31
	s_nop 0
	v_pk_mul_f32 v[28:29], v[30:31], v[28:29]
	s_nop 0
	v_pk_mul_f32 v[22:23], v[28:29], v[22:23]
	s_nop 0
	v_cvt_pk_bf16_f32 v10, v22, v23
	v_pk_add_f32 v[22:23], v[46:47], v[24:25] op_sel_hi:[0,1]
	v_pk_mul_f32 v[24:25], v[14:15], v[14:15]
	s_nop 0
	v_pk_fma_f32 v[24:25], v[24:25], s[18:19], v[40:41] op_sel_hi:[1,0,0] neg_lo:[1,0,0] neg_hi:[1,0,0]
	s_nop 0
	v_pk_mul_f32 v[24:25], v[24:25], v[14:15]
	s_nop 0
	v_exp_f32_e32 v24, v24
	v_exp_f32_e32 v25, v25
	s_nop 0
	v_pk_add_f32 v[24:25], v[24:25], 1.0 op_sel_hi:[1,0]
	s_nop 0
	v_rcp_f32_e32 v24, v24
	v_rcp_f32_e32 v25, v25
	s_nop 0
	v_pk_mul_f32 v[14:15], v[24:25], v[14:15]
	s_nop 0
	v_pk_mul_f32 v[14:15], v[14:15], v[22:23]
	v_lshlrev_b32_e32 v22, 16, v11
	v_and_b32_e32 v23, 0xffff0000, v11
	v_pk_mul_f32 v[24:25], v[22:23], s[24:25] op_sel_hi:[1,0]
	s_nop 0
	v_exp_f32_e32 v24, v24
	v_exp_f32_e32 v25, v25
	s_nop 0
	v_pk_add_f32 v[24:25], v[24:25], 1.0 op_sel_hi:[1,0]
	s_nop 0
	v_rcp_f32_e32 v24, v24
	v_rcp_f32_e32 v25, v25
	s_nop 0
	v_pk_mul_f32 v[22:23], v[24:25], v[22:23]
	s_nop 0
	v_pk_mul_f32 v[14:15], v[22:23], v[14:15]
	s_nop 0
	v_cvt_pk_bf16_f32 v11, v14, v15
	s_waitcnt lgkmcnt(0)
	v_pk_add_f32 v[14:15], v[46:47], v[18:19] op_sel_hi:[0,1]
	v_lshlrev_b32_e32 v18, 16, v16
	v_and_b32_e32 v19, 0xffff0000, v16
	v_pk_mul_f32 v[22:23], v[18:19], v[18:19]
	v_lshlrev_b32_e32 v16, 16, v17
	v_pk_fma_f32 v[22:23], v[22:23], s[18:19], v[40:41] op_sel_hi:[1,0,0] neg_lo:[1,0,0] neg_hi:[1,0,0]
	v_and_b32_e32 v17, 0xffff0000, v17
	v_pk_mul_f32 v[22:23], v[22:23], v[18:19]
	s_nop 0
	v_exp_f32_e32 v22, v22
	v_exp_f32_e32 v23, v23
	s_nop 0
	v_pk_add_f32 v[22:23], v[22:23], 1.0 op_sel_hi:[1,0]
	s_nop 0
	v_rcp_f32_e32 v22, v22
	v_rcp_f32_e32 v23, v23
	s_nop 0
	v_pk_mul_f32 v[18:19], v[22:23], v[18:19]
	s_nop 0
	v_pk_mul_f32 v[14:15], v[18:19], v[14:15]
	v_lshlrev_b32_e32 v18, 16, v12
	v_and_b32_e32 v19, 0xffff0000, v12
	v_pk_mul_f32 v[22:23], v[18:19], s[24:25] op_sel_hi:[1,0]
	s_nop 0
	v_exp_f32_e32 v22, v22
	v_exp_f32_e32 v23, v23
	s_nop 0
	v_pk_add_f32 v[22:23], v[22:23], 1.0 op_sel_hi:[1,0]
	s_nop 0
	v_rcp_f32_e32 v22, v22
	v_rcp_f32_e32 v23, v23
	s_nop 0
	v_pk_mul_f32 v[18:19], v[22:23], v[18:19]
	s_nop 0
	v_pk_mul_f32 v[14:15], v[18:19], v[14:15]
	v_pk_mul_f32 v[18:19], v[16:17], v[16:17]
	v_cvt_pk_bf16_f32 v12, v14, v15
	v_pk_add_f32 v[14:15], v[46:47], v[20:21] op_sel_hi:[0,1]
	v_pk_fma_f32 v[18:19], v[18:19], s[18:19], v[40:41] op_sel_hi:[1,0,0] neg_lo:[1,0,0] neg_hi:[1,0,0]
	s_nop 0
	v_pk_mul_f32 v[18:19], v[18:19], v[16:17]
	s_nop 0
	v_exp_f32_e32 v18, v18
	v_exp_f32_e32 v19, v19
	s_nop 0
	v_pk_add_f32 v[18:19], v[18:19], 1.0 op_sel_hi:[1,0]
	s_nop 0
	v_rcp_f32_e32 v18, v18
	v_rcp_f32_e32 v19, v19
	s_nop 0
	v_pk_mul_f32 v[16:17], v[18:19], v[16:17]
	s_nop 0
	v_pk_mul_f32 v[14:15], v[16:17], v[14:15]
	v_lshlrev_b32_e32 v16, 16, v13
	v_and_b32_e32 v17, 0xffff0000, v13
	v_pk_mul_f32 v[18:19], v[16:17], s[24:25] op_sel_hi:[1,0]
	s_nop 0
	v_exp_f32_e32 v18, v18
	v_exp_f32_e32 v19, v19
	s_nop 0
	v_pk_add_f32 v[18:19], v[18:19], 1.0 op_sel_hi:[1,0]
	s_nop 0
	v_rcp_f32_e32 v18, v18
	v_rcp_f32_e32 v19, v19
	s_nop 0
	v_pk_mul_f32 v[16:17], v[18:19], v[16:17]
	s_waitcnt vmcnt(4)
	v_lshlrev_b32_e32 v18, 16, v6
	v_and_b32_e32 v19, 0xffff0000, v6
	v_pk_mul_f32 v[20:21], v[18:19], v[18:19]
	v_pk_mul_f32 v[14:15], v[16:17], v[14:15]
	v_pk_fma_f32 v[20:21], v[20:21], s[18:19], v[40:41] op_sel_hi:[1,0,0] neg_lo:[1,0,0] neg_hi:[1,0,0]
	v_cvt_pk_bf16_f32 v13, v14, v15
	global_store_dwordx4 v[44:45], v[10:13], off
	v_pk_mul_f32 v[20:21], v[20:21], v[18:19]
	ds_read_b128 v[14:17], v47 offset:15232
	ds_read_b128 v[10:13], v47 offset:15248
	v_exp_f32_e32 v20, v20
	v_exp_f32_e32 v21, v21
	v_lshlrev_b32_e32 v6, 16, v7
	s_waitcnt vmcnt(3) lgkmcnt(1)
	v_pk_add_f32 v[14:15], v[42:43], v[14:15] op_sel_hi:[0,1]
	v_and_b32_e32 v7, 0xffff0000, v7
	v_pk_add_f32 v[20:21], v[20:21], 1.0 op_sel_hi:[1,0]
	s_nop 0
	v_rcp_f32_e32 v20, v20
	v_rcp_f32_e32 v21, v21
	s_nop 0
	v_pk_mul_f32 v[18:19], v[20:21], v[18:19]
	s_nop 0
	v_pk_mul_f32 v[14:15], v[18:19], v[14:15]
	v_lshlrev_b32_e32 v18, 16, v2
	v_and_b32_e32 v19, 0xffff0000, v2
	v_pk_mul_f32 v[20:21], v[18:19], s[24:25] op_sel_hi:[1,0]
	s_nop 0
	v_exp_f32_e32 v20, v20
	v_exp_f32_e32 v21, v21
	s_nop 0
	v_pk_add_f32 v[20:21], v[20:21], 1.0 op_sel_hi:[1,0]
	s_nop 0
	v_rcp_f32_e32 v20, v20
	v_rcp_f32_e32 v21, v21
	s_nop 0
	v_pk_mul_f32 v[18:19], v[20:21], v[18:19]
	s_nop 0
	v_pk_mul_f32 v[14:15], v[18:19], v[14:15]
	s_nop 0
	v_cvt_pk_bf16_f32 v2, v14, v15
	v_pk_add_f32 v[14:15], v[42:43], v[16:17] op_sel_hi:[0,1]
	v_pk_mul_f32 v[16:17], v[6:7], v[6:7]
	s_nop 0
	v_pk_fma_f32 v[16:17], v[16:17], s[18:19], v[40:41] op_sel_hi:[1,0,0] neg_lo:[1,0,0] neg_hi:[1,0,0]
	s_nop 0
	v_pk_mul_f32 v[16:17], v[16:17], v[6:7]
	s_nop 0
	v_exp_f32_e32 v16, v16
	v_exp_f32_e32 v17, v17
	s_nop 0
	v_pk_add_f32 v[16:17], v[16:17], 1.0 op_sel_hi:[1,0]
	s_nop 0
	v_rcp_f32_e32 v16, v16
	v_rcp_f32_e32 v17, v17
	s_nop 0
	v_pk_mul_f32 v[6:7], v[16:17], v[6:7]
	s_nop 0
	v_pk_mul_f32 v[6:7], v[6:7], v[14:15]
	v_lshlrev_b32_e32 v14, 16, v3
	v_and_b32_e32 v15, 0xffff0000, v3
	v_pk_mul_f32 v[16:17], v[14:15], s[24:25] op_sel_hi:[1,0]
	s_nop 0
	v_exp_f32_e32 v16, v16
	v_exp_f32_e32 v17, v17
	s_nop 0
	v_pk_add_f32 v[16:17], v[16:17], 1.0 op_sel_hi:[1,0]
	s_nop 0
	v_rcp_f32_e32 v16, v16
	v_rcp_f32_e32 v17, v17
	s_nop 0
	v_pk_mul_f32 v[14:15], v[16:17], v[14:15]
	s_nop 0
	v_pk_mul_f32 v[6:7], v[14:15], v[6:7]
	s_nop 0
	v_cvt_pk_bf16_f32 v3, v6, v7
	s_waitcnt lgkmcnt(0)
	v_pk_add_f32 v[6:7], v[42:43], v[10:11] op_sel_hi:[0,1]
	v_lshlrev_b32_e32 v10, 16, v8
	v_and_b32_e32 v11, 0xffff0000, v8
	v_pk_mul_f32 v[14:15], v[10:11], v[10:11]
	v_lshlrev_b32_e32 v8, 16, v9
	v_pk_fma_f32 v[14:15], v[14:15], s[18:19], v[40:41] op_sel_hi:[1,0,0] neg_lo:[1,0,0] neg_hi:[1,0,0]
	v_and_b32_e32 v9, 0xffff0000, v9
	v_pk_mul_f32 v[14:15], v[14:15], v[10:11]
	s_nop 0
	v_exp_f32_e32 v14, v14
	v_exp_f32_e32 v15, v15
	s_nop 0
	v_pk_add_f32 v[14:15], v[14:15], 1.0 op_sel_hi:[1,0]
	s_nop 0
	v_rcp_f32_e32 v14, v14
	v_rcp_f32_e32 v15, v15
	s_nop 0
	v_pk_mul_f32 v[10:11], v[14:15], v[10:11]
	s_nop 0
	v_pk_mul_f32 v[6:7], v[10:11], v[6:7]
	v_lshlrev_b32_e32 v10, 16, v4
	v_and_b32_e32 v11, 0xffff0000, v4
	v_pk_mul_f32 v[14:15], v[10:11], s[24:25] op_sel_hi:[1,0]
	s_nop 0
	v_exp_f32_e32 v14, v14
	v_exp_f32_e32 v15, v15
	s_nop 0
	v_pk_add_f32 v[14:15], v[14:15], 1.0 op_sel_hi:[1,0]
	s_nop 0
	v_rcp_f32_e32 v14, v14
	v_rcp_f32_e32 v15, v15
	s_nop 0
	v_pk_mul_f32 v[10:11], v[14:15], v[10:11]
	s_nop 0
	v_pk_mul_f32 v[6:7], v[10:11], v[6:7]
	v_pk_mul_f32 v[10:11], v[8:9], v[8:9]
	v_cvt_pk_bf16_f32 v4, v6, v7
	v_pk_add_f32 v[6:7], v[42:43], v[12:13] op_sel_hi:[0,1]
	v_pk_fma_f32 v[10:11], v[10:11], s[18:19], v[40:41] op_sel_hi:[1,0,0] neg_lo:[1,0,0] neg_hi:[1,0,0]
	s_nop 0
	v_pk_mul_f32 v[10:11], v[10:11], v[8:9]
	s_nop 0
	v_exp_f32_e32 v10, v10
	v_exp_f32_e32 v11, v11
	s_nop 0
	v_pk_add_f32 v[10:11], v[10:11], 1.0 op_sel_hi:[1,0]
	s_nop 0
	v_rcp_f32_e32 v10, v10
	v_rcp_f32_e32 v11, v11
	s_nop 0
	v_pk_mul_f32 v[8:9], v[10:11], v[8:9]
	s_nop 0
	v_pk_mul_f32 v[6:7], v[8:9], v[6:7]
	v_lshlrev_b32_e32 v8, 16, v5
	v_and_b32_e32 v9, 0xffff0000, v5
	v_pk_mul_f32 v[10:11], v[8:9], s[24:25] op_sel_hi:[1,0]
	s_nop 0
	v_exp_f32_e32 v10, v10
	v_exp_f32_e32 v11, v11
	s_nop 0
	v_pk_add_f32 v[10:11], v[10:11], 1.0 op_sel_hi:[1,0]
	s_nop 0
	v_rcp_f32_e32 v10, v10
	v_rcp_f32_e32 v11, v11
	s_nop 0
	v_pk_mul_f32 v[8:9], v[10:11], v[8:9]
	s_nop 0
	v_pk_mul_f32 v[6:7], v[8:9], v[6:7]
	s_nop 0
	v_cvt_pk_bf16_f32 v5, v6, v7
	v_add_co_u32_e32 v6, vcc, 0x9a000, v88
	s_nop 1
	v_addc_co_u32_e32 v7, vcc, 0, v89, vcc
	global_store_dwordx4 v[6:7], v[2:5], off
	s_waitcnt lgkmcnt(0)
	s_branch .LBB0_467
